# s_setprio 3 hoisted above the leading barrier so the MFMA stream begins right at barrier release (on top of k-inner+snake, no mid flip, no redundant wait)
# baseline (speedup 1.0000x reference)
; #define PG8_STAGE(bufoff, gbase, voff) do { _Pragma("unroll") for (int _i = 0; _i < 2; ++_i) \
;         __builtin_amdgcn_global_load_lds((const unsigned*)((const char*)(gbase) + (voff)[_i]), (PG8_LAS unsigned*)(lds + (bufoff) + ldsw + _i * 8192), 16, 0, 0); } while (0)
; #define PG8_LDA(dst, b, h) do { _Pragma("unroll") for (int m = 0; m < 4; ++m) _Pragma("unroll") for (int k = 0; k < 2; ++k) dst[m][k] = *(const PG8_LAS bf16x8*)(lds + PG8_SA(b, h) + aoff + m * 2048 + k * 1024); } while (0)
; #define PG8_MMA(ai, bj, At, Bt) do { __builtin_amdgcn_s_setprio(3); _Pragma("unroll") for (int m = 0; m < 4; ++m) _Pragma("unroll") for (int n = 0; n < 2; ++n) _Pragma("unroll") for (int k = 0; k < 2; ++k) \
;         acc[ai][bj][m][n] = __builtin_amdgcn_mfma_f32_16x16x32_bf16(Bt[n][k], At[m][k], acc[ai][bj][m][n], 0, 0, 0); __builtin_amdgcn_s_setprio(0); } while (0)
; #define PG8_WAIT_V(n) asm volatile("s_waitcnt vmcnt(" #n ")" ::: "memory")
; #define PG8_WAIT_L(n) asm volatile("s_waitcnt lgkmcnt(" #n ")" ::: "memory")
; #define PG8_BAR __builtin_amdgcn_s_barrier()
; #define PG8_SCHED __builtin_amdgcn_sched_barrier(0)
; template <class Epi, class Sched, bool ALIGN_EPI = false, bool SP2 = false>
; __device__ __forceinline__ void gemm_phase(PG8_LAS unsigned char* lds, const Gemm g, const Sched& S, const Epi& E) {
;     ...
;             PG8_WAIT_V(8); PG8_WAIT_L(0); PG8_BAR; PG8_MMA(0, 0, At, B0); PG8_MMA(0, 1, At, B1); PG8_BAR; PG8_SCHED;
;             PG8_LDA(At, 0, 1); PG8_STAGE(PG8_SB(0, 0), b2, voffB); PG8_STAGE(PG8_SB(0, 1), b2 + hstepB, voffB); PG8_STAGE(PG8_SA(0, 0), a2, voffA);
;             PG8_WAIT_V(8); PG8_WAIT_L(0); PG8_BAR; PG8_MMA(1, 0, At, B0); PG8_MMA(1, 1, At, B1); PG8_BAR; PG8_SCHED;
.Lengw1_e:
	s_waitcnt lgkmcnt(0)
	s_setprio 3
	s_barrier
	v_mfma_f32_16x16x32_bf16 v[126:129], v[130:133], v[192:195], v[126:129]
	v_mfma_f32_16x16x32_bf16 v[126:129], v[134:137], v[196:199], v[126:129]
	v_mfma_f32_16x16x32_bf16 v[118:121], v[156:159], v[192:195], v[118:121]
	v_mfma_f32_16x16x32_bf16 v[118:121], v[172:175], v[196:199], v[118:121]
	v_mfma_f32_16x16x32_bf16 v[102:105], v[156:159], v[200:203], v[102:105]
	v_mfma_f32_16x16x32_bf16 v[102:105], v[172:175], v[204:207], v[102:105]
	v_mfma_f32_16x16x32_bf16 v[110:113], v[130:133], v[200:203], v[110:113]
	v_mfma_f32_16x16x32_bf16 v[110:113], v[134:137], v[204:207], v[110:113]
	v_mfma_f32_16x16x32_bf16 v[94:97], v[130:133], v[208:211], v[94:97]
	v_mfma_f32_16x16x32_bf16 v[94:97], v[134:137], v[212:215], v[94:97]
	v_mfma_f32_16x16x32_bf16 v[86:89], v[156:159], v[208:211], v[86:89]
	v_mfma_f32_16x16x32_bf16 v[86:89], v[172:175], v[212:215], v[86:89]
	v_mfma_f32_16x16x32_bf16 v[70:73], v[156:159], v[216:219], v[70:73]
	v_mfma_f32_16x16x32_bf16 v[70:73], v[172:175], v[220:223], v[70:73]
	v_mfma_f32_16x16x32_bf16 v[78:81], v[130:133], v[216:219], v[78:81]
	v_mfma_f32_16x16x32_bf16 v[78:81], v[134:137], v[220:223], v[78:81]
	v_mfma_f32_16x16x32_bf16 v[122:125], v[176:179], v[192:195], v[122:125]
	v_mfma_f32_16x16x32_bf16 v[122:125], v[180:183], v[196:199], v[122:125]
	v_mfma_f32_16x16x32_bf16 v[114:117], v[184:187], v[192:195], v[114:117]
	v_mfma_f32_16x16x32_bf16 v[114:117], v[188:191], v[196:199], v[114:117]
	v_mfma_f32_16x16x32_bf16 v[98:101], v[184:187], v[200:203], v[98:101]
	v_mfma_f32_16x16x32_bf16 v[98:101], v[188:191], v[204:207], v[98:101]
	v_mfma_f32_16x16x32_bf16 v[106:109], v[176:179], v[200:203], v[106:109]
	v_mfma_f32_16x16x32_bf16 v[106:109], v[180:183], v[204:207], v[106:109]
	v_mfma_f32_16x16x32_bf16 v[90:93], v[176:179], v[208:211], v[90:93]
	v_mfma_f32_16x16x32_bf16 v[90:93], v[180:183], v[212:215], v[90:93]
	v_mfma_f32_16x16x32_bf16 v[82:85], v[184:187], v[208:211], v[82:85]
	v_mfma_f32_16x16x32_bf16 v[82:85], v[188:191], v[212:215], v[82:85]
	v_mfma_f32_16x16x32_bf16 v[66:69], v[184:187], v[216:219], v[66:69]
	v_mfma_f32_16x16x32_bf16 v[66:69], v[188:191], v[220:223], v[66:69]
	v_mfma_f32_16x16x32_bf16 v[74:77], v[176:179], v[216:219], v[74:77]
	v_mfma_f32_16x16x32_bf16 v[74:77], v[180:183], v[220:223], v[74:77]
	s_setprio 0
	s_barrier
	s_add_i32 s56, s83, s66
	v_lshl_add_u64 v[160:161], s[8:9], 0, v[140:141]
	s_mov_b32 m0, s56
	ds_read_b128 v[192:195], v169 offset:16384
	ds_read_b128 v[196:199], v169 offset:17408
	ds_read_b128 v[200:203], v169 offset:18432
	ds_read_b128 v[204:207], v169 offset:19456
	ds_read_b128 v[208:211], v169 offset:20480
	ds_read_b128 v[212:215], v169 offset:21504
	ds_read_b128 v[216:219], v169 offset:22528
	ds_read_b128 v[220:223], v169 offset:23552
	global_load_lds_dwordx4 v[160:161], off
	s_add_i32 m0, s56, 0x2000
	s_add_u32 s56, s8, 0x100000
	v_lshl_add_u64 v[224:225], s[8:9], 0, v[144:145]
	s_addc_u32 s57, s9, 0
	s_add_i32 s58, s89, s66
	global_load_lds_dwordx4 v[224:225], off
	v_lshl_add_u64 v[226:227], s[56:57], 0, v[140:141]
	s_mov_b32 m0, s58
	v_lshl_add_u64 v[228:229], s[36:37], 0, v[142:143]
	global_load_lds_dwordx4 v[226:227], off
	v_lshl_add_u64 v[226:227], s[56:57], 0, v[144:145]
	s_add_i32 m0, s58, 0x2000
	s_nop 0
	global_load_lds_dwordx4 v[226:227], off
	v_lshl_add_u64 v[226:227], s[36:37], 0, v[138:139]
	s_mov_b32 m0, s55
	s_nop 0
	global_load_lds_dwordx4 v[226:227], off
	s_mov_b32 m0, s67
	s_nop 0
	global_load_lds_dwordx4 v[228:229], off
	s_cmp_eq_u32 s97, 0
	s_cbranch_scc1 .Lengw2_a
	s_cmp_eq_u32 s97, 2
	s_cbranch_scc1 .Lengw2_b
	s_cmp_eq_u32 s97, 4
	s_cbranch_scc1 .Lengw2_c
	s_waitcnt vmcnt(16)
	s_branch .Lengw2_e

; #define PG8_STAGE(bufoff, gbase, voff) do { _Pragma("unroll") for (int _i = 0; _i < 2; ++_i) \
;         __builtin_amdgcn_global_load_lds((const unsigned*)((const char*)(gbase) + (voff)[_i]), (PG8_LAS unsigned*)(lds + (bufoff) + ldsw + _i * 8192), 16, 0, 0); } while (0)
; #define PG8_LDA(dst, b, h) do { _Pragma("unroll") for (int m = 0; m < 4; ++m) _Pragma("unroll") for (int k = 0; k < 2; ++k) dst[m][k] = *(const PG8_LAS bf16x8*)(lds + PG8_SA(b, h) + aoff + m * 2048 + k * 1024); } while (0)
; #define PG8_LDB(dst, b, h) do { _Pragma("unroll") for (int n = 0; n < 2; ++n) _Pragma("unroll") for (int k = 0; k < 2; ++k) dst[n][k] = *(const PG8_LAS bf16x8*)(lds + PG8_SB(b, h) + boff + n * 2048 + k * 1024); } while (0)
; #define PG8_MMA(ai, bj, At, Bt) do { __builtin_amdgcn_s_setprio(3); _Pragma("unroll") for (int m = 0; m < 4; ++m) _Pragma("unroll") for (int n = 0; n < 2; ++n) _Pragma("unroll") for (int k = 0; k < 2; ++k) \
;         acc[ai][bj][m][n] = __builtin_amdgcn_mfma_f32_16x16x32_bf16(Bt[n][k], At[m][k], acc[ai][bj][m][n], 0, 0, 0); __builtin_amdgcn_s_setprio(0); } while (0)
; #define PG8_WAIT_V(n) asm volatile("s_waitcnt vmcnt(" #n ")" ::: "memory")
; #define PG8_WAIT_L(n) asm volatile("s_waitcnt lgkmcnt(" #n ")" ::: "memory")
; #define PG8_BAR __builtin_amdgcn_s_barrier()
; #define PG8_SCHED __builtin_amdgcn_sched_barrier(0)
; template <class Epi, class Sched, bool ALIGN_EPI = false, bool SP2 = false>
; __device__ __forceinline__ void gemm_phase(PG8_LAS unsigned char* lds, const Gemm g, const Sched& S, const Epi& E) {
;     ...
;             PG8_WAIT_V(8); PG8_WAIT_L(0); PG8_BAR; PG8_MMA(1, 0, At, B0); PG8_MMA(1, 1, At, B1); PG8_BAR; PG8_SCHED;
;             PG8_LDB(B0, 1, 0); PG8_LDB(B1, 1, 1); PG8_SCHED; PG8_LDA(At, 1, 0); PG8_STAGE(PG8_SA(0, 1), a2 + hstepA, voffA);
;             PG8_WAIT_V(8); PG8_WAIT_L(0); PG8_BAR; PG8_MMA(0, 0, At, B0); PG8_MMA(0, 1, At, B1); PG8_BAR; PG8_SCHED;
.Lengw2_e:
	s_waitcnt lgkmcnt(0)
	s_setprio 3
	s_barrier
	v_mfma_f32_16x16x32_bf16 v[62:65], v[130:133], v[192:195], v[62:65]
	v_mfma_f32_16x16x32_bf16 v[62:65], v[134:137], v[196:199], v[62:65]
	v_mfma_f32_16x16x32_bf16 v[54:57], v[156:159], v[192:195], v[54:57]
	v_mfma_f32_16x16x32_bf16 v[54:57], v[172:175], v[196:199], v[54:57]
	v_mfma_f32_16x16x32_bf16 v[38:41], v[156:159], v[200:203], v[38:41]
	v_mfma_f32_16x16x32_bf16 v[38:41], v[172:175], v[204:207], v[38:41]
	v_mfma_f32_16x16x32_bf16 v[46:49], v[130:133], v[200:203], v[46:49]
	v_mfma_f32_16x16x32_bf16 v[46:49], v[134:137], v[204:207], v[46:49]
	v_mfma_f32_16x16x32_bf16 v[30:33], v[130:133], v[208:211], v[30:33]
	v_mfma_f32_16x16x32_bf16 v[30:33], v[134:137], v[212:215], v[30:33]
	v_mfma_f32_16x16x32_bf16 v[22:25], v[156:159], v[208:211], v[22:25]
	v_mfma_f32_16x16x32_bf16 v[22:25], v[172:175], v[212:215], v[22:25]
	v_mfma_f32_16x16x32_bf16 v[6:9], v[156:159], v[216:219], v[6:9]
	v_mfma_f32_16x16x32_bf16 v[6:9], v[172:175], v[220:223], v[6:9]
	v_mfma_f32_16x16x32_bf16 v[14:17], v[130:133], v[216:219], v[14:17]
	v_mfma_f32_16x16x32_bf16 v[14:17], v[134:137], v[220:223], v[14:17]
	v_mfma_f32_16x16x32_bf16 v[58:61], v[176:179], v[192:195], v[58:61]
	v_mfma_f32_16x16x32_bf16 v[58:61], v[180:183], v[196:199], v[58:61]
	v_mfma_f32_16x16x32_bf16 v[50:53], v[184:187], v[192:195], v[50:53]
	v_mfma_f32_16x16x32_bf16 v[50:53], v[188:191], v[196:199], v[50:53]
	v_mfma_f32_16x16x32_bf16 v[34:37], v[184:187], v[200:203], v[34:37]
	v_mfma_f32_16x16x32_bf16 v[34:37], v[188:191], v[204:207], v[34:37]
	v_mfma_f32_16x16x32_bf16 v[42:45], v[176:179], v[200:203], v[42:45]
	v_mfma_f32_16x16x32_bf16 v[42:45], v[180:183], v[204:207], v[42:45]
	v_mfma_f32_16x16x32_bf16 v[26:29], v[176:179], v[208:211], v[26:29]
	v_mfma_f32_16x16x32_bf16 v[26:29], v[180:183], v[212:215], v[26:29]
	v_mfma_f32_16x16x32_bf16 v[18:21], v[184:187], v[208:211], v[18:21]
	v_mfma_f32_16x16x32_bf16 v[18:21], v[188:191], v[212:215], v[18:21]
	v_mfma_f32_16x16x32_bf16 v[2:5], v[184:187], v[216:219], v[2:5]
	v_mfma_f32_16x16x32_bf16 v[2:5], v[188:191], v[220:223], v[2:5]
	v_mfma_f32_16x16x32_bf16 v[10:13], v[176:179], v[216:219], v[10:13]
	v_mfma_f32_16x16x32_bf16 v[10:13], v[180:183], v[220:223], v[10:13]
	s_setprio 0
	s_barrier
	s_add_i32 s56, 0, 0x18000
	v_add_u32_e32 v146, s56, v164
	s_add_i32 s57, 0, 0x1c000
	ds_read_b128 v[130:133], v146
	ds_read_b128 v[134:137], v146 offset:1024
	ds_read_b128 v[156:159], v146 offset:2048
	ds_read_b128 v[172:175], v146 offset:3072
	v_add_u32_e32 v146, s57, v164
	ds_read_b128 v[176:179], v146
	ds_read_b128 v[180:183], v146 offset:1024
	ds_read_b128 v[184:187], v146 offset:2048
	ds_read_b128 v[188:191], v146 offset:3072
	s_add_u32 s36, s36, 0x100000
	s_addc_u32 s37, s37, 0
	s_mov_b32 m0, s72
	v_lshl_add_u64 v[230:231], s[36:37], 0, v[138:139]
	ds_read_b128 v[192:195], v169 offset:32768
	ds_read_b128 v[196:199], v169 offset:33792
	ds_read_b128 v[200:203], v169 offset:34816
	ds_read_b128 v[204:207], v169 offset:35840
	ds_read_b128 v[208:211], v169 offset:36864
	ds_read_b128 v[212:215], v169 offset:37888
	ds_read_b128 v[216:219], v169 offset:38912
	ds_read_b128 v[220:223], v169 offset:39936
	global_load_lds_dwordx4 v[230:231], off
	v_lshl_add_u64 v[230:231], s[36:37], 0, v[142:143]
	s_mov_b32 m0, s73
	s_nop 0
	global_load_lds_dwordx4 v[230:231], off
	s_cmp_eq_u32 s97, 4
	s_cbranch_scc1 .Lengw3_c
	s_cmp_eq_u32 s97, 8
	s_cbranch_scc1 .Lengw3_d
	s_waitcnt vmcnt(8)
	s_branch .Lengw3_e

; #define PG8_STAGE(bufoff, gbase, voff) do { _Pragma("unroll") for (int _i = 0; _i < 2; ++_i) \
;         __builtin_amdgcn_global_load_lds((const unsigned*)((const char*)(gbase) + (voff)[_i]), (PG8_LAS unsigned*)(lds + (bufoff) + ldsw + _i * 8192), 16, 0, 0); } while (0)
; #define PG8_LDA(dst, b, h) do { _Pragma("unroll") for (int m = 0; m < 4; ++m) _Pragma("unroll") for (int k = 0; k < 2; ++k) dst[m][k] = *(const PG8_LAS bf16x8*)(lds + PG8_SA(b, h) + aoff + m * 2048 + k * 1024); } while (0)
; #define PG8_MMA(ai, bj, At, Bt) do { __builtin_amdgcn_s_setprio(3); _Pragma("unroll") for (int m = 0; m < 4; ++m) _Pragma("unroll") for (int n = 0; n < 2; ++n) _Pragma("unroll") for (int k = 0; k < 2; ++k) \
;         acc[ai][bj][m][n] = __builtin_amdgcn_mfma_f32_16x16x32_bf16(Bt[n][k], At[m][k], acc[ai][bj][m][n], 0, 0, 0); __builtin_amdgcn_s_setprio(0); } while (0)
; #define PG8_WAIT_V(n) asm volatile("s_waitcnt vmcnt(" #n ")" ::: "memory")
; #define PG8_WAIT_L(n) asm volatile("s_waitcnt lgkmcnt(" #n ")" ::: "memory")
; #define PG8_BAR __builtin_amdgcn_s_barrier()
; #define PG8_SCHED __builtin_amdgcn_sched_barrier(0)
; template <class Epi, class Sched, bool ALIGN_EPI = false, bool SP2 = false>
; __device__ __forceinline__ void gemm_phase(PG8_LAS unsigned char* lds, const Gemm g, const Sched& S, const Epi& E) {
;     ...
;             PG8_WAIT_V(8); PG8_WAIT_L(0); PG8_BAR; PG8_MMA(0, 0, At, B0); PG8_MMA(0, 1, At, B1); PG8_BAR; PG8_SCHED;
;             PG8_LDA(At, 1, 1); PG8_STAGE(PG8_SB(1, 0), b3, voffB); PG8_STAGE(PG8_SB(1, 1), b3 + hstepB, voffB); PG8_STAGE(PG8_SA(1, 0), a3, voffA);
;             PG8_WAIT_V(8); PG8_WAIT_L(0); PG8_BAR; PG8_MMA(1, 0, At, B0); PG8_MMA(1, 1, At, B1); PG8_BAR; PG8_SCHED;
;     ...
;         if constexpr (ALIGN_EPI) { if (wr == 0) PG8_BAR; }
.Lengw3_e:
	s_waitcnt lgkmcnt(0)
	s_setprio 3
	s_barrier
	v_mfma_f32_16x16x32_bf16 v[126:129], v[130:133], v[192:195], v[126:129]
	v_mfma_f32_16x16x32_bf16 v[126:129], v[134:137], v[196:199], v[126:129]
	v_mfma_f32_16x16x32_bf16 v[118:121], v[156:159], v[192:195], v[118:121]
	v_mfma_f32_16x16x32_bf16 v[118:121], v[172:175], v[196:199], v[118:121]
	v_mfma_f32_16x16x32_bf16 v[102:105], v[156:159], v[200:203], v[102:105]
	v_mfma_f32_16x16x32_bf16 v[102:105], v[172:175], v[204:207], v[102:105]
	v_mfma_f32_16x16x32_bf16 v[110:113], v[130:133], v[200:203], v[110:113]
	v_mfma_f32_16x16x32_bf16 v[110:113], v[134:137], v[204:207], v[110:113]
	v_mfma_f32_16x16x32_bf16 v[94:97], v[130:133], v[208:211], v[94:97]
	v_mfma_f32_16x16x32_bf16 v[94:97], v[134:137], v[212:215], v[94:97]
	v_mfma_f32_16x16x32_bf16 v[86:89], v[156:159], v[208:211], v[86:89]
	v_mfma_f32_16x16x32_bf16 v[86:89], v[172:175], v[212:215], v[86:89]
	v_mfma_f32_16x16x32_bf16 v[70:73], v[156:159], v[216:219], v[70:73]
	v_mfma_f32_16x16x32_bf16 v[70:73], v[172:175], v[220:223], v[70:73]
	v_mfma_f32_16x16x32_bf16 v[78:81], v[130:133], v[216:219], v[78:81]
	v_mfma_f32_16x16x32_bf16 v[78:81], v[134:137], v[220:223], v[78:81]
	v_mfma_f32_16x16x32_bf16 v[122:125], v[176:179], v[192:195], v[122:125]
	v_mfma_f32_16x16x32_bf16 v[122:125], v[180:183], v[196:199], v[122:125]
	v_mfma_f32_16x16x32_bf16 v[114:117], v[184:187], v[192:195], v[114:117]
	v_mfma_f32_16x16x32_bf16 v[114:117], v[188:191], v[196:199], v[114:117]
	v_mfma_f32_16x16x32_bf16 v[98:101], v[184:187], v[200:203], v[98:101]
	v_mfma_f32_16x16x32_bf16 v[98:101], v[188:191], v[204:207], v[98:101]
	v_mfma_f32_16x16x32_bf16 v[106:109], v[176:179], v[200:203], v[106:109]
	v_mfma_f32_16x16x32_bf16 v[106:109], v[180:183], v[204:207], v[106:109]
	v_mfma_f32_16x16x32_bf16 v[90:93], v[176:179], v[208:211], v[90:93]
	v_mfma_f32_16x16x32_bf16 v[90:93], v[180:183], v[212:215], v[90:93]
	v_mfma_f32_16x16x32_bf16 v[82:85], v[184:187], v[208:211], v[82:85]
	v_mfma_f32_16x16x32_bf16 v[82:85], v[188:191], v[212:215], v[82:85]
	v_mfma_f32_16x16x32_bf16 v[66:69], v[184:187], v[216:219], v[66:69]
	v_mfma_f32_16x16x32_bf16 v[66:69], v[188:191], v[220:223], v[66:69]
	v_mfma_f32_16x16x32_bf16 v[74:77], v[176:179], v[216:219], v[74:77]
	v_mfma_f32_16x16x32_bf16 v[74:77], v[180:183], v[220:223], v[74:77]
	s_setprio 0
	s_barrier
	s_add_i32 s36, s56, s66
	v_lshl_add_u64 v[160:161], v[160:161], 0, s[18:19]
	s_mov_b32 m0, s36
	ds_read_b128 v[192:195], v169 offset:49152
	ds_read_b128 v[196:199], v169 offset:50176
	ds_read_b128 v[200:203], v169 offset:51200
	ds_read_b128 v[204:207], v169 offset:52224
	ds_read_b128 v[208:211], v169 offset:53248
	ds_read_b128 v[212:215], v169 offset:54272
	ds_read_b128 v[216:219], v169 offset:55296
	ds_read_b128 v[220:223], v169 offset:56320
	global_load_lds_dwordx4 v[160:161], off
	s_add_i32 m0, s36, 0x2000
	s_add_u32 s8, s8, 0x100080
	v_lshl_add_u64 v[160:161], v[224:225], 0, s[18:19]
	s_addc_u32 s9, s9, 0
	s_add_i32 s36, s57, s66
	global_load_lds_dwordx4 v[160:161], off
	v_lshl_add_u64 v[160:161], s[8:9], 0, v[140:141]
	s_mov_b32 m0, s36
	s_nop 0
	global_load_lds_dwordx4 v[160:161], off
	v_lshl_add_u64 v[160:161], s[8:9], 0, v[144:145]
	s_add_i32 m0, s36, 0x2000
	s_nop 0
	global_load_lds_dwordx4 v[160:161], off
	v_lshl_add_u64 v[160:161], v[226:227], 0, s[18:19]
	s_mov_b32 m0, s75
	s_nop 0
	global_load_lds_dwordx4 v[160:161], off
	v_lshl_add_u64 v[160:161], v[228:229], 0, s[18:19]
	s_mov_b32 m0, s76
	s_nop 0
	global_load_lds_dwordx4 v[160:161], off
	s_waitcnt vmcnt(8)
	s_waitcnt lgkmcnt(0)
	s_setprio 3
	s_barrier
	v_mfma_f32_16x16x32_bf16 v[62:65], v[130:133], v[192:195], v[62:65]
	v_mfma_f32_16x16x32_bf16 v[62:65], v[134:137], v[196:199], v[62:65]
	v_mfma_f32_16x16x32_bf16 v[54:57], v[156:159], v[192:195], v[54:57]
	v_mfma_f32_16x16x32_bf16 v[54:57], v[172:175], v[196:199], v[54:57]
	v_mfma_f32_16x16x32_bf16 v[38:41], v[156:159], v[200:203], v[38:41]
	v_mfma_f32_16x16x32_bf16 v[38:41], v[172:175], v[204:207], v[38:41]
	v_mfma_f32_16x16x32_bf16 v[46:49], v[130:133], v[200:203], v[46:49]
	v_mfma_f32_16x16x32_bf16 v[46:49], v[134:137], v[204:207], v[46:49]
	v_mfma_f32_16x16x32_bf16 v[30:33], v[130:133], v[208:211], v[30:33]
	v_mfma_f32_16x16x32_bf16 v[30:33], v[134:137], v[212:215], v[30:33]
	v_mfma_f32_16x16x32_bf16 v[22:25], v[156:159], v[208:211], v[22:25]
	v_mfma_f32_16x16x32_bf16 v[22:25], v[172:175], v[212:215], v[22:25]
	v_mfma_f32_16x16x32_bf16 v[6:9], v[156:159], v[216:219], v[6:9]
	v_mfma_f32_16x16x32_bf16 v[6:9], v[172:175], v[220:223], v[6:9]
	v_mfma_f32_16x16x32_bf16 v[14:17], v[130:133], v[216:219], v[14:17]
	v_mfma_f32_16x16x32_bf16 v[14:17], v[134:137], v[220:223], v[14:17]
	v_mfma_f32_16x16x32_bf16 v[58:61], v[176:179], v[192:195], v[58:61]
	v_mfma_f32_16x16x32_bf16 v[58:61], v[180:183], v[196:199], v[58:61]
	v_mfma_f32_16x16x32_bf16 v[50:53], v[184:187], v[192:195], v[50:53]
	v_mfma_f32_16x16x32_bf16 v[50:53], v[188:191], v[196:199], v[50:53]
	v_mfma_f32_16x16x32_bf16 v[34:37], v[184:187], v[200:203], v[34:37]
	v_mfma_f32_16x16x32_bf16 v[34:37], v[188:191], v[204:207], v[34:37]
	v_mfma_f32_16x16x32_bf16 v[42:45], v[176:179], v[200:203], v[42:45]
	v_mfma_f32_16x16x32_bf16 v[42:45], v[180:183], v[204:207], v[42:45]
	v_mfma_f32_16x16x32_bf16 v[26:29], v[176:179], v[208:211], v[26:29]
	v_mfma_f32_16x16x32_bf16 v[26:29], v[180:183], v[212:215], v[26:29]
	v_mfma_f32_16x16x32_bf16 v[18:21], v[184:187], v[208:211], v[18:21]
	v_mfma_f32_16x16x32_bf16 v[18:21], v[188:191], v[212:215], v[18:21]
	v_mfma_f32_16x16x32_bf16 v[2:5], v[184:187], v[216:219], v[2:5]
	v_mfma_f32_16x16x32_bf16 v[2:5], v[188:191], v[220:223], v[2:5]
	v_mfma_f32_16x16x32_bf16 v[10:13], v[176:179], v[216:219], v[10:13]
	v_mfma_f32_16x16x32_bf16 v[10:13], v[180:183], v[220:223], v[10:13]
	s_setprio 0
	s_barrier
	s_add_i32 s45, s45, 2
	s_add_u32 s6, s6, 0x100
	s_addc_u32 s7, s7, 0
	s_add_u32 s33, s33, 0x100
	s_addc_u32 s44, s44, 0
	s_cmp_gt_u32 s45, 61
	s_cbranch_scc0 .LBB0_143
	s_and_b64 vcc, exec, s[20:21]
	s_cbranch_vccz .LBB0_148
	s_barrier
	v_lshl_add_u32 v156, s0, 8, v163
	s_cmp_lt_i32 s54, 40
	s_mov_b64 s[0:1], -1
	s_cbranch_scc1 .LBB0_149

; #define PG8_STAGE(bufoff, gbase, voff) do { _Pragma("unroll") for (int _i = 0; _i < 2; ++_i) \
;         __builtin_amdgcn_global_load_lds((const unsigned*)((const char*)(gbase) + (voff)[_i]), (PG8_LAS unsigned*)(lds + (bufoff) + ldsw + _i * 8192), 16, 0, 0); } while (0)
; #define PG8_LDA(dst, b, h) do { _Pragma("unroll") for (int m = 0; m < 4; ++m) _Pragma("unroll") for (int k = 0; k < 2; ++k) dst[m][k] = *(const PG8_LAS bf16x8*)(lds + PG8_SA(b, h) + aoff + m * 2048 + k * 1024); } while (0)
; #define PG8_LDB(dst, b, h) do { _Pragma("unroll") for (int n = 0; n < 2; ++n) _Pragma("unroll") for (int k = 0; k < 2; ++k) dst[n][k] = *(const PG8_LAS bf16x8*)(lds + PG8_SB(b, h) + boff + n * 2048 + k * 1024); } while (0)
; #define PG8_MMA(ai, bj, At, Bt) do { __builtin_amdgcn_s_setprio(3); _Pragma("unroll") for (int m = 0; m < 4; ++m) _Pragma("unroll") for (int n = 0; n < 2; ++n) _Pragma("unroll") for (int k = 0; k < 2; ++k) \
;         acc[ai][bj][m][n] = __builtin_amdgcn_mfma_f32_16x16x32_bf16(Bt[n][k], At[m][k], acc[ai][bj][m][n], 0, 0, 0); __builtin_amdgcn_s_setprio(0); } while (0)
; #define PG8_WAIT_V(n) asm volatile("s_waitcnt vmcnt(" #n ")" ::: "memory")
; #define PG8_WAIT_L(n) asm volatile("s_waitcnt lgkmcnt(" #n ")" ::: "memory")
; #define PG8_BAR __builtin_amdgcn_s_barrier()
; #define PG8_SCHED __builtin_amdgcn_sched_barrier(0)
; template <class Epi, class Sched, bool ALIGN_EPI = false, bool SP2 = false>
; __device__ __forceinline__ void gemm_phase(PG8_LAS unsigned char* lds, const Gemm g, const Sched& S, const Epi& E) {
;     ...
;             PG8_LDB(B0, 0, 0); PG8_LDB(B1, 0, 1); PG8_SCHED; PG8_LDA(At, 0, 0); PG8_STAGE(PG8_SA(1, 1), a1 + hstepA, voffA);
;             PG8_WAIT_V(8); PG8_WAIT_L(0); PG8_BAR; PG8_MMA(0, 0, At, B0); PG8_MMA(0, 1, At, B1); PG8_BAR; PG8_SCHED;
;             PG8_LDA(At, 0, 1); PG8_STAGE(PG8_SB(0, 0), b2, voffB); PG8_STAGE(PG8_SB(0, 1), b2 + hstepB, voffB); PG8_STAGE(PG8_SA(0, 0), a2, voffA);
;             PG8_WAIT_V(8); PG8_WAIT_L(0); PG8_BAR; PG8_MMA(1, 0, At, B0); PG8_MMA(1, 1, At, B1); PG8_BAR; PG8_SCHED;
.LBB0_478:
	ds_read_b128 v[130:133], v170
	ds_read_b128 v[134:137], v170 offset:1024
	ds_read_b128 v[138:141], v170 offset:2048
	ds_read_b128 v[142:145], v170 offset:3072
	ds_read_b128 v[164:167], v171
	ds_read_b128 v[174:177], v171 offset:1024
	ds_read_b128 v[178:181], v171 offset:2048
	ds_read_b128 v[182:185], v171 offset:3072
	s_add_u32 s36, s6, 0xfff80080
	s_addc_u32 s37, s7, -1
	s_cmp_eq_u32 s79, 4
	s_cselect_b32 s59, s27, s37
	s_cselect_b32 s58, s26, s36
	s_cselect_b32 s37, s23, s78
	s_cselect_b32 s36, s25, s77
	v_lshl_add_u64 v[218:219], s[6:7], 0, v[154:155]
	s_add_i32 m0, s31, 0xc000
	ds_read_b128 v[186:189], v172
	ds_read_b128 v[190:193], v172 offset:1024
	ds_read_b128 v[194:197], v172 offset:2048
	ds_read_b128 v[198:201], v172 offset:3072
	ds_read_b128 v[202:205], v172 offset:4096
	ds_read_b128 v[206:209], v172 offset:5120
	ds_read_b128 v[210:213], v172 offset:6144
	ds_read_b128 v[214:217], v172 offset:7168
	global_load_lds_dwordx4 v[218:219], off
	v_lshl_add_u64 v[218:219], s[6:7], 0, v[156:157]
	s_add_i32 m0, s31, 0xe000
	s_nop 0
	global_load_lds_dwordx4 v[218:219], off
	s_waitcnt vmcnt(8)
	s_waitcnt lgkmcnt(0)
	s_setprio 3
	s_barrier
	v_mfma_f32_16x16x32_bf16 v[126:129], v[130:133], v[186:189], v[126:129]
	v_mfma_f32_16x16x32_bf16 v[126:129], v[134:137], v[190:193], v[126:129]
	v_mfma_f32_16x16x32_bf16 v[122:125], v[138:141], v[186:189], v[122:125]
	v_mfma_f32_16x16x32_bf16 v[122:125], v[142:145], v[190:193], v[122:125]
	v_mfma_f32_16x16x32_bf16 v[114:117], v[138:141], v[194:197], v[114:117]
	v_mfma_f32_16x16x32_bf16 v[114:117], v[142:145], v[198:201], v[114:117]
	v_mfma_f32_16x16x32_bf16 v[118:121], v[130:133], v[194:197], v[118:121]
	v_mfma_f32_16x16x32_bf16 v[118:121], v[134:137], v[198:201], v[118:121]
	v_mfma_f32_16x16x32_bf16 v[110:113], v[130:133], v[202:205], v[110:113]
	v_mfma_f32_16x16x32_bf16 v[110:113], v[134:137], v[206:209], v[110:113]
	v_mfma_f32_16x16x32_bf16 v[102:105], v[138:141], v[202:205], v[102:105]
	v_mfma_f32_16x16x32_bf16 v[102:105], v[142:145], v[206:209], v[102:105]
	v_mfma_f32_16x16x32_bf16 v[74:77], v[138:141], v[210:213], v[74:77]
	v_mfma_f32_16x16x32_bf16 v[74:77], v[142:145], v[214:217], v[74:77]
	v_mfma_f32_16x16x32_bf16 v[78:81], v[130:133], v[210:213], v[78:81]
	v_mfma_f32_16x16x32_bf16 v[78:81], v[134:137], v[214:217], v[78:81]
	v_mfma_f32_16x16x32_bf16 v[106:109], v[164:167], v[186:189], v[106:109]
	v_mfma_f32_16x16x32_bf16 v[106:109], v[174:177], v[190:193], v[106:109]
	v_mfma_f32_16x16x32_bf16 v[98:101], v[178:181], v[186:189], v[98:101]
	v_mfma_f32_16x16x32_bf16 v[98:101], v[182:185], v[190:193], v[98:101]
	v_mfma_f32_16x16x32_bf16 v[90:93], v[178:181], v[194:197], v[90:93]
	v_mfma_f32_16x16x32_bf16 v[90:93], v[182:185], v[198:201], v[90:93]
	v_mfma_f32_16x16x32_bf16 v[94:97], v[164:167], v[194:197], v[94:97]
	v_mfma_f32_16x16x32_bf16 v[94:97], v[174:177], v[198:201], v[94:97]
	v_mfma_f32_16x16x32_bf16 v[86:89], v[164:167], v[202:205], v[86:89]
	v_mfma_f32_16x16x32_bf16 v[86:89], v[174:177], v[206:209], v[86:89]
	v_mfma_f32_16x16x32_bf16 v[82:85], v[178:181], v[202:205], v[82:85]
	v_mfma_f32_16x16x32_bf16 v[82:85], v[182:185], v[206:209], v[82:85]
	v_mfma_f32_16x16x32_bf16 v[66:69], v[178:181], v[210:213], v[66:69]
	v_mfma_f32_16x16x32_bf16 v[66:69], v[182:185], v[214:217], v[66:69]
	v_mfma_f32_16x16x32_bf16 v[70:73], v[164:167], v[210:213], v[70:73]
	v_mfma_f32_16x16x32_bf16 v[70:73], v[174:177], v[214:217], v[70:73]
	s_setprio 0
	s_barrier
	s_add_i32 s83, s72, s44
	v_lshl_add_u64 v[218:219], s[36:37], 0, v[148:149]
	s_mov_b32 m0, s83
	ds_read_b128 v[186:189], v172 offset:16384
	ds_read_b128 v[190:193], v172 offset:17408
	ds_read_b128 v[194:197], v172 offset:18432
	ds_read_b128 v[198:201], v172 offset:19456
	ds_read_b128 v[202:205], v172 offset:20480
	ds_read_b128 v[206:209], v172 offset:21504
	ds_read_b128 v[210:213], v172 offset:22528
	ds_read_b128 v[214:217], v172 offset:23552
	global_load_lds_dwordx4 v[218:219], off
	s_add_i32 m0, s83, 0x2000
	s_add_u32 s84, s36, 0x20000
	v_lshl_add_u64 v[220:221], s[36:37], 0, v[152:153]
	s_addc_u32 s85, s37, 0
	s_add_i32 s83, s73, s44
	global_load_lds_dwordx4 v[220:221], off
	v_lshl_add_u64 v[222:223], s[84:85], 0, v[148:149]
	s_mov_b32 m0, s83
	v_lshl_add_u64 v[224:225], s[58:59], 0, v[150:151]
	global_load_lds_dwordx4 v[222:223], off
	v_lshl_add_u64 v[222:223], s[84:85], 0, v[152:153]
	s_add_i32 m0, s83, 0x2000
	s_nop 0
	global_load_lds_dwordx4 v[222:223], off
	v_lshl_add_u64 v[222:223], s[58:59], 0, v[146:147]
	s_mov_b32 m0, s31
	s_nop 0
	global_load_lds_dwordx4 v[222:223], off
	s_mov_b32 m0, s45
	s_nop 0
	global_load_lds_dwordx4 v[224:225], off
	s_waitcnt vmcnt(8)
	s_waitcnt lgkmcnt(0)
	s_setprio 3
	s_barrier
; #define PG8_STAGE(bufoff, gbase, voff) do { _Pragma("unroll") for (int _i = 0; _i < 2; ++_i) \
;         __builtin_amdgcn_global_load_lds((const unsigned*)((const char*)(gbase) + (voff)[_i]), (PG8_LAS unsigned*)(lds + (bufoff) + ldsw + _i * 8192), 16, 0, 0); } while (0)
; #define PG8_LDA(dst, b, h) do { _Pragma("unroll") for (int m = 0; m < 4; ++m) _Pragma("unroll") for (int k = 0; k < 2; ++k) dst[m][k] = *(const PG8_LAS bf16x8*)(lds + PG8_SA(b, h) + aoff + m * 2048 + k * 1024); } while (0)
; #define PG8_LDB(dst, b, h) do { _Pragma("unroll") for (int n = 0; n < 2; ++n) _Pragma("unroll") for (int k = 0; k < 2; ++k) dst[n][k] = *(const PG8_LAS bf16x8*)(lds + PG8_SB(b, h) + boff + n * 2048 + k * 1024); } while (0)
; #define PG8_MMA(ai, bj, At, Bt) do { __builtin_amdgcn_s_setprio(3); _Pragma("unroll") for (int m = 0; m < 4; ++m) _Pragma("unroll") for (int n = 0; n < 2; ++n) _Pragma("unroll") for (int k = 0; k < 2; ++k) \
;         acc[ai][bj][m][n] = __builtin_amdgcn_mfma_f32_16x16x32_bf16(Bt[n][k], At[m][k], acc[ai][bj][m][n], 0, 0, 0); __builtin_amdgcn_s_setprio(0); } while (0)
; #define PG8_WAIT_V(n) asm volatile("s_waitcnt vmcnt(" #n ")" ::: "memory")
; #define PG8_WAIT_L(n) asm volatile("s_waitcnt lgkmcnt(" #n ")" ::: "memory")
; #define PG8_BAR __builtin_amdgcn_s_barrier()
; #define PG8_SCHED __builtin_amdgcn_sched_barrier(0)
; template <class Epi, class Sched, bool ALIGN_EPI = false, bool SP2 = false>
; __device__ __forceinline__ void gemm_phase(PG8_LAS unsigned char* lds, const Gemm g, const Sched& S, const Epi& E) {
;     ...
;             PG8_WAIT_V(8); PG8_WAIT_L(0); PG8_BAR; PG8_MMA(1, 0, At, B0); PG8_MMA(1, 1, At, B1); PG8_BAR; PG8_SCHED;
;             PG8_LDB(B0, 1, 0); PG8_LDB(B1, 1, 1); PG8_SCHED; PG8_LDA(At, 1, 0); PG8_STAGE(PG8_SA(0, 1), a2 + hstepA, voffA);
;             PG8_WAIT_V(8); PG8_WAIT_L(0); PG8_BAR; PG8_MMA(0, 0, At, B0); PG8_MMA(0, 1, At, B1); PG8_BAR; PG8_SCHED;
	v_mfma_f32_16x16x32_bf16 v[62:65], v[130:133], v[186:189], v[62:65]
	v_mfma_f32_16x16x32_bf16 v[62:65], v[134:137], v[190:193], v[62:65]
	v_mfma_f32_16x16x32_bf16 v[58:61], v[138:141], v[186:189], v[58:61]
	v_mfma_f32_16x16x32_bf16 v[58:61], v[142:145], v[190:193], v[58:61]
	v_mfma_f32_16x16x32_bf16 v[46:49], v[138:141], v[194:197], v[46:49]
	v_mfma_f32_16x16x32_bf16 v[46:49], v[142:145], v[198:201], v[46:49]
	v_mfma_f32_16x16x32_bf16 v[54:57], v[130:133], v[194:197], v[54:57]
	v_mfma_f32_16x16x32_bf16 v[54:57], v[134:137], v[198:201], v[54:57]
	v_mfma_f32_16x16x32_bf16 v[38:41], v[130:133], v[202:205], v[38:41]
	v_mfma_f32_16x16x32_bf16 v[38:41], v[134:137], v[206:209], v[38:41]
	v_mfma_f32_16x16x32_bf16 v[30:33], v[138:141], v[202:205], v[30:33]
	v_mfma_f32_16x16x32_bf16 v[30:33], v[142:145], v[206:209], v[30:33]
	v_mfma_f32_16x16x32_bf16 v[14:17], v[138:141], v[210:213], v[14:17]
	v_mfma_f32_16x16x32_bf16 v[14:17], v[142:145], v[214:217], v[14:17]
	v_mfma_f32_16x16x32_bf16 v[22:25], v[130:133], v[210:213], v[22:25]
	v_mfma_f32_16x16x32_bf16 v[22:25], v[134:137], v[214:217], v[22:25]
	v_mfma_f32_16x16x32_bf16 v[50:53], v[164:167], v[186:189], v[50:53]
	v_mfma_f32_16x16x32_bf16 v[50:53], v[174:177], v[190:193], v[50:53]
	v_mfma_f32_16x16x32_bf16 v[42:45], v[178:181], v[186:189], v[42:45]
	v_mfma_f32_16x16x32_bf16 v[42:45], v[182:185], v[190:193], v[42:45]
	v_mfma_f32_16x16x32_bf16 v[26:29], v[178:181], v[194:197], v[26:29]
	v_mfma_f32_16x16x32_bf16 v[26:29], v[182:185], v[198:201], v[26:29]
	v_mfma_f32_16x16x32_bf16 v[34:37], v[164:167], v[194:197], v[34:37]
	v_mfma_f32_16x16x32_bf16 v[34:37], v[174:177], v[198:201], v[34:37]
	v_mfma_f32_16x16x32_bf16 v[18:21], v[164:167], v[202:205], v[18:21]
	v_mfma_f32_16x16x32_bf16 v[18:21], v[174:177], v[206:209], v[18:21]
	v_mfma_f32_16x16x32_bf16 v[10:13], v[178:181], v[202:205], v[10:13]
	v_mfma_f32_16x16x32_bf16 v[10:13], v[182:185], v[206:209], v[10:13]
	v_mfma_f32_16x16x32_bf16 v[2:5], v[178:181], v[210:213], v[2:5]
	v_mfma_f32_16x16x32_bf16 v[2:5], v[182:185], v[214:217], v[2:5]
	v_mfma_f32_16x16x32_bf16 v[6:9], v[164:167], v[210:213], v[6:9]
	v_mfma_f32_16x16x32_bf16 v[6:9], v[174:177], v[214:217], v[6:9]
	s_setprio 0
	s_barrier
	s_add_i32 s83, 0, 0x18000
	s_add_i32 s84, 0, 0x1c000
	v_add_u32_e32 v142, s83, v168
	v_add_u32_e32 v173, s84, v168
	ds_read_b128 v[130:133], v142
	ds_read_b128 v[134:137], v142 offset:1024
	ds_read_b128 v[138:141], v142 offset:2048
	ds_read_b128 v[142:145], v142 offset:3072
	ds_read_b128 v[164:167], v173
	ds_read_b128 v[174:177], v173 offset:1024
	ds_read_b128 v[178:181], v173 offset:2048
	ds_read_b128 v[182:185], v173 offset:3072
	s_add_u32 s58, s58, 0x80000
	s_addc_u32 s59, s59, 0
	s_mov_b32 m0, s54
	v_lshl_add_u64 v[226:227], s[58:59], 0, v[146:147]
	ds_read_b128 v[186:189], v172 offset:32768
	ds_read_b128 v[190:193], v172 offset:33792
	ds_read_b128 v[194:197], v172 offset:34816
	ds_read_b128 v[198:201], v172 offset:35840
	ds_read_b128 v[202:205], v172 offset:36864
	ds_read_b128 v[206:209], v172 offset:37888
	ds_read_b128 v[210:213], v172 offset:38912
	ds_read_b128 v[214:217], v172 offset:39936
	global_load_lds_dwordx4 v[226:227], off
	v_lshl_add_u64 v[226:227], s[58:59], 0, v[150:151]
	s_mov_b32 m0, s55
	s_nop 0
	global_load_lds_dwordx4 v[226:227], off
	s_waitcnt vmcnt(8)
	s_waitcnt lgkmcnt(0)
	s_setprio 3
	s_barrier
	v_mfma_f32_16x16x32_bf16 v[126:129], v[130:133], v[186:189], v[126:129]
	v_mfma_f32_16x16x32_bf16 v[126:129], v[134:137], v[190:193], v[126:129]
	v_mfma_f32_16x16x32_bf16 v[122:125], v[138:141], v[186:189], v[122:125]
	v_mfma_f32_16x16x32_bf16 v[122:125], v[142:145], v[190:193], v[122:125]
	v_mfma_f32_16x16x32_bf16 v[114:117], v[138:141], v[194:197], v[114:117]
	v_mfma_f32_16x16x32_bf16 v[114:117], v[142:145], v[198:201], v[114:117]
	v_mfma_f32_16x16x32_bf16 v[118:121], v[130:133], v[194:197], v[118:121]
	v_mfma_f32_16x16x32_bf16 v[118:121], v[134:137], v[198:201], v[118:121]
	v_mfma_f32_16x16x32_bf16 v[110:113], v[130:133], v[202:205], v[110:113]
	v_mfma_f32_16x16x32_bf16 v[110:113], v[134:137], v[206:209], v[110:113]
	v_mfma_f32_16x16x32_bf16 v[102:105], v[138:141], v[202:205], v[102:105]
	v_mfma_f32_16x16x32_bf16 v[102:105], v[142:145], v[206:209], v[102:105]
	v_mfma_f32_16x16x32_bf16 v[74:77], v[138:141], v[210:213], v[74:77]
	v_mfma_f32_16x16x32_bf16 v[74:77], v[142:145], v[214:217], v[74:77]
	v_mfma_f32_16x16x32_bf16 v[78:81], v[130:133], v[210:213], v[78:81]
	v_mfma_f32_16x16x32_bf16 v[78:81], v[134:137], v[214:217], v[78:81]
	v_mfma_f32_16x16x32_bf16 v[106:109], v[164:167], v[186:189], v[106:109]
	v_mfma_f32_16x16x32_bf16 v[106:109], v[174:177], v[190:193], v[106:109]
	v_mfma_f32_16x16x32_bf16 v[98:101], v[178:181], v[186:189], v[98:101]
	v_mfma_f32_16x16x32_bf16 v[98:101], v[182:185], v[190:193], v[98:101]
	v_mfma_f32_16x16x32_bf16 v[90:93], v[178:181], v[194:197], v[90:93]
	v_mfma_f32_16x16x32_bf16 v[90:93], v[182:185], v[198:201], v[90:93]
	v_mfma_f32_16x16x32_bf16 v[94:97], v[164:167], v[194:197], v[94:97]
	v_mfma_f32_16x16x32_bf16 v[94:97], v[174:177], v[198:201], v[94:97]
	v_mfma_f32_16x16x32_bf16 v[86:89], v[164:167], v[202:205], v[86:89]
	v_mfma_f32_16x16x32_bf16 v[86:89], v[174:177], v[206:209], v[86:89]
	v_mfma_f32_16x16x32_bf16 v[82:85], v[178:181], v[202:205], v[82:85]
	v_mfma_f32_16x16x32_bf16 v[82:85], v[182:185], v[206:209], v[82:85]
	v_mfma_f32_16x16x32_bf16 v[66:69], v[178:181], v[210:213], v[66:69]
	v_mfma_f32_16x16x32_bf16 v[66:69], v[182:185], v[214:217], v[66:69]
	v_mfma_f32_16x16x32_bf16 v[70:73], v[164:167], v[210:213], v[70:73]
	v_mfma_f32_16x16x32_bf16 v[70:73], v[174:177], v[214:217], v[70:73]
	s_setprio 0
	s_barrier
; #define PG8_STAGE(bufoff, gbase, voff) do { _Pragma("unroll") for (int _i = 0; _i < 2; ++_i) \
;         __builtin_amdgcn_global_load_lds((const unsigned*)((const char*)(gbase) + (voff)[_i]), (PG8_LAS unsigned*)(lds + (bufoff) + ldsw + _i * 8192), 16, 0, 0); } while (0)
; #define PG8_LDA(dst, b, h) do { _Pragma("unroll") for (int m = 0; m < 4; ++m) _Pragma("unroll") for (int k = 0; k < 2; ++k) dst[m][k] = *(const PG8_LAS bf16x8*)(lds + PG8_SA(b, h) + aoff + m * 2048 + k * 1024); } while (0)
; #define PG8_MMA(ai, bj, At, Bt) do { __builtin_amdgcn_s_setprio(3); _Pragma("unroll") for (int m = 0; m < 4; ++m) _Pragma("unroll") for (int n = 0; n < 2; ++n) _Pragma("unroll") for (int k = 0; k < 2; ++k) \
;         acc[ai][bj][m][n] = __builtin_amdgcn_mfma_f32_16x16x32_bf16(Bt[n][k], At[m][k], acc[ai][bj][m][n], 0, 0, 0); __builtin_amdgcn_s_setprio(0); } while (0)
; #define PG8_WAIT_V(n) asm volatile("s_waitcnt vmcnt(" #n ")" ::: "memory")
; #define PG8_WAIT_L(n) asm volatile("s_waitcnt lgkmcnt(" #n ")" ::: "memory")
; #define PG8_BAR __builtin_amdgcn_s_barrier()
; #define PG8_SCHED __builtin_amdgcn_sched_barrier(0)
; template <class Epi, class Sched, bool ALIGN_EPI = false, bool SP2 = false>
; __device__ __forceinline__ void gemm_phase(PG8_LAS unsigned char* lds, const Gemm g, const Sched& S, const Epi& E) {
;     ...
;             PG8_LDA(At, 1, 1); PG8_STAGE(PG8_SB(1, 0), b3, voffB); PG8_STAGE(PG8_SB(1, 1), b3 + hstepB, voffB); PG8_STAGE(PG8_SA(1, 0), a3, voffA);
;             PG8_WAIT_V(8); PG8_WAIT_L(0); PG8_BAR; PG8_MMA(1, 0, At, B0); PG8_MMA(1, 1, At, B1); PG8_BAR; PG8_SCHED;
	s_add_i32 s58, s83, s44
	v_lshl_add_u64 v[218:219], v[218:219], 0, s[18:19]
	s_mov_b32 m0, s58
	ds_read_b128 v[186:189], v172 offset:49152
	ds_read_b128 v[190:193], v172 offset:50176
	ds_read_b128 v[194:197], v172 offset:51200
	ds_read_b128 v[198:201], v172 offset:52224
	ds_read_b128 v[202:205], v172 offset:53248
	ds_read_b128 v[206:209], v172 offset:54272
	ds_read_b128 v[210:213], v172 offset:55296
	ds_read_b128 v[214:217], v172 offset:56320
	global_load_lds_dwordx4 v[218:219], off
	s_add_i32 m0, s58, 0x2000
	s_add_u32 s36, s36, 0x20080
	v_lshl_add_u64 v[218:219], v[220:221], 0, s[18:19]
	s_addc_u32 s37, s37, 0
	s_add_i32 s58, s84, s44
	global_load_lds_dwordx4 v[218:219], off
	v_lshl_add_u64 v[218:219], s[36:37], 0, v[148:149]
	s_mov_b32 m0, s58
	s_nop 0
	global_load_lds_dwordx4 v[218:219], off
	v_lshl_add_u64 v[218:219], s[36:37], 0, v[152:153]
	s_add_i32 m0, s58, 0x2000
	s_nop 0
	global_load_lds_dwordx4 v[218:219], off
	v_lshl_add_u64 v[218:219], v[222:223], 0, s[18:19]
	s_mov_b32 m0, s63
	s_nop 0
	global_load_lds_dwordx4 v[218:219], off
	v_lshl_add_u64 v[218:219], v[224:225], 0, s[18:19]
	s_mov_b32 m0, s66
	s_nop 0
	global_load_lds_dwordx4 v[218:219], off
	s_waitcnt vmcnt(8)
	s_waitcnt lgkmcnt(0)
	s_setprio 3
	s_barrier
	v_mfma_f32_16x16x32_bf16 v[62:65], v[130:133], v[186:189], v[62:65]
	v_mfma_f32_16x16x32_bf16 v[62:65], v[134:137], v[190:193], v[62:65]
	v_mfma_f32_16x16x32_bf16 v[58:61], v[138:141], v[186:189], v[58:61]
	v_mfma_f32_16x16x32_bf16 v[58:61], v[142:145], v[190:193], v[58:61]
	v_mfma_f32_16x16x32_bf16 v[46:49], v[138:141], v[194:197], v[46:49]
	v_mfma_f32_16x16x32_bf16 v[46:49], v[142:145], v[198:201], v[46:49]
	v_mfma_f32_16x16x32_bf16 v[54:57], v[130:133], v[194:197], v[54:57]
	v_mfma_f32_16x16x32_bf16 v[54:57], v[134:137], v[198:201], v[54:57]
	v_mfma_f32_16x16x32_bf16 v[38:41], v[130:133], v[202:205], v[38:41]
	v_mfma_f32_16x16x32_bf16 v[38:41], v[134:137], v[206:209], v[38:41]
	v_mfma_f32_16x16x32_bf16 v[30:33], v[138:141], v[202:205], v[30:33]
	v_mfma_f32_16x16x32_bf16 v[30:33], v[142:145], v[206:209], v[30:33]
	v_mfma_f32_16x16x32_bf16 v[14:17], v[138:141], v[210:213], v[14:17]
	v_mfma_f32_16x16x32_bf16 v[14:17], v[142:145], v[214:217], v[14:17]
	v_mfma_f32_16x16x32_bf16 v[22:25], v[130:133], v[210:213], v[22:25]
	v_mfma_f32_16x16x32_bf16 v[22:25], v[134:137], v[214:217], v[22:25]
	v_mfma_f32_16x16x32_bf16 v[50:53], v[164:167], v[186:189], v[50:53]
	v_mfma_f32_16x16x32_bf16 v[50:53], v[174:177], v[190:193], v[50:53]
	v_mfma_f32_16x16x32_bf16 v[42:45], v[178:181], v[186:189], v[42:45]
	v_mfma_f32_16x16x32_bf16 v[42:45], v[182:185], v[190:193], v[42:45]
	v_mfma_f32_16x16x32_bf16 v[26:29], v[178:181], v[194:197], v[26:29]
	v_mfma_f32_16x16x32_bf16 v[26:29], v[182:185], v[198:201], v[26:29]
	v_mfma_f32_16x16x32_bf16 v[34:37], v[164:167], v[194:197], v[34:37]
	v_mfma_f32_16x16x32_bf16 v[34:37], v[174:177], v[198:201], v[34:37]
	v_mfma_f32_16x16x32_bf16 v[18:21], v[164:167], v[202:205], v[18:21]
	v_mfma_f32_16x16x32_bf16 v[18:21], v[174:177], v[206:209], v[18:21]
	v_mfma_f32_16x16x32_bf16 v[10:13], v[178:181], v[202:205], v[10:13]
	v_mfma_f32_16x16x32_bf16 v[10:13], v[182:185], v[206:209], v[10:13]
	v_mfma_f32_16x16x32_bf16 v[2:5], v[178:181], v[210:213], v[2:5]
	v_mfma_f32_16x16x32_bf16 v[2:5], v[182:185], v[214:217], v[2:5]
	v_mfma_f32_16x16x32_bf16 v[6:9], v[164:167], v[210:213], v[6:9]
	v_mfma_f32_16x16x32_bf16 v[6:9], v[174:177], v[214:217], v[6:9]
	s_setprio 0
	s_barrier
	s_add_i32 s79, s79, 2
	s_add_u32 s6, s6, 0x100
	s_addc_u32 s7, s7, 0
	s_add_u32 s77, s77, 0x100
	s_addc_u32 s78, s78, 0
	s_cmp_gt_u32 s79, 5
	s_cbranch_scc0 .LBB0_478
	s_and_b64 vcc, exec, s[20:21]
	s_cbranch_vccz .LBB0_481
	s_barrier

; #define PG8_STAGE(bufoff, gbase, voff) do { _Pragma("unroll") for (int _i = 0; _i < 2; ++_i) \
;         __builtin_amdgcn_global_load_lds((const unsigned*)((const char*)(gbase) + (voff)[_i]), (PG8_LAS unsigned*)(lds + (bufoff) + ldsw + _i * 8192), 16, 0, 0); } while (0)
; #define PG8_LDA(dst, b, h) do { _Pragma("unroll") for (int m = 0; m < 4; ++m) _Pragma("unroll") for (int k = 0; k < 2; ++k) dst[m][k] = *(const PG8_LAS bf16x8*)(lds + PG8_SA(b, h) + aoff + m * 2048 + k * 1024); } while (0)
; #define PG8_LDB(dst, b, h) do { _Pragma("unroll") for (int n = 0; n < 2; ++n) _Pragma("unroll") for (int k = 0; k < 2; ++k) dst[n][k] = *(const PG8_LAS bf16x8*)(lds + PG8_SB(b, h) + boff + n * 2048 + k * 1024); } while (0)
; #define PG8_MMA(ai, bj, At, Bt) do { __builtin_amdgcn_s_setprio(3); _Pragma("unroll") for (int m = 0; m < 4; ++m) _Pragma("unroll") for (int n = 0; n < 2; ++n) _Pragma("unroll") for (int k = 0; k < 2; ++k) \
;         acc[ai][bj][m][n] = __builtin_amdgcn_mfma_f32_16x16x32_bf16(Bt[n][k], At[m][k], acc[ai][bj][m][n], 0, 0, 0); __builtin_amdgcn_s_setprio(0); } while (0)
; #define PG8_WAIT_V(n) asm volatile("s_waitcnt vmcnt(" #n ")" ::: "memory")
; #define PG8_WAIT_L(n) asm volatile("s_waitcnt lgkmcnt(" #n ")" ::: "memory")
; #define PG8_BAR __builtin_amdgcn_s_barrier()
; #define PG8_SCHED __builtin_amdgcn_sched_barrier(0)
; template <class Epi, class Sched, bool ALIGN_EPI = false, bool SP2 = false>
; __device__ __forceinline__ void gemm_phase(PG8_LAS unsigned char* lds, const Gemm g, const Sched& S, const Epi& E) {
;     ...
;             PG8_LDB(B0, 0, 0); PG8_LDB(B1, 0, 1); PG8_SCHED; PG8_LDA(At, 0, 0); PG8_STAGE(PG8_SA(1, 1), a1 + hstepA, voffA);
;             PG8_WAIT_V(8); PG8_WAIT_L(0); PG8_BAR; PG8_MMA(0, 0, At, B0); PG8_MMA(0, 1, At, B1); PG8_BAR; PG8_SCHED;
;             PG8_LDA(At, 0, 1); PG8_STAGE(PG8_SB(0, 0), b2, voffB); PG8_STAGE(PG8_SB(0, 1), b2 + hstepB, voffB); PG8_STAGE(PG8_SA(0, 0), a2, voffA);
;             PG8_WAIT_V(8); PG8_WAIT_L(0); PG8_BAR; PG8_MMA(1, 0, At, B0); PG8_MMA(1, 1, At, B1); PG8_BAR; PG8_SCHED;
.LBB0_727:
	v_add_u32_e32 v160, s66, v157
	ds_read_b128 v[130:133], v160
	ds_read_b128 v[164:167], v160 offset:1024
	ds_read_b128 v[168:171], v160 offset:2048
	ds_read_b128 v[172:175], v160 offset:3072
	v_add_u32_e32 v160, s67, v157
	s_add_u32 s0, s28, s30
	ds_read_b128 v[176:179], v160
	ds_read_b128 v[180:183], v160 offset:1024
	ds_read_b128 v[184:187], v160 offset:2048
	ds_read_b128 v[188:191], v160 offset:3072
	s_addc_u32 s1, s29, s31
	s_add_u32 s0, s0, 0x100
	s_addc_u32 s1, s1, 0
	s_add_u32 s84, s79, s30
	s_addc_u32 s85, s81, s31
	s_cmpk_eq_i32 s30, 0x1f00
	s_cselect_b32 s37, s23, s1
	s_cselect_b32 s36, s72, s0
	s_cselect_b32 s1, s75, s85
	s_cselect_b32 s0, s76, s84
	v_lshl_add_u64 v[160:161], v[150:151], 0, s[30:31]
	s_add_i32 m0, s44, 0xc000
	ds_read_b128 v[192:195], v159
	ds_read_b128 v[196:199], v159 offset:1024
	ds_read_b128 v[200:203], v159 offset:2048
	ds_read_b128 v[204:207], v159 offset:3072
	ds_read_b128 v[208:211], v159 offset:4096
	ds_read_b128 v[212:215], v159 offset:5120
	ds_read_b128 v[216:219], v159 offset:6144
	ds_read_b128 v[220:223], v159 offset:7168
	global_load_lds_dwordx4 v[160:161], off
	v_lshl_add_u64 v[160:161], v[152:153], 0, s[30:31]
	s_add_i32 m0, s44, 0xe000
	s_nop 0
	global_load_lds_dwordx4 v[160:161], off
	s_waitcnt vmcnt(8)
	s_waitcnt lgkmcnt(0)
	s_setprio 3
	s_barrier
	v_mfma_f32_16x16x32_bf16 v[126:129], v[130:133], v[192:195], v[126:129]
	v_mfma_f32_16x16x32_bf16 v[126:129], v[164:167], v[196:199], v[126:129]
	v_mfma_f32_16x16x32_bf16 v[122:125], v[168:171], v[192:195], v[122:125]
	v_mfma_f32_16x16x32_bf16 v[122:125], v[172:175], v[196:199], v[122:125]
	v_mfma_f32_16x16x32_bf16 v[106:109], v[168:171], v[200:203], v[106:109]
	v_mfma_f32_16x16x32_bf16 v[106:109], v[172:175], v[204:207], v[106:109]
	v_mfma_f32_16x16x32_bf16 v[110:113], v[130:133], v[200:203], v[110:113]
	v_mfma_f32_16x16x32_bf16 v[110:113], v[164:167], v[204:207], v[110:113]
	v_mfma_f32_16x16x32_bf16 v[94:97], v[130:133], v[208:211], v[94:97]
	v_mfma_f32_16x16x32_bf16 v[94:97], v[164:167], v[212:215], v[94:97]
	v_mfma_f32_16x16x32_bf16 v[90:93], v[168:171], v[208:211], v[90:93]
	v_mfma_f32_16x16x32_bf16 v[90:93], v[172:175], v[212:215], v[90:93]
	v_mfma_f32_16x16x32_bf16 v[74:77], v[168:171], v[216:219], v[74:77]
	v_mfma_f32_16x16x32_bf16 v[74:77], v[172:175], v[220:223], v[74:77]
	v_mfma_f32_16x16x32_bf16 v[78:81], v[130:133], v[216:219], v[78:81]
	v_mfma_f32_16x16x32_bf16 v[78:81], v[164:167], v[220:223], v[78:81]
	v_mfma_f32_16x16x32_bf16 v[118:121], v[176:179], v[192:195], v[118:121]
	v_mfma_f32_16x16x32_bf16 v[118:121], v[180:183], v[196:199], v[118:121]
	v_mfma_f32_16x16x32_bf16 v[114:117], v[184:187], v[192:195], v[114:117]
	v_mfma_f32_16x16x32_bf16 v[114:117], v[188:191], v[196:199], v[114:117]
	v_mfma_f32_16x16x32_bf16 v[98:101], v[184:187], v[200:203], v[98:101]
	v_mfma_f32_16x16x32_bf16 v[98:101], v[188:191], v[204:207], v[98:101]
	v_mfma_f32_16x16x32_bf16 v[102:105], v[176:179], v[200:203], v[102:105]
	v_mfma_f32_16x16x32_bf16 v[102:105], v[180:183], v[204:207], v[102:105]
	v_mfma_f32_16x16x32_bf16 v[86:89], v[176:179], v[208:211], v[86:89]
	v_mfma_f32_16x16x32_bf16 v[86:89], v[180:183], v[212:215], v[86:89]
	v_mfma_f32_16x16x32_bf16 v[82:85], v[184:187], v[208:211], v[82:85]
	v_mfma_f32_16x16x32_bf16 v[82:85], v[188:191], v[212:215], v[82:85]
	v_mfma_f32_16x16x32_bf16 v[66:69], v[184:187], v[216:219], v[66:69]
	v_mfma_f32_16x16x32_bf16 v[66:69], v[188:191], v[220:223], v[66:69]
	v_mfma_f32_16x16x32_bf16 v[70:73], v[176:179], v[216:219], v[70:73]
	v_mfma_f32_16x16x32_bf16 v[70:73], v[180:183], v[220:223], v[70:73]
	s_setprio 0
	s_barrier
	s_add_i32 s84, s66, s33
	v_lshl_add_u64 v[160:161], s[0:1], 0, v[136:137]
	s_mov_b32 m0, s84
	ds_read_b128 v[192:195], v159 offset:16384
	ds_read_b128 v[196:199], v159 offset:17408
	ds_read_b128 v[200:203], v159 offset:18432
	ds_read_b128 v[204:207], v159 offset:19456
	ds_read_b128 v[208:211], v159 offset:20480
	ds_read_b128 v[212:215], v159 offset:21504
	ds_read_b128 v[216:219], v159 offset:22528
	ds_read_b128 v[220:223], v159 offset:23552
	global_load_lds_dwordx4 v[160:161], off
	s_add_i32 m0, s84, 0x2000
	s_add_u32 s84, s0, 0x100000
	v_lshl_add_u64 v[224:225], s[0:1], 0, v[140:141]
	s_addc_u32 s85, s1, 0
	s_add_i32 s86, s67, s33
	global_load_lds_dwordx4 v[224:225], off
	v_lshl_add_u64 v[226:227], s[84:85], 0, v[136:137]
	s_mov_b32 m0, s86
	v_lshl_add_u64 v[228:229], s[36:37], 0, v[138:139]
	global_load_lds_dwordx4 v[226:227], off
	v_lshl_add_u64 v[226:227], s[84:85], 0, v[140:141]
	s_add_i32 m0, s86, 0x2000
	s_nop 0
	global_load_lds_dwordx4 v[226:227], off
	v_lshl_add_u64 v[226:227], s[36:37], 0, v[134:135]
	s_mov_b32 m0, s44
	s_nop 0
	global_load_lds_dwordx4 v[226:227], off
	s_mov_b32 m0, s45
	s_nop 0
	global_load_lds_dwordx4 v[228:229], off
	s_waitcnt vmcnt(8)
	s_waitcnt lgkmcnt(0)
	s_setprio 3
	s_barrier
; #define PG8_STAGE(bufoff, gbase, voff) do { _Pragma("unroll") for (int _i = 0; _i < 2; ++_i) \
;         __builtin_amdgcn_global_load_lds((const unsigned*)((const char*)(gbase) + (voff)[_i]), (PG8_LAS unsigned*)(lds + (bufoff) + ldsw + _i * 8192), 16, 0, 0); } while (0)
; #define PG8_LDA(dst, b, h) do { _Pragma("unroll") for (int m = 0; m < 4; ++m) _Pragma("unroll") for (int k = 0; k < 2; ++k) dst[m][k] = *(const PG8_LAS bf16x8*)(lds + PG8_SA(b, h) + aoff + m * 2048 + k * 1024); } while (0)
; #define PG8_LDB(dst, b, h) do { _Pragma("unroll") for (int n = 0; n < 2; ++n) _Pragma("unroll") for (int k = 0; k < 2; ++k) dst[n][k] = *(const PG8_LAS bf16x8*)(lds + PG8_SB(b, h) + boff + n * 2048 + k * 1024); } while (0)
; #define PG8_MMA(ai, bj, At, Bt) do { __builtin_amdgcn_s_setprio(3); _Pragma("unroll") for (int m = 0; m < 4; ++m) _Pragma("unroll") for (int n = 0; n < 2; ++n) _Pragma("unroll") for (int k = 0; k < 2; ++k) \
;         acc[ai][bj][m][n] = __builtin_amdgcn_mfma_f32_16x16x32_bf16(Bt[n][k], At[m][k], acc[ai][bj][m][n], 0, 0, 0); __builtin_amdgcn_s_setprio(0); } while (0)
; #define PG8_WAIT_V(n) asm volatile("s_waitcnt vmcnt(" #n ")" ::: "memory")
; #define PG8_WAIT_L(n) asm volatile("s_waitcnt lgkmcnt(" #n ")" ::: "memory")
; #define PG8_BAR __builtin_amdgcn_s_barrier()
; #define PG8_SCHED __builtin_amdgcn_sched_barrier(0)
; template <class Epi, class Sched, bool ALIGN_EPI = false, bool SP2 = false>
; __device__ __forceinline__ void gemm_phase(PG8_LAS unsigned char* lds, const Gemm g, const Sched& S, const Epi& E) {
;     ...
;             PG8_WAIT_V(8); PG8_WAIT_L(0); PG8_BAR; PG8_MMA(1, 0, At, B0); PG8_MMA(1, 1, At, B1); PG8_BAR; PG8_SCHED;
;             PG8_LDB(B0, 1, 0); PG8_LDB(B1, 1, 1); PG8_SCHED; PG8_LDA(At, 1, 0); PG8_STAGE(PG8_SA(0, 1), a2 + hstepA, voffA);
;             PG8_WAIT_V(8); PG8_WAIT_L(0); PG8_BAR; PG8_MMA(0, 0, At, B0); PG8_MMA(0, 1, At, B1); PG8_BAR; PG8_SCHED;
	v_mfma_f32_16x16x32_bf16 v[62:65], v[130:133], v[192:195], v[62:65]
	v_mfma_f32_16x16x32_bf16 v[62:65], v[164:167], v[196:199], v[62:65]
	v_mfma_f32_16x16x32_bf16 v[58:61], v[168:171], v[192:195], v[58:61]
	v_mfma_f32_16x16x32_bf16 v[58:61], v[172:175], v[196:199], v[58:61]
	v_mfma_f32_16x16x32_bf16 v[42:45], v[168:171], v[200:203], v[42:45]
	v_mfma_f32_16x16x32_bf16 v[42:45], v[172:175], v[204:207], v[42:45]
	v_mfma_f32_16x16x32_bf16 v[46:49], v[130:133], v[200:203], v[46:49]
	v_mfma_f32_16x16x32_bf16 v[46:49], v[164:167], v[204:207], v[46:49]
	v_mfma_f32_16x16x32_bf16 v[30:33], v[130:133], v[208:211], v[30:33]
	v_mfma_f32_16x16x32_bf16 v[30:33], v[164:167], v[212:215], v[30:33]
	v_mfma_f32_16x16x32_bf16 v[26:29], v[168:171], v[208:211], v[26:29]
	v_mfma_f32_16x16x32_bf16 v[26:29], v[172:175], v[212:215], v[26:29]
	v_mfma_f32_16x16x32_bf16 v[10:13], v[168:171], v[216:219], v[10:13]
	v_mfma_f32_16x16x32_bf16 v[10:13], v[172:175], v[220:223], v[10:13]
	v_mfma_f32_16x16x32_bf16 v[14:17], v[130:133], v[216:219], v[14:17]
	v_mfma_f32_16x16x32_bf16 v[14:17], v[164:167], v[220:223], v[14:17]
	v_mfma_f32_16x16x32_bf16 v[54:57], v[176:179], v[192:195], v[54:57]
	v_mfma_f32_16x16x32_bf16 v[54:57], v[180:183], v[196:199], v[54:57]
	v_mfma_f32_16x16x32_bf16 v[50:53], v[184:187], v[192:195], v[50:53]
	v_mfma_f32_16x16x32_bf16 v[50:53], v[188:191], v[196:199], v[50:53]
	v_mfma_f32_16x16x32_bf16 v[34:37], v[184:187], v[200:203], v[34:37]
	v_mfma_f32_16x16x32_bf16 v[34:37], v[188:191], v[204:207], v[34:37]
	v_mfma_f32_16x16x32_bf16 v[38:41], v[176:179], v[200:203], v[38:41]
	v_mfma_f32_16x16x32_bf16 v[38:41], v[180:183], v[204:207], v[38:41]
	v_mfma_f32_16x16x32_bf16 v[22:25], v[176:179], v[208:211], v[22:25]
	v_mfma_f32_16x16x32_bf16 v[22:25], v[180:183], v[212:215], v[22:25]
	v_mfma_f32_16x16x32_bf16 v[18:21], v[184:187], v[208:211], v[18:21]
	v_mfma_f32_16x16x32_bf16 v[18:21], v[188:191], v[212:215], v[18:21]
	v_mfma_f32_16x16x32_bf16 v[2:5], v[184:187], v[216:219], v[2:5]
	v_mfma_f32_16x16x32_bf16 v[2:5], v[188:191], v[220:223], v[2:5]
	v_mfma_f32_16x16x32_bf16 v[6:9], v[176:179], v[216:219], v[6:9]
	v_mfma_f32_16x16x32_bf16 v[6:9], v[180:183], v[220:223], v[6:9]
	s_setprio 0
	s_barrier
	s_add_i32 s84, 0, 0x18000
	v_add_u32_e32 v163, s84, v157
	s_add_i32 s85, 0, 0x1c000
	ds_read_b128 v[130:133], v163
	ds_read_b128 v[164:167], v163 offset:1024
	ds_read_b128 v[168:171], v163 offset:2048
	ds_read_b128 v[172:175], v163 offset:3072
	v_add_u32_e32 v163, s85, v157
	ds_read_b128 v[176:179], v163
	ds_read_b128 v[180:183], v163 offset:1024
	ds_read_b128 v[184:187], v163 offset:2048
	ds_read_b128 v[188:191], v163 offset:3072
	s_add_u32 s36, s36, 0x100000
	s_addc_u32 s37, s37, 0
	s_mov_b32 m0, s54
	v_lshl_add_u64 v[230:231], s[36:37], 0, v[134:135]
	ds_read_b128 v[192:195], v159 offset:32768
	ds_read_b128 v[196:199], v159 offset:33792
	ds_read_b128 v[200:203], v159 offset:34816
	ds_read_b128 v[204:207], v159 offset:35840
	ds_read_b128 v[208:211], v159 offset:36864
	ds_read_b128 v[212:215], v159 offset:37888
	ds_read_b128 v[216:219], v159 offset:38912
	ds_read_b128 v[220:223], v159 offset:39936
	global_load_lds_dwordx4 v[230:231], off
	v_lshl_add_u64 v[230:231], s[36:37], 0, v[138:139]
	s_mov_b32 m0, s55
	s_nop 0
	global_load_lds_dwordx4 v[230:231], off
	s_waitcnt vmcnt(8)
	s_waitcnt lgkmcnt(0)
	s_setprio 3
	s_barrier
	v_mfma_f32_16x16x32_bf16 v[126:129], v[130:133], v[192:195], v[126:129]
	v_mfma_f32_16x16x32_bf16 v[126:129], v[164:167], v[196:199], v[126:129]
	v_mfma_f32_16x16x32_bf16 v[122:125], v[168:171], v[192:195], v[122:125]
	v_mfma_f32_16x16x32_bf16 v[122:125], v[172:175], v[196:199], v[122:125]
	v_mfma_f32_16x16x32_bf16 v[106:109], v[168:171], v[200:203], v[106:109]
	v_mfma_f32_16x16x32_bf16 v[106:109], v[172:175], v[204:207], v[106:109]
	v_mfma_f32_16x16x32_bf16 v[110:113], v[130:133], v[200:203], v[110:113]
	v_mfma_f32_16x16x32_bf16 v[110:113], v[164:167], v[204:207], v[110:113]
	v_mfma_f32_16x16x32_bf16 v[94:97], v[130:133], v[208:211], v[94:97]
	v_mfma_f32_16x16x32_bf16 v[94:97], v[164:167], v[212:215], v[94:97]
	v_mfma_f32_16x16x32_bf16 v[90:93], v[168:171], v[208:211], v[90:93]
	v_mfma_f32_16x16x32_bf16 v[90:93], v[172:175], v[212:215], v[90:93]
	v_mfma_f32_16x16x32_bf16 v[74:77], v[168:171], v[216:219], v[74:77]
	v_mfma_f32_16x16x32_bf16 v[74:77], v[172:175], v[220:223], v[74:77]
	v_mfma_f32_16x16x32_bf16 v[78:81], v[130:133], v[216:219], v[78:81]
	v_mfma_f32_16x16x32_bf16 v[78:81], v[164:167], v[220:223], v[78:81]
	v_mfma_f32_16x16x32_bf16 v[118:121], v[176:179], v[192:195], v[118:121]
	v_mfma_f32_16x16x32_bf16 v[118:121], v[180:183], v[196:199], v[118:121]
	v_mfma_f32_16x16x32_bf16 v[114:117], v[184:187], v[192:195], v[114:117]
	v_mfma_f32_16x16x32_bf16 v[114:117], v[188:191], v[196:199], v[114:117]
	v_mfma_f32_16x16x32_bf16 v[98:101], v[184:187], v[200:203], v[98:101]
	v_mfma_f32_16x16x32_bf16 v[98:101], v[188:191], v[204:207], v[98:101]
	v_mfma_f32_16x16x32_bf16 v[102:105], v[176:179], v[200:203], v[102:105]
	v_mfma_f32_16x16x32_bf16 v[102:105], v[180:183], v[204:207], v[102:105]
	v_mfma_f32_16x16x32_bf16 v[86:89], v[176:179], v[208:211], v[86:89]
	v_mfma_f32_16x16x32_bf16 v[86:89], v[180:183], v[212:215], v[86:89]
	v_mfma_f32_16x16x32_bf16 v[82:85], v[184:187], v[208:211], v[82:85]
	v_mfma_f32_16x16x32_bf16 v[82:85], v[188:191], v[212:215], v[82:85]
	v_mfma_f32_16x16x32_bf16 v[66:69], v[184:187], v[216:219], v[66:69]
	v_mfma_f32_16x16x32_bf16 v[66:69], v[188:191], v[220:223], v[66:69]
	v_mfma_f32_16x16x32_bf16 v[70:73], v[176:179], v[216:219], v[70:73]
	v_mfma_f32_16x16x32_bf16 v[70:73], v[180:183], v[220:223], v[70:73]
	s_setprio 0
	s_barrier
; #define PG8_STAGE(bufoff, gbase, voff) do { _Pragma("unroll") for (int _i = 0; _i < 2; ++_i) \
;         __builtin_amdgcn_global_load_lds((const unsigned*)((const char*)(gbase) + (voff)[_i]), (PG8_LAS unsigned*)(lds + (bufoff) + ldsw + _i * 8192), 16, 0, 0); } while (0)
; #define PG8_LDA(dst, b, h) do { _Pragma("unroll") for (int m = 0; m < 4; ++m) _Pragma("unroll") for (int k = 0; k < 2; ++k) dst[m][k] = *(const PG8_LAS bf16x8*)(lds + PG8_SA(b, h) + aoff + m * 2048 + k * 1024); } while (0)
; #define PG8_MMA(ai, bj, At, Bt) do { __builtin_amdgcn_s_setprio(3); _Pragma("unroll") for (int m = 0; m < 4; ++m) _Pragma("unroll") for (int n = 0; n < 2; ++n) _Pragma("unroll") for (int k = 0; k < 2; ++k) \
;         acc[ai][bj][m][n] = __builtin_amdgcn_mfma_f32_16x16x32_bf16(Bt[n][k], At[m][k], acc[ai][bj][m][n], 0, 0, 0); __builtin_amdgcn_s_setprio(0); } while (0)
; #define PG8_WAIT_V(n) asm volatile("s_waitcnt vmcnt(" #n ")" ::: "memory")
; #define PG8_WAIT_L(n) asm volatile("s_waitcnt lgkmcnt(" #n ")" ::: "memory")
; #define PG8_BAR __builtin_amdgcn_s_barrier()
; #define PG8_SCHED __builtin_amdgcn_sched_barrier(0)
; template <class Epi, class Sched, bool ALIGN_EPI = false, bool SP2 = false>
; __device__ __forceinline__ void gemm_phase(PG8_LAS unsigned char* lds, const Gemm g, const Sched& S, const Epi& E) {
;     ...
;             PG8_LDA(At, 1, 1); PG8_STAGE(PG8_SB(1, 0), b3, voffB); PG8_STAGE(PG8_SB(1, 1), b3 + hstepB, voffB); PG8_STAGE(PG8_SA(1, 0), a3, voffA);
;             PG8_WAIT_V(8); PG8_WAIT_L(0); PG8_BAR; PG8_MMA(1, 0, At, B0); PG8_MMA(1, 1, At, B1); PG8_BAR; PG8_SCHED;
	s_add_i32 s36, s84, s33
	v_lshl_add_u64 v[160:161], v[160:161], 0, s[10:11]
	s_mov_b32 m0, s36
	ds_read_b128 v[192:195], v159 offset:49152
	ds_read_b128 v[196:199], v159 offset:50176
	ds_read_b128 v[200:203], v159 offset:51200
	ds_read_b128 v[204:207], v159 offset:52224
	ds_read_b128 v[208:211], v159 offset:53248
	ds_read_b128 v[212:215], v159 offset:54272
	ds_read_b128 v[216:219], v159 offset:55296
	ds_read_b128 v[220:223], v159 offset:56320
	global_load_lds_dwordx4 v[160:161], off
	s_add_i32 m0, s36, 0x2000
	s_add_u32 s0, s0, 0x100080
	v_lshl_add_u64 v[160:161], v[224:225], 0, s[10:11]
	s_addc_u32 s1, s1, 0
	s_add_i32 s36, s85, s33
	global_load_lds_dwordx4 v[160:161], off
	v_lshl_add_u64 v[160:161], s[0:1], 0, v[136:137]
	s_mov_b32 m0, s36
	s_nop 0
	global_load_lds_dwordx4 v[160:161], off
	v_lshl_add_u64 v[160:161], s[0:1], 0, v[140:141]
	s_add_i32 m0, s36, 0x2000
	s_nop 0
	global_load_lds_dwordx4 v[160:161], off
	v_lshl_add_u64 v[160:161], v[226:227], 0, s[10:11]
	s_mov_b32 m0, s61
	s_nop 0
	global_load_lds_dwordx4 v[160:161], off
	v_lshl_add_u64 v[160:161], v[228:229], 0, s[10:11]
	s_mov_b32 m0, s62
	s_nop 0
	global_load_lds_dwordx4 v[160:161], off
	s_waitcnt vmcnt(8)
	s_waitcnt lgkmcnt(0)
	s_setprio 3
	s_barrier
	v_mfma_f32_16x16x32_bf16 v[62:65], v[130:133], v[192:195], v[62:65]
	v_mfma_f32_16x16x32_bf16 v[62:65], v[164:167], v[196:199], v[62:65]
	v_mfma_f32_16x16x32_bf16 v[58:61], v[168:171], v[192:195], v[58:61]
	v_mfma_f32_16x16x32_bf16 v[58:61], v[172:175], v[196:199], v[58:61]
	v_mfma_f32_16x16x32_bf16 v[42:45], v[168:171], v[200:203], v[42:45]
	v_mfma_f32_16x16x32_bf16 v[42:45], v[172:175], v[204:207], v[42:45]
	v_mfma_f32_16x16x32_bf16 v[46:49], v[130:133], v[200:203], v[46:49]
	v_mfma_f32_16x16x32_bf16 v[46:49], v[164:167], v[204:207], v[46:49]
	v_mfma_f32_16x16x32_bf16 v[30:33], v[130:133], v[208:211], v[30:33]
	v_mfma_f32_16x16x32_bf16 v[30:33], v[164:167], v[212:215], v[30:33]
	v_mfma_f32_16x16x32_bf16 v[26:29], v[168:171], v[208:211], v[26:29]
	v_mfma_f32_16x16x32_bf16 v[26:29], v[172:175], v[212:215], v[26:29]
	v_mfma_f32_16x16x32_bf16 v[10:13], v[168:171], v[216:219], v[10:13]
	v_mfma_f32_16x16x32_bf16 v[10:13], v[172:175], v[220:223], v[10:13]
	v_mfma_f32_16x16x32_bf16 v[14:17], v[130:133], v[216:219], v[14:17]
	v_mfma_f32_16x16x32_bf16 v[14:17], v[164:167], v[220:223], v[14:17]
	v_mfma_f32_16x16x32_bf16 v[54:57], v[176:179], v[192:195], v[54:57]
	v_mfma_f32_16x16x32_bf16 v[54:57], v[180:183], v[196:199], v[54:57]
	v_mfma_f32_16x16x32_bf16 v[50:53], v[184:187], v[192:195], v[50:53]
	v_mfma_f32_16x16x32_bf16 v[50:53], v[188:191], v[196:199], v[50:53]
	v_mfma_f32_16x16x32_bf16 v[34:37], v[184:187], v[200:203], v[34:37]
	v_mfma_f32_16x16x32_bf16 v[34:37], v[188:191], v[204:207], v[34:37]
	v_mfma_f32_16x16x32_bf16 v[38:41], v[176:179], v[200:203], v[38:41]
	v_mfma_f32_16x16x32_bf16 v[38:41], v[180:183], v[204:207], v[38:41]
	v_mfma_f32_16x16x32_bf16 v[22:25], v[176:179], v[208:211], v[22:25]
	v_mfma_f32_16x16x32_bf16 v[22:25], v[180:183], v[212:215], v[22:25]
	v_mfma_f32_16x16x32_bf16 v[18:21], v[184:187], v[208:211], v[18:21]
	v_mfma_f32_16x16x32_bf16 v[18:21], v[188:191], v[212:215], v[18:21]
	v_mfma_f32_16x16x32_bf16 v[2:5], v[184:187], v[216:219], v[2:5]
	v_mfma_f32_16x16x32_bf16 v[2:5], v[188:191], v[220:223], v[2:5]
	v_mfma_f32_16x16x32_bf16 v[6:9], v[176:179], v[216:219], v[6:9]
	v_mfma_f32_16x16x32_bf16 v[6:9], v[180:183], v[220:223], v[6:9]
	s_setprio 0
	s_barrier
	s_add_i32 s83, s83, 2
	s_add_u32 s30, s30, 0x100
	s_addc_u32 s31, s31, 0
	s_cmp_gt_u32 s83, 61
	s_cbranch_scc1 .LBB0_730

; #define PG8_STAGE(bufoff, gbase, voff) do { _Pragma("unroll") for (int _i = 0; _i < 2; ++_i) \
;         __builtin_amdgcn_global_load_lds((const unsigned*)((const char*)(gbase) + (voff)[_i]), (PG8_LAS unsigned*)(lds + (bufoff) + ldsw + _i * 8192), 16, 0, 0); } while (0)
; #define PG8_LDA(dst, b, h) do { _Pragma("unroll") for (int m = 0; m < 4; ++m) _Pragma("unroll") for (int k = 0; k < 2; ++k) dst[m][k] = *(const PG8_LAS bf16x8*)(lds + PG8_SA(b, h) + aoff + m * 2048 + k * 1024); } while (0)
; #define PG8_LDB(dst, b, h) do { _Pragma("unroll") for (int n = 0; n < 2; ++n) _Pragma("unroll") for (int k = 0; k < 2; ++k) dst[n][k] = *(const PG8_LAS bf16x8*)(lds + PG8_SB(b, h) + boff + n * 2048 + k * 1024); } while (0)
; #define PG8_MMA(ai, bj, At, Bt) do { __builtin_amdgcn_s_setprio(3); _Pragma("unroll") for (int m = 0; m < 4; ++m) _Pragma("unroll") for (int n = 0; n < 2; ++n) _Pragma("unroll") for (int k = 0; k < 2; ++k) \
;         acc[ai][bj][m][n] = __builtin_amdgcn_mfma_f32_16x16x32_bf16(Bt[n][k], At[m][k], acc[ai][bj][m][n], 0, 0, 0); __builtin_amdgcn_s_setprio(0); } while (0)
; #define PG8_WAIT_V(n) asm volatile("s_waitcnt vmcnt(" #n ")" ::: "memory")
; #define PG8_WAIT_L(n) asm volatile("s_waitcnt lgkmcnt(" #n ")" ::: "memory")
; #define PG8_BAR __builtin_amdgcn_s_barrier()
; #define PG8_SCHED __builtin_amdgcn_sched_barrier(0)
; template <class Epi, class Sched, bool ALIGN_EPI = false, bool SP2 = false>
; __device__ __forceinline__ void gemm_phase(PG8_LAS unsigned char* lds, const Gemm g, const Sched& S, const Epi& E) {
;     ...
;             PG8_LDB(B0, 0, 0); PG8_LDB(B1, 0, 1); PG8_SCHED; PG8_LDA(At, 0, 0); PG8_STAGE(PG8_SA(1, 1), a1 + hstepA, voffA);
;             PG8_WAIT_V(8); PG8_WAIT_L(0); PG8_BAR; PG8_MMA(0, 0, At, B0); PG8_MMA(0, 1, At, B1); PG8_BAR; PG8_SCHED;
;             PG8_LDA(At, 0, 1); PG8_STAGE(PG8_SB(0, 0), b2, voffB); PG8_STAGE(PG8_SB(0, 1), b2 + hstepB, voffB); PG8_STAGE(PG8_SA(0, 0), a2, voffA);
;             PG8_WAIT_V(8); PG8_WAIT_L(0); PG8_BAR; PG8_MMA(1, 0, At, B0); PG8_MMA(1, 1, At, B1); PG8_BAR; PG8_SCHED;
.LBB0_808:
	v_add_u32_e32 v3, s65, v186
	ds_read_b128 v[134:137], v3
	ds_read_b128 v[138:141], v3 offset:1024
	ds_read_b128 v[142:145], v3 offset:2048
	ds_read_b128 v[146:149], v3 offset:3072
	v_add_u32_e32 v3, s66, v186
	s_add_u32 s36, s28, s30
	ds_read_b128 v[150:153], v3
	ds_read_b128 v[154:157], v3 offset:1024
	ds_read_b128 v[158:161], v3 offset:2048
	ds_read_b128 v[190:193], v3 offset:3072
	s_addc_u32 s37, s29, s31
	s_add_u32 s36, s36, 0x100
	s_addc_u32 s37, s37, 0
	s_add_u32 s86, s83, s30
	s_addc_u32 s87, s84, s31
	s_cmpk_eq_i32 s30, 0x1f00
	s_cselect_b32 s41, s23, s37
	s_cselect_b32 s40, s75, s36
	s_cselect_b32 s37, s77, s87
	s_cselect_b32 s36, s78, s86
	v_lshl_add_u64 v[4:5], v[180:181], 0, s[30:31]
	s_add_i32 m0, s42, 0xc000
	ds_read_b128 v[194:197], v188
	ds_read_b128 v[198:201], v188 offset:1024
	ds_read_b128 v[202:205], v188 offset:2048
	ds_read_b128 v[206:209], v188 offset:3072
	ds_read_b128 v[210:213], v188 offset:4096
	ds_read_b128 v[214:217], v188 offset:5120
	ds_read_b128 v[218:221], v188 offset:6144
	ds_read_b128 v[222:225], v188 offset:7168
	global_load_lds_dwordx4 v[4:5], off
	v_lshl_add_u64 v[4:5], v[182:183], 0, s[30:31]
	s_add_i32 m0, s42, 0xe000
	s_nop 0
	global_load_lds_dwordx4 v[4:5], off
	s_waitcnt vmcnt(8)
	s_waitcnt lgkmcnt(0)
	s_setprio 3
	s_barrier
	v_mfma_f32_16x16x32_bf16 v[130:133], v[134:137], v[194:197], v[130:133]
	v_mfma_f32_16x16x32_bf16 v[130:133], v[138:141], v[198:201], v[130:133]
	v_mfma_f32_16x16x32_bf16 v[126:129], v[142:145], v[194:197], v[126:129]
	v_mfma_f32_16x16x32_bf16 v[126:129], v[146:149], v[198:201], v[126:129]
	v_mfma_f32_16x16x32_bf16 v[110:113], v[142:145], v[202:205], v[110:113]
	v_mfma_f32_16x16x32_bf16 v[110:113], v[146:149], v[206:209], v[110:113]
	v_mfma_f32_16x16x32_bf16 v[114:117], v[134:137], v[202:205], v[114:117]
	v_mfma_f32_16x16x32_bf16 v[114:117], v[138:141], v[206:209], v[114:117]
	v_mfma_f32_16x16x32_bf16 v[98:101], v[134:137], v[210:213], v[98:101]
	v_mfma_f32_16x16x32_bf16 v[98:101], v[138:141], v[214:217], v[98:101]
	v_mfma_f32_16x16x32_bf16 v[94:97], v[142:145], v[210:213], v[94:97]
	v_mfma_f32_16x16x32_bf16 v[94:97], v[146:149], v[214:217], v[94:97]
	v_mfma_f32_16x16x32_bf16 v[78:81], v[142:145], v[218:221], v[78:81]
	v_mfma_f32_16x16x32_bf16 v[78:81], v[146:149], v[222:225], v[78:81]
	v_mfma_f32_16x16x32_bf16 v[82:85], v[134:137], v[218:221], v[82:85]
	v_mfma_f32_16x16x32_bf16 v[82:85], v[138:141], v[222:225], v[82:85]
	v_mfma_f32_16x16x32_bf16 v[122:125], v[150:153], v[194:197], v[122:125]
	v_mfma_f32_16x16x32_bf16 v[122:125], v[154:157], v[198:201], v[122:125]
	v_mfma_f32_16x16x32_bf16 v[118:121], v[158:161], v[194:197], v[118:121]
	v_mfma_f32_16x16x32_bf16 v[118:121], v[190:193], v[198:201], v[118:121]
	v_mfma_f32_16x16x32_bf16 v[102:105], v[158:161], v[202:205], v[102:105]
	v_mfma_f32_16x16x32_bf16 v[102:105], v[190:193], v[206:209], v[102:105]
	v_mfma_f32_16x16x32_bf16 v[106:109], v[150:153], v[202:205], v[106:109]
	v_mfma_f32_16x16x32_bf16 v[106:109], v[154:157], v[206:209], v[106:109]
	v_mfma_f32_16x16x32_bf16 v[90:93], v[150:153], v[210:213], v[90:93]
	v_mfma_f32_16x16x32_bf16 v[90:93], v[154:157], v[214:217], v[90:93]
	v_mfma_f32_16x16x32_bf16 v[86:89], v[158:161], v[210:213], v[86:89]
	v_mfma_f32_16x16x32_bf16 v[86:89], v[190:193], v[214:217], v[86:89]
	v_mfma_f32_16x16x32_bf16 v[70:73], v[158:161], v[218:221], v[70:73]
	v_mfma_f32_16x16x32_bf16 v[70:73], v[190:193], v[222:225], v[70:73]
	v_mfma_f32_16x16x32_bf16 v[74:77], v[150:153], v[218:221], v[74:77]
	v_mfma_f32_16x16x32_bf16 v[74:77], v[154:157], v[222:225], v[74:77]
	s_setprio 0
	s_barrier
	s_add_i32 s86, s65, s33
	v_lshl_add_u64 v[226:227], s[36:37], 0, v[166:167]
	s_mov_b32 m0, s86
	ds_read_b128 v[194:197], v188 offset:16384
	ds_read_b128 v[198:201], v188 offset:17408
	ds_read_b128 v[202:205], v188 offset:18432
	ds_read_b128 v[206:209], v188 offset:19456
	ds_read_b128 v[210:213], v188 offset:20480
	ds_read_b128 v[214:217], v188 offset:21504
	ds_read_b128 v[218:221], v188 offset:22528
	ds_read_b128 v[222:225], v188 offset:23552
	global_load_lds_dwordx4 v[226:227], off
	s_add_i32 m0, s86, 0x2000
	s_add_u32 s86, s36, 0x100000
	v_lshl_add_u64 v[228:229], s[36:37], 0, v[170:171]
	s_addc_u32 s87, s37, 0
	s_add_i32 s88, s66, s33
	global_load_lds_dwordx4 v[228:229], off
	v_lshl_add_u64 v[4:5], s[86:87], 0, v[166:167]
	s_mov_b32 m0, s88
	v_lshl_add_u64 v[230:231], s[40:41], 0, v[164:165]
	global_load_lds_dwordx4 v[4:5], off
	v_lshl_add_u64 v[4:5], s[86:87], 0, v[170:171]
	s_add_i32 m0, s88, 0x2000
	v_lshl_add_u64 v[232:233], s[40:41], 0, v[168:169]
	global_load_lds_dwordx4 v[4:5], off
	s_mov_b32 m0, s42
	s_nop 0
	global_load_lds_dwordx4 v[230:231], off
	s_mov_b32 m0, s43
	s_nop 0
	global_load_lds_dwordx4 v[232:233], off
	s_waitcnt vmcnt(8)
	s_waitcnt lgkmcnt(0)
	s_setprio 3
	s_barrier
; #define PG8_STAGE(bufoff, gbase, voff) do { _Pragma("unroll") for (int _i = 0; _i < 2; ++_i) \
;         __builtin_amdgcn_global_load_lds((const unsigned*)((const char*)(gbase) + (voff)[_i]), (PG8_LAS unsigned*)(lds + (bufoff) + ldsw + _i * 8192), 16, 0, 0); } while (0)
; #define PG8_LDA(dst, b, h) do { _Pragma("unroll") for (int m = 0; m < 4; ++m) _Pragma("unroll") for (int k = 0; k < 2; ++k) dst[m][k] = *(const PG8_LAS bf16x8*)(lds + PG8_SA(b, h) + aoff + m * 2048 + k * 1024); } while (0)
; #define PG8_LDB(dst, b, h) do { _Pragma("unroll") for (int n = 0; n < 2; ++n) _Pragma("unroll") for (int k = 0; k < 2; ++k) dst[n][k] = *(const PG8_LAS bf16x8*)(lds + PG8_SB(b, h) + boff + n * 2048 + k * 1024); } while (0)
; #define PG8_MMA(ai, bj, At, Bt) do { __builtin_amdgcn_s_setprio(3); _Pragma("unroll") for (int m = 0; m < 4; ++m) _Pragma("unroll") for (int n = 0; n < 2; ++n) _Pragma("unroll") for (int k = 0; k < 2; ++k) \
;         acc[ai][bj][m][n] = __builtin_amdgcn_mfma_f32_16x16x32_bf16(Bt[n][k], At[m][k], acc[ai][bj][m][n], 0, 0, 0); __builtin_amdgcn_s_setprio(0); } while (0)
; #define PG8_WAIT_V(n) asm volatile("s_waitcnt vmcnt(" #n ")" ::: "memory")
; #define PG8_WAIT_L(n) asm volatile("s_waitcnt lgkmcnt(" #n ")" ::: "memory")
; #define PG8_BAR __builtin_amdgcn_s_barrier()
; #define PG8_SCHED __builtin_amdgcn_sched_barrier(0)
; template <class Epi, class Sched, bool ALIGN_EPI = false, bool SP2 = false>
; __device__ __forceinline__ void gemm_phase(PG8_LAS unsigned char* lds, const Gemm g, const Sched& S, const Epi& E) {
;     ...
;             PG8_WAIT_V(8); PG8_WAIT_L(0); PG8_BAR; PG8_MMA(1, 0, At, B0); PG8_MMA(1, 1, At, B1); PG8_BAR; PG8_SCHED;
;             PG8_LDB(B0, 1, 0); PG8_LDB(B1, 1, 1); PG8_SCHED; PG8_LDA(At, 1, 0); PG8_STAGE(PG8_SA(0, 1), a2 + hstepA, voffA);
;             PG8_WAIT_V(8); PG8_WAIT_L(0); PG8_BAR; PG8_MMA(0, 0, At, B0); PG8_MMA(0, 1, At, B1); PG8_BAR; PG8_SCHED;
	v_mfma_f32_16x16x32_bf16 v[66:69], v[134:137], v[194:197], v[66:69]
	v_mfma_f32_16x16x32_bf16 v[66:69], v[138:141], v[198:201], v[66:69]
	v_mfma_f32_16x16x32_bf16 v[62:65], v[142:145], v[194:197], v[62:65]
	v_mfma_f32_16x16x32_bf16 v[62:65], v[146:149], v[198:201], v[62:65]
	v_mfma_f32_16x16x32_bf16 v[46:49], v[142:145], v[202:205], v[46:49]
	v_mfma_f32_16x16x32_bf16 v[46:49], v[146:149], v[206:209], v[46:49]
	v_mfma_f32_16x16x32_bf16 v[50:53], v[134:137], v[202:205], v[50:53]
	v_mfma_f32_16x16x32_bf16 v[50:53], v[138:141], v[206:209], v[50:53]
	v_mfma_f32_16x16x32_bf16 v[34:37], v[134:137], v[210:213], v[34:37]
	v_mfma_f32_16x16x32_bf16 v[34:37], v[138:141], v[214:217], v[34:37]
	v_mfma_f32_16x16x32_bf16 v[30:33], v[142:145], v[210:213], v[30:33]
	v_mfma_f32_16x16x32_bf16 v[30:33], v[146:149], v[214:217], v[30:33]
	v_mfma_f32_16x16x32_bf16 v[14:17], v[142:145], v[218:221], v[14:17]
	v_mfma_f32_16x16x32_bf16 v[14:17], v[146:149], v[222:225], v[14:17]
	v_mfma_f32_16x16x32_bf16 v[18:21], v[134:137], v[218:221], v[18:21]
	v_mfma_f32_16x16x32_bf16 v[18:21], v[138:141], v[222:225], v[18:21]
	v_mfma_f32_16x16x32_bf16 v[58:61], v[150:153], v[194:197], v[58:61]
	v_mfma_f32_16x16x32_bf16 v[58:61], v[154:157], v[198:201], v[58:61]
	v_mfma_f32_16x16x32_bf16 v[54:57], v[158:161], v[194:197], v[54:57]
	v_mfma_f32_16x16x32_bf16 v[54:57], v[190:193], v[198:201], v[54:57]
	v_mfma_f32_16x16x32_bf16 v[38:41], v[158:161], v[202:205], v[38:41]
	v_mfma_f32_16x16x32_bf16 v[38:41], v[190:193], v[206:209], v[38:41]
	v_mfma_f32_16x16x32_bf16 v[42:45], v[150:153], v[202:205], v[42:45]
	v_mfma_f32_16x16x32_bf16 v[42:45], v[154:157], v[206:209], v[42:45]
	v_mfma_f32_16x16x32_bf16 v[26:29], v[150:153], v[210:213], v[26:29]
	v_mfma_f32_16x16x32_bf16 v[26:29], v[154:157], v[214:217], v[26:29]
	v_mfma_f32_16x16x32_bf16 v[22:25], v[158:161], v[210:213], v[22:25]
	v_mfma_f32_16x16x32_bf16 v[22:25], v[190:193], v[214:217], v[22:25]
	v_mfma_f32_16x16x32_bf16 v[4:7], v[158:161], v[218:221], v[6:9]
	v_mfma_f32_16x16x32_bf16 v[4:7], v[190:193], v[222:225], v[4:7]
	v_mfma_f32_16x16x32_bf16 v[10:13], v[150:153], v[218:221], v[10:13]
	v_mfma_f32_16x16x32_bf16 v[10:13], v[154:157], v[222:225], v[10:13]
	s_setprio 0
	s_barrier
	s_add_i32 s86, 0, 0x18000
	v_add_u32_e32 v3, s86, v186
	s_add_i32 s87, 0, 0x1c000
	ds_read_b128 v[134:137], v3
	ds_read_b128 v[138:141], v3 offset:1024
	ds_read_b128 v[142:145], v3 offset:2048
	ds_read_b128 v[146:149], v3 offset:3072
	v_add_u32_e32 v3, s87, v186
	ds_read_b128 v[150:153], v3
	ds_read_b128 v[154:157], v3 offset:1024
	ds_read_b128 v[158:161], v3 offset:2048
	ds_read_b128 v[190:193], v3 offset:3072
	s_add_u32 s40, s40, 0x100000
	s_addc_u32 s41, s41, 0
	s_mov_b32 m0, s44
	v_lshl_add_u64 v[8:9], s[40:41], 0, v[164:165]
	ds_read_b128 v[194:197], v188 offset:32768
	ds_read_b128 v[198:201], v188 offset:33792
	ds_read_b128 v[202:205], v188 offset:34816
	ds_read_b128 v[206:209], v188 offset:35840
	ds_read_b128 v[210:213], v188 offset:36864
	ds_read_b128 v[214:217], v188 offset:37888
	ds_read_b128 v[218:221], v188 offset:38912
	ds_read_b128 v[222:225], v188 offset:39936
	global_load_lds_dwordx4 v[8:9], off
	v_lshl_add_u64 v[8:9], s[40:41], 0, v[168:169]
	s_mov_b32 m0, s45
	s_nop 0
	global_load_lds_dwordx4 v[8:9], off
	s_waitcnt vmcnt(8)
	s_waitcnt lgkmcnt(0)
	s_setprio 3
	s_barrier
	v_mfma_f32_16x16x32_bf16 v[130:133], v[134:137], v[194:197], v[130:133]
	v_mfma_f32_16x16x32_bf16 v[130:133], v[138:141], v[198:201], v[130:133]
	v_mfma_f32_16x16x32_bf16 v[126:129], v[142:145], v[194:197], v[126:129]
	v_mfma_f32_16x16x32_bf16 v[126:129], v[146:149], v[198:201], v[126:129]
	v_mfma_f32_16x16x32_bf16 v[110:113], v[142:145], v[202:205], v[110:113]
	v_mfma_f32_16x16x32_bf16 v[110:113], v[146:149], v[206:209], v[110:113]
	v_mfma_f32_16x16x32_bf16 v[114:117], v[134:137], v[202:205], v[114:117]
	v_mfma_f32_16x16x32_bf16 v[114:117], v[138:141], v[206:209], v[114:117]
	v_mfma_f32_16x16x32_bf16 v[98:101], v[134:137], v[210:213], v[98:101]
	v_mfma_f32_16x16x32_bf16 v[98:101], v[138:141], v[214:217], v[98:101]
	v_mfma_f32_16x16x32_bf16 v[94:97], v[142:145], v[210:213], v[94:97]
	v_mfma_f32_16x16x32_bf16 v[94:97], v[146:149], v[214:217], v[94:97]
	v_mfma_f32_16x16x32_bf16 v[78:81], v[142:145], v[218:221], v[78:81]
	v_mfma_f32_16x16x32_bf16 v[78:81], v[146:149], v[222:225], v[78:81]
	v_mfma_f32_16x16x32_bf16 v[82:85], v[134:137], v[218:221], v[82:85]
	v_mfma_f32_16x16x32_bf16 v[82:85], v[138:141], v[222:225], v[82:85]
	v_mfma_f32_16x16x32_bf16 v[122:125], v[150:153], v[194:197], v[122:125]
	v_mfma_f32_16x16x32_bf16 v[122:125], v[154:157], v[198:201], v[122:125]
	v_mfma_f32_16x16x32_bf16 v[118:121], v[158:161], v[194:197], v[118:121]
	v_mfma_f32_16x16x32_bf16 v[118:121], v[190:193], v[198:201], v[118:121]
	v_mfma_f32_16x16x32_bf16 v[102:105], v[158:161], v[202:205], v[102:105]
	v_mfma_f32_16x16x32_bf16 v[102:105], v[190:193], v[206:209], v[102:105]
	v_mfma_f32_16x16x32_bf16 v[106:109], v[150:153], v[202:205], v[106:109]
	v_mfma_f32_16x16x32_bf16 v[106:109], v[154:157], v[206:209], v[106:109]
	v_mfma_f32_16x16x32_bf16 v[90:93], v[150:153], v[210:213], v[90:93]
	v_mfma_f32_16x16x32_bf16 v[90:93], v[154:157], v[214:217], v[90:93]
	v_mfma_f32_16x16x32_bf16 v[86:89], v[158:161], v[210:213], v[86:89]
	v_mfma_f32_16x16x32_bf16 v[86:89], v[190:193], v[214:217], v[86:89]
	v_mfma_f32_16x16x32_bf16 v[70:73], v[158:161], v[218:221], v[70:73]
	v_mfma_f32_16x16x32_bf16 v[70:73], v[190:193], v[222:225], v[70:73]
	v_mfma_f32_16x16x32_bf16 v[74:77], v[150:153], v[218:221], v[74:77]
	v_mfma_f32_16x16x32_bf16 v[74:77], v[154:157], v[222:225], v[74:77]
	s_setprio 0
	s_barrier
; #define PG8_STAGE(bufoff, gbase, voff) do { _Pragma("unroll") for (int _i = 0; _i < 2; ++_i) \
;         __builtin_amdgcn_global_load_lds((const unsigned*)((const char*)(gbase) + (voff)[_i]), (PG8_LAS unsigned*)(lds + (bufoff) + ldsw + _i * 8192), 16, 0, 0); } while (0)
; #define PG8_LDA(dst, b, h) do { _Pragma("unroll") for (int m = 0; m < 4; ++m) _Pragma("unroll") for (int k = 0; k < 2; ++k) dst[m][k] = *(const PG8_LAS bf16x8*)(lds + PG8_SA(b, h) + aoff + m * 2048 + k * 1024); } while (0)
; #define PG8_MMA(ai, bj, At, Bt) do { __builtin_amdgcn_s_setprio(3); _Pragma("unroll") for (int m = 0; m < 4; ++m) _Pragma("unroll") for (int n = 0; n < 2; ++n) _Pragma("unroll") for (int k = 0; k < 2; ++k) \
;         acc[ai][bj][m][n] = __builtin_amdgcn_mfma_f32_16x16x32_bf16(Bt[n][k], At[m][k], acc[ai][bj][m][n], 0, 0, 0); __builtin_amdgcn_s_setprio(0); } while (0)
; #define PG8_WAIT_V(n) asm volatile("s_waitcnt vmcnt(" #n ")" ::: "memory")
; #define PG8_WAIT_L(n) asm volatile("s_waitcnt lgkmcnt(" #n ")" ::: "memory")
; #define PG8_BAR __builtin_amdgcn_s_barrier()
; #define PG8_SCHED __builtin_amdgcn_sched_barrier(0)
; template <class Epi, class Sched, bool ALIGN_EPI = false, bool SP2 = false>
; __device__ __forceinline__ void gemm_phase(PG8_LAS unsigned char* lds, const Gemm g, const Sched& S, const Epi& E) {
;     ...
;             PG8_LDA(At, 1, 1); PG8_STAGE(PG8_SB(1, 0), b3, voffB); PG8_STAGE(PG8_SB(1, 1), b3 + hstepB, voffB); PG8_STAGE(PG8_SA(1, 0), a3, voffA);
;             PG8_WAIT_V(8); PG8_WAIT_L(0); PG8_BAR; PG8_MMA(1, 0, At, B0); PG8_MMA(1, 1, At, B1); PG8_BAR; PG8_SCHED;
	s_add_i32 s40, s86, s33
	v_lshl_add_u64 v[8:9], v[226:227], 0, s[10:11]
	s_mov_b32 m0, s40
	ds_read_b128 v[194:197], v188 offset:49152
	ds_read_b128 v[198:201], v188 offset:50176
	ds_read_b128 v[202:205], v188 offset:51200
	ds_read_b128 v[206:209], v188 offset:52224
	ds_read_b128 v[210:213], v188 offset:53248
	ds_read_b128 v[214:217], v188 offset:54272
	ds_read_b128 v[218:221], v188 offset:55296
	ds_read_b128 v[222:225], v188 offset:56320
	global_load_lds_dwordx4 v[8:9], off
	s_add_i32 m0, s40, 0x2000
	s_add_u32 s36, s36, 0x100080
	v_lshl_add_u64 v[8:9], v[228:229], 0, s[10:11]
	s_addc_u32 s37, s37, 0
	s_add_i32 s40, s87, s33
	global_load_lds_dwordx4 v[8:9], off
	v_lshl_add_u64 v[8:9], s[36:37], 0, v[166:167]
	s_mov_b32 m0, s40
	s_nop 0
	global_load_lds_dwordx4 v[8:9], off
	v_lshl_add_u64 v[8:9], s[36:37], 0, v[170:171]
	s_add_i32 m0, s40, 0x2000
	s_nop 0
	global_load_lds_dwordx4 v[8:9], off
	v_lshl_add_u64 v[8:9], v[230:231], 0, s[10:11]
	s_mov_b32 m0, s60
	s_nop 0
	global_load_lds_dwordx4 v[8:9], off
	v_lshl_add_u64 v[8:9], v[232:233], 0, s[10:11]
	s_mov_b32 m0, s61
	s_nop 0
	global_load_lds_dwordx4 v[8:9], off
	s_waitcnt vmcnt(8)
	s_waitcnt lgkmcnt(0)
	s_setprio 3
	s_barrier
	v_mfma_f32_16x16x32_bf16 v[66:69], v[134:137], v[194:197], v[66:69]
	v_mfma_f32_16x16x32_bf16 v[66:69], v[138:141], v[198:201], v[66:69]
	v_mfma_f32_16x16x32_bf16 v[62:65], v[142:145], v[194:197], v[62:65]
	v_mfma_f32_16x16x32_bf16 v[62:65], v[146:149], v[198:201], v[62:65]
	v_mfma_f32_16x16x32_bf16 v[46:49], v[142:145], v[202:205], v[46:49]
	v_mfma_f32_16x16x32_bf16 v[46:49], v[146:149], v[206:209], v[46:49]
	v_mfma_f32_16x16x32_bf16 v[50:53], v[134:137], v[202:205], v[50:53]
	v_mfma_f32_16x16x32_bf16 v[50:53], v[138:141], v[206:209], v[50:53]
	v_mfma_f32_16x16x32_bf16 v[34:37], v[134:137], v[210:213], v[34:37]
	v_mfma_f32_16x16x32_bf16 v[34:37], v[138:141], v[214:217], v[34:37]
	v_mfma_f32_16x16x32_bf16 v[30:33], v[142:145], v[210:213], v[30:33]
	v_mfma_f32_16x16x32_bf16 v[30:33], v[146:149], v[214:217], v[30:33]
	v_mfma_f32_16x16x32_bf16 v[14:17], v[142:145], v[218:221], v[14:17]
	v_mfma_f32_16x16x32_bf16 v[14:17], v[146:149], v[222:225], v[14:17]
	v_mfma_f32_16x16x32_bf16 v[18:21], v[134:137], v[218:221], v[18:21]
	v_mfma_f32_16x16x32_bf16 v[18:21], v[138:141], v[222:225], v[18:21]
	v_mfma_f32_16x16x32_bf16 v[58:61], v[150:153], v[194:197], v[58:61]
	v_mfma_f32_16x16x32_bf16 v[54:57], v[158:161], v[194:197], v[54:57]
	v_mfma_f32_16x16x32_bf16 v[42:45], v[150:153], v[202:205], v[42:45]
	v_mfma_f32_16x16x32_bf16 v[38:41], v[158:161], v[202:205], v[38:41]
	v_mfma_f32_16x16x32_bf16 v[26:29], v[150:153], v[210:213], v[26:29]
	v_mfma_f32_16x16x32_bf16 v[22:25], v[158:161], v[210:213], v[22:25]
	v_mfma_f32_16x16x32_bf16 v[8:11], v[150:153], v[218:221], v[10:13]
	v_mfma_f32_16x16x32_bf16 v[4:7], v[158:161], v[218:221], v[4:7]
	v_mfma_f32_16x16x32_bf16 v[58:61], v[154:157], v[198:201], v[58:61]
	v_mfma_f32_16x16x32_bf16 v[54:57], v[190:193], v[198:201], v[54:57]
	v_mfma_f32_16x16x32_bf16 v[42:45], v[154:157], v[206:209], v[42:45]
	v_mfma_f32_16x16x32_bf16 v[38:41], v[190:193], v[206:209], v[38:41]
	v_mfma_f32_16x16x32_bf16 v[26:29], v[154:157], v[214:217], v[26:29]
	v_mfma_f32_16x16x32_bf16 v[22:25], v[190:193], v[214:217], v[22:25]
	v_mfma_f32_16x16x32_bf16 v[10:13], v[154:157], v[222:225], v[8:11]
	v_mfma_f32_16x16x32_bf16 v[6:9], v[190:193], v[222:225], v[4:7]
	s_setprio 0
	s_barrier
	s_add_i32 s85, s85, 2
	s_add_u32 s30, s30, 0x100
	s_addc_u32 s31, s31, 0
	s_cmp_gt_u32 s85, 61
	s_cbranch_scc1 .LBB0_811

; #define PG8_STAGE(bufoff, gbase, voff) do { _Pragma("unroll") for (int _i = 0; _i < 2; ++_i) \
;         __builtin_amdgcn_global_load_lds((const unsigned*)((const char*)(gbase) + (voff)[_i]), (PG8_LAS unsigned*)(lds + (bufoff) + ldsw + _i * 8192), 16, 0, 0); } while (0)
; #define PG8_LDA(dst, b, h) do { _Pragma("unroll") for (int m = 0; m < 4; ++m) _Pragma("unroll") for (int k = 0; k < 2; ++k) dst[m][k] = *(const PG8_LAS bf16x8*)(lds + PG8_SA(b, h) + aoff + m * 2048 + k * 1024); } while (0)
; #define PG8_LDB(dst, b, h) do { _Pragma("unroll") for (int n = 0; n < 2; ++n) _Pragma("unroll") for (int k = 0; k < 2; ++k) dst[n][k] = *(const PG8_LAS bf16x8*)(lds + PG8_SB(b, h) + boff + n * 2048 + k * 1024); } while (0)
; #define PG8_MMA(ai, bj, At, Bt) do { __builtin_amdgcn_s_setprio(3); _Pragma("unroll") for (int m = 0; m < 4; ++m) _Pragma("unroll") for (int n = 0; n < 2; ++n) _Pragma("unroll") for (int k = 0; k < 2; ++k) \
;         acc[ai][bj][m][n] = __builtin_amdgcn_mfma_f32_16x16x32_bf16(Bt[n][k], At[m][k], acc[ai][bj][m][n], 0, 0, 0); __builtin_amdgcn_s_setprio(0); } while (0)
; #define PG8_WAIT_V(n) asm volatile("s_waitcnt vmcnt(" #n ")" ::: "memory")
; #define PG8_WAIT_L(n) asm volatile("s_waitcnt lgkmcnt(" #n ")" ::: "memory")
; #define PG8_BAR __builtin_amdgcn_s_barrier()
; #define PG8_SCHED __builtin_amdgcn_sched_barrier(0)
; template <class Epi, class Sched, bool ALIGN_EPI = false, bool SP2 = false>
; __device__ __forceinline__ void gemm_phase(PG8_LAS unsigned char* lds, const Gemm g, const Sched& S, const Epi& E) {
;     ...
;             PG8_LDB(B0, 0, 0); PG8_LDB(B1, 0, 1); PG8_SCHED; PG8_LDA(At, 0, 0); PG8_STAGE(PG8_SA(1, 1), a1 + hstepA, voffA);
;             PG8_WAIT_V(8); PG8_WAIT_L(0); PG8_BAR; PG8_MMA(0, 0, At, B0); PG8_MMA(0, 1, At, B1); PG8_BAR; PG8_SCHED;
;             PG8_LDA(At, 0, 1); PG8_STAGE(PG8_SB(0, 0), b2, voffB); PG8_STAGE(PG8_SB(0, 1), b2 + hstepB, voffB); PG8_STAGE(PG8_SA(0, 0), a2, voffA);
;             PG8_WAIT_V(8); PG8_WAIT_L(0); PG8_BAR; PG8_MMA(1, 0, At, B0); PG8_MMA(1, 1, At, B1); PG8_BAR; PG8_SCHED;
.LBB0_908:
	ds_read_b128 v[158:161], v155
	ds_read_b128 v[164:167], v155 offset:1024
	ds_read_b128 v[168:171], v155 offset:2048
	ds_read_b128 v[172:175], v155 offset:3072
	ds_read_b128 v[176:179], v156
	ds_read_b128 v[180:183], v156 offset:1024
	ds_read_b128 v[184:187], v156 offset:2048
	ds_read_b128 v[188:191], v156 offset:3072
	s_add_u32 s26, s24, 0xfff00080
	s_addc_u32 s27, s25, -1
	s_cmp_eq_u32 s55, 60
	s_cselect_b32 s29, s17, s27
	s_cselect_b32 s28, s47, s26
	s_cselect_b32 s27, s15, s54
	s_cselect_b32 s26, s52, s53
	v_lshl_add_u64 v[146:147], s[24:25], 0, v[138:139]
	s_add_i32 m0, s23, 0xc000
	ds_read_b128 v[192:195], v157
	ds_read_b128 v[196:199], v157 offset:1024
	ds_read_b128 v[200:203], v157 offset:2048
	ds_read_b128 v[204:207], v157 offset:3072
	ds_read_b128 v[208:211], v157 offset:4096
	ds_read_b128 v[212:215], v157 offset:5120
	ds_read_b128 v[216:219], v157 offset:6144
	ds_read_b128 v[220:223], v157 offset:7168
	global_load_lds_dwordx4 v[146:147], off
	v_lshl_add_u64 v[146:147], s[24:25], 0, v[140:141]
	s_add_i32 m0, s23, 0xe000
	s_nop 0
	global_load_lds_dwordx4 v[146:147], off
	s_waitcnt vmcnt(8)
	s_waitcnt lgkmcnt(0)
	s_setprio 3
	s_barrier
	v_mfma_f32_16x16x32_bf16 v[126:129], v[158:161], v[192:195], v[126:129]
	v_mfma_f32_16x16x32_bf16 v[126:129], v[164:167], v[196:199], v[126:129]
	v_mfma_f32_16x16x32_bf16 v[122:125], v[168:171], v[192:195], v[122:125]
	v_mfma_f32_16x16x32_bf16 v[122:125], v[172:175], v[196:199], v[122:125]
	v_mfma_f32_16x16x32_bf16 v[106:109], v[168:171], v[200:203], v[106:109]
	v_mfma_f32_16x16x32_bf16 v[106:109], v[172:175], v[204:207], v[106:109]
	v_mfma_f32_16x16x32_bf16 v[114:117], v[158:161], v[200:203], v[114:117]
	v_mfma_f32_16x16x32_bf16 v[114:117], v[164:167], v[204:207], v[114:117]
	v_mfma_f32_16x16x32_bf16 v[98:101], v[158:161], v[208:211], v[98:101]
	v_mfma_f32_16x16x32_bf16 v[98:101], v[164:167], v[212:215], v[98:101]
	v_mfma_f32_16x16x32_bf16 v[90:93], v[168:171], v[208:211], v[90:93]
	v_mfma_f32_16x16x32_bf16 v[90:93], v[172:175], v[212:215], v[90:93]
	v_mfma_f32_16x16x32_bf16 v[74:77], v[168:171], v[216:219], v[74:77]
	v_mfma_f32_16x16x32_bf16 v[74:77], v[172:175], v[220:223], v[74:77]
	v_mfma_f32_16x16x32_bf16 v[82:85], v[158:161], v[216:219], v[82:85]
	v_mfma_f32_16x16x32_bf16 v[82:85], v[164:167], v[220:223], v[82:85]
	v_mfma_f32_16x16x32_bf16 v[118:121], v[176:179], v[192:195], v[118:121]
	v_mfma_f32_16x16x32_bf16 v[118:121], v[180:183], v[196:199], v[118:121]
	v_mfma_f32_16x16x32_bf16 v[110:113], v[184:187], v[192:195], v[110:113]
	v_mfma_f32_16x16x32_bf16 v[110:113], v[188:191], v[196:199], v[110:113]
	v_mfma_f32_16x16x32_bf16 v[94:97], v[184:187], v[200:203], v[94:97]
	v_mfma_f32_16x16x32_bf16 v[94:97], v[188:191], v[204:207], v[94:97]
	v_mfma_f32_16x16x32_bf16 v[102:105], v[176:179], v[200:203], v[102:105]
	v_mfma_f32_16x16x32_bf16 v[102:105], v[180:183], v[204:207], v[102:105]
	v_mfma_f32_16x16x32_bf16 v[86:89], v[176:179], v[208:211], v[86:89]
	v_mfma_f32_16x16x32_bf16 v[86:89], v[180:183], v[212:215], v[86:89]
	v_mfma_f32_16x16x32_bf16 v[78:81], v[184:187], v[208:211], v[78:81]
	v_mfma_f32_16x16x32_bf16 v[78:81], v[188:191], v[212:215], v[78:81]
	v_mfma_f32_16x16x32_bf16 v[66:69], v[184:187], v[216:219], v[66:69]
	v_mfma_f32_16x16x32_bf16 v[66:69], v[188:191], v[220:223], v[66:69]
	v_mfma_f32_16x16x32_bf16 v[70:73], v[176:179], v[216:219], v[70:73]
	v_mfma_f32_16x16x32_bf16 v[70:73], v[180:183], v[220:223], v[70:73]
	s_setprio 0
	s_barrier
	s_add_i32 s56, s42, s30
	v_lshl_add_u64 v[146:147], s[26:27], 0, v[134:135]
	s_mov_b32 m0, s56
	ds_read_b128 v[192:195], v157 offset:16384
	ds_read_b128 v[196:199], v157 offset:17408
	ds_read_b128 v[200:203], v157 offset:18432
	ds_read_b128 v[204:207], v157 offset:19456
	ds_read_b128 v[208:211], v157 offset:20480
	ds_read_b128 v[212:215], v157 offset:21504
	ds_read_b128 v[216:219], v157 offset:22528
	ds_read_b128 v[220:223], v157 offset:23552
	global_load_lds_dwordx4 v[146:147], off
	s_add_i32 m0, s56, 0x2000
	s_add_u32 s56, s26, 0x100000
	v_lshl_add_u64 v[224:225], s[26:27], 0, v[130:131]
	s_addc_u32 s57, s27, 0
	s_add_i32 s58, s43, s30
	global_load_lds_dwordx4 v[224:225], off
	v_lshl_add_u64 v[226:227], s[56:57], 0, v[134:135]
	s_mov_b32 m0, s58
	v_lshl_add_u64 v[228:229], s[28:29], 0, v[132:133]
	global_load_lds_dwordx4 v[226:227], off
	v_lshl_add_u64 v[226:227], s[56:57], 0, v[130:131]
	s_add_i32 m0, s58, 0x2000
	s_nop 0
	global_load_lds_dwordx4 v[226:227], off
	v_lshl_add_u64 v[226:227], s[28:29], 0, v[136:137]
	s_mov_b32 m0, s23
	s_nop 0
	global_load_lds_dwordx4 v[226:227], off
	s_mov_b32 m0, s33
	s_nop 0
	global_load_lds_dwordx4 v[228:229], off
	s_waitcnt vmcnt(8)
	s_waitcnt lgkmcnt(0)
	s_setprio 3
	s_barrier
; #define PG8_STAGE(bufoff, gbase, voff) do { _Pragma("unroll") for (int _i = 0; _i < 2; ++_i) \
;         __builtin_amdgcn_global_load_lds((const unsigned*)((const char*)(gbase) + (voff)[_i]), (PG8_LAS unsigned*)(lds + (bufoff) + ldsw + _i * 8192), 16, 0, 0); } while (0)
; #define PG8_LDA(dst, b, h) do { _Pragma("unroll") for (int m = 0; m < 4; ++m) _Pragma("unroll") for (int k = 0; k < 2; ++k) dst[m][k] = *(const PG8_LAS bf16x8*)(lds + PG8_SA(b, h) + aoff + m * 2048 + k * 1024); } while (0)
; #define PG8_LDB(dst, b, h) do { _Pragma("unroll") for (int n = 0; n < 2; ++n) _Pragma("unroll") for (int k = 0; k < 2; ++k) dst[n][k] = *(const PG8_LAS bf16x8*)(lds + PG8_SB(b, h) + boff + n * 2048 + k * 1024); } while (0)
; #define PG8_MMA(ai, bj, At, Bt) do { __builtin_amdgcn_s_setprio(3); _Pragma("unroll") for (int m = 0; m < 4; ++m) _Pragma("unroll") for (int n = 0; n < 2; ++n) _Pragma("unroll") for (int k = 0; k < 2; ++k) \
;         acc[ai][bj][m][n] = __builtin_amdgcn_mfma_f32_16x16x32_bf16(Bt[n][k], At[m][k], acc[ai][bj][m][n], 0, 0, 0); __builtin_amdgcn_s_setprio(0); } while (0)
; #define PG8_WAIT_V(n) asm volatile("s_waitcnt vmcnt(" #n ")" ::: "memory")
; #define PG8_WAIT_L(n) asm volatile("s_waitcnt lgkmcnt(" #n ")" ::: "memory")
; #define PG8_BAR __builtin_amdgcn_s_barrier()
; #define PG8_SCHED __builtin_amdgcn_sched_barrier(0)
; template <class Epi, class Sched, bool ALIGN_EPI = false, bool SP2 = false>
; __device__ __forceinline__ void gemm_phase(PG8_LAS unsigned char* lds, const Gemm g, const Sched& S, const Epi& E) {
;     ...
;             PG8_WAIT_V(8); PG8_WAIT_L(0); PG8_BAR; PG8_MMA(1, 0, At, B0); PG8_MMA(1, 1, At, B1); PG8_BAR; PG8_SCHED;
;             PG8_LDB(B0, 1, 0); PG8_LDB(B1, 1, 1); PG8_SCHED; PG8_LDA(At, 1, 0); PG8_STAGE(PG8_SA(0, 1), a2 + hstepA, voffA);
;             PG8_WAIT_V(8); PG8_WAIT_L(0); PG8_BAR; PG8_MMA(0, 0, At, B0); PG8_MMA(0, 1, At, B1); PG8_BAR; PG8_SCHED;
	v_mfma_f32_16x16x32_bf16 v[62:65], v[158:161], v[192:195], v[62:65]
	v_mfma_f32_16x16x32_bf16 v[62:65], v[164:167], v[196:199], v[62:65]
	v_mfma_f32_16x16x32_bf16 v[58:61], v[168:171], v[192:195], v[58:61]
	v_mfma_f32_16x16x32_bf16 v[58:61], v[172:175], v[196:199], v[58:61]
	v_mfma_f32_16x16x32_bf16 v[42:45], v[168:171], v[200:203], v[42:45]
	v_mfma_f32_16x16x32_bf16 v[42:45], v[172:175], v[204:207], v[42:45]
	v_mfma_f32_16x16x32_bf16 v[50:53], v[158:161], v[200:203], v[50:53]
	v_mfma_f32_16x16x32_bf16 v[50:53], v[164:167], v[204:207], v[50:53]
	v_mfma_f32_16x16x32_bf16 v[34:37], v[158:161], v[208:211], v[34:37]
	v_mfma_f32_16x16x32_bf16 v[34:37], v[164:167], v[212:215], v[34:37]
	v_mfma_f32_16x16x32_bf16 v[26:29], v[168:171], v[208:211], v[26:29]
	v_mfma_f32_16x16x32_bf16 v[26:29], v[172:175], v[212:215], v[26:29]
	v_mfma_f32_16x16x32_bf16 v[10:13], v[168:171], v[216:219], v[10:13]
	v_mfma_f32_16x16x32_bf16 v[10:13], v[172:175], v[220:223], v[10:13]
	v_mfma_f32_16x16x32_bf16 v[14:17], v[158:161], v[216:219], v[14:17]
	v_mfma_f32_16x16x32_bf16 v[14:17], v[164:167], v[220:223], v[14:17]
	v_mfma_f32_16x16x32_bf16 v[54:57], v[176:179], v[192:195], v[54:57]
	v_mfma_f32_16x16x32_bf16 v[54:57], v[180:183], v[196:199], v[54:57]
	v_mfma_f32_16x16x32_bf16 v[46:49], v[184:187], v[192:195], v[46:49]
	v_mfma_f32_16x16x32_bf16 v[46:49], v[188:191], v[196:199], v[46:49]
	v_mfma_f32_16x16x32_bf16 v[30:33], v[184:187], v[200:203], v[30:33]
	v_mfma_f32_16x16x32_bf16 v[30:33], v[188:191], v[204:207], v[30:33]
	v_mfma_f32_16x16x32_bf16 v[38:41], v[176:179], v[200:203], v[38:41]
	v_mfma_f32_16x16x32_bf16 v[38:41], v[180:183], v[204:207], v[38:41]
	v_mfma_f32_16x16x32_bf16 v[22:25], v[176:179], v[208:211], v[22:25]
	v_mfma_f32_16x16x32_bf16 v[22:25], v[180:183], v[212:215], v[22:25]
	v_mfma_f32_16x16x32_bf16 v[18:21], v[184:187], v[208:211], v[18:21]
	v_mfma_f32_16x16x32_bf16 v[18:21], v[188:191], v[212:215], v[18:21]
	v_mfma_f32_16x16x32_bf16 v[2:5], v[184:187], v[216:219], v[2:5]
	v_mfma_f32_16x16x32_bf16 v[2:5], v[188:191], v[220:223], v[2:5]
	v_mfma_f32_16x16x32_bf16 v[6:9], v[176:179], v[216:219], v[6:9]
	v_mfma_f32_16x16x32_bf16 v[6:9], v[180:183], v[220:223], v[6:9]
	s_setprio 0
	s_barrier
	s_add_i32 s56, 0, 0x18000
	v_add_u32_e32 v148, s56, v151
	s_add_i32 s57, 0, 0x1c000
	ds_read_b128 v[158:161], v148
	ds_read_b128 v[164:167], v148 offset:1024
	ds_read_b128 v[168:171], v148 offset:2048
	ds_read_b128 v[172:175], v148 offset:3072
	v_add_u32_e32 v148, s57, v151
	ds_read_b128 v[176:179], v148
	ds_read_b128 v[180:183], v148 offset:1024
	ds_read_b128 v[184:187], v148 offset:2048
	ds_read_b128 v[188:191], v148 offset:3072
	s_add_u32 s28, s28, 0x100000
	s_addc_u32 s29, s29, 0
	s_mov_b32 m0, s36
	v_lshl_add_u64 v[230:231], s[28:29], 0, v[136:137]
	ds_read_b128 v[192:195], v157 offset:32768
	ds_read_b128 v[196:199], v157 offset:33792
	ds_read_b128 v[200:203], v157 offset:34816
	ds_read_b128 v[204:207], v157 offset:35840
	ds_read_b128 v[208:211], v157 offset:36864
	ds_read_b128 v[212:215], v157 offset:37888
	ds_read_b128 v[216:219], v157 offset:38912
	ds_read_b128 v[220:223], v157 offset:39936
	global_load_lds_dwordx4 v[230:231], off
	v_lshl_add_u64 v[230:231], s[28:29], 0, v[132:133]
	s_mov_b32 m0, s37
	s_nop 0
	global_load_lds_dwordx4 v[230:231], off
	s_waitcnt vmcnt(8)
	s_waitcnt lgkmcnt(0)
	s_setprio 3
	s_barrier
	v_mfma_f32_16x16x32_bf16 v[126:129], v[158:161], v[192:195], v[126:129]
	v_mfma_f32_16x16x32_bf16 v[126:129], v[164:167], v[196:199], v[126:129]
	v_mfma_f32_16x16x32_bf16 v[122:125], v[168:171], v[192:195], v[122:125]
	v_mfma_f32_16x16x32_bf16 v[122:125], v[172:175], v[196:199], v[122:125]
	v_mfma_f32_16x16x32_bf16 v[106:109], v[168:171], v[200:203], v[106:109]
	v_mfma_f32_16x16x32_bf16 v[106:109], v[172:175], v[204:207], v[106:109]
	v_mfma_f32_16x16x32_bf16 v[114:117], v[158:161], v[200:203], v[114:117]
	v_mfma_f32_16x16x32_bf16 v[114:117], v[164:167], v[204:207], v[114:117]
	v_mfma_f32_16x16x32_bf16 v[98:101], v[158:161], v[208:211], v[98:101]
	v_mfma_f32_16x16x32_bf16 v[98:101], v[164:167], v[212:215], v[98:101]
	v_mfma_f32_16x16x32_bf16 v[90:93], v[168:171], v[208:211], v[90:93]
	v_mfma_f32_16x16x32_bf16 v[90:93], v[172:175], v[212:215], v[90:93]
	v_mfma_f32_16x16x32_bf16 v[74:77], v[168:171], v[216:219], v[74:77]
	v_mfma_f32_16x16x32_bf16 v[74:77], v[172:175], v[220:223], v[74:77]
	v_mfma_f32_16x16x32_bf16 v[82:85], v[158:161], v[216:219], v[82:85]
	v_mfma_f32_16x16x32_bf16 v[82:85], v[164:167], v[220:223], v[82:85]
	v_mfma_f32_16x16x32_bf16 v[118:121], v[176:179], v[192:195], v[118:121]
	v_mfma_f32_16x16x32_bf16 v[118:121], v[180:183], v[196:199], v[118:121]
	v_mfma_f32_16x16x32_bf16 v[110:113], v[184:187], v[192:195], v[110:113]
	v_mfma_f32_16x16x32_bf16 v[110:113], v[188:191], v[196:199], v[110:113]
	v_mfma_f32_16x16x32_bf16 v[94:97], v[184:187], v[200:203], v[94:97]
	v_mfma_f32_16x16x32_bf16 v[94:97], v[188:191], v[204:207], v[94:97]
	v_mfma_f32_16x16x32_bf16 v[102:105], v[176:179], v[200:203], v[102:105]
	v_mfma_f32_16x16x32_bf16 v[102:105], v[180:183], v[204:207], v[102:105]
	v_mfma_f32_16x16x32_bf16 v[86:89], v[176:179], v[208:211], v[86:89]
	v_mfma_f32_16x16x32_bf16 v[86:89], v[180:183], v[212:215], v[86:89]
	v_mfma_f32_16x16x32_bf16 v[78:81], v[184:187], v[208:211], v[78:81]
	v_mfma_f32_16x16x32_bf16 v[78:81], v[188:191], v[212:215], v[78:81]
	v_mfma_f32_16x16x32_bf16 v[66:69], v[184:187], v[216:219], v[66:69]
	v_mfma_f32_16x16x32_bf16 v[66:69], v[188:191], v[220:223], v[66:69]
	v_mfma_f32_16x16x32_bf16 v[70:73], v[176:179], v[216:219], v[70:73]
	v_mfma_f32_16x16x32_bf16 v[70:73], v[180:183], v[220:223], v[70:73]
	s_setprio 0
	s_barrier
; #define PG8_STAGE(bufoff, gbase, voff) do { _Pragma("unroll") for (int _i = 0; _i < 2; ++_i) \
;         __builtin_amdgcn_global_load_lds((const unsigned*)((const char*)(gbase) + (voff)[_i]), (PG8_LAS unsigned*)(lds + (bufoff) + ldsw + _i * 8192), 16, 0, 0); } while (0)
; #define PG8_LDA(dst, b, h) do { _Pragma("unroll") for (int m = 0; m < 4; ++m) _Pragma("unroll") for (int k = 0; k < 2; ++k) dst[m][k] = *(const PG8_LAS bf16x8*)(lds + PG8_SA(b, h) + aoff + m * 2048 + k * 1024); } while (0)
; #define PG8_MMA(ai, bj, At, Bt) do { __builtin_amdgcn_s_setprio(3); _Pragma("unroll") for (int m = 0; m < 4; ++m) _Pragma("unroll") for (int n = 0; n < 2; ++n) _Pragma("unroll") for (int k = 0; k < 2; ++k) \
;         acc[ai][bj][m][n] = __builtin_amdgcn_mfma_f32_16x16x32_bf16(Bt[n][k], At[m][k], acc[ai][bj][m][n], 0, 0, 0); __builtin_amdgcn_s_setprio(0); } while (0)
; #define PG8_WAIT_V(n) asm volatile("s_waitcnt vmcnt(" #n ")" ::: "memory")
; #define PG8_WAIT_L(n) asm volatile("s_waitcnt lgkmcnt(" #n ")" ::: "memory")
; #define PG8_BAR __builtin_amdgcn_s_barrier()
; #define PG8_SCHED __builtin_amdgcn_sched_barrier(0)
; template <class Epi, class Sched, bool ALIGN_EPI = false, bool SP2 = false>
; __device__ __forceinline__ void gemm_phase(PG8_LAS unsigned char* lds, const Gemm g, const Sched& S, const Epi& E) {
;     ...
;             PG8_LDA(At, 1, 1); PG8_STAGE(PG8_SB(1, 0), b3, voffB); PG8_STAGE(PG8_SB(1, 1), b3 + hstepB, voffB); PG8_STAGE(PG8_SA(1, 0), a3, voffA);
;             PG8_WAIT_V(8); PG8_WAIT_L(0); PG8_BAR; PG8_MMA(1, 0, At, B0); PG8_MMA(1, 1, At, B1); PG8_BAR; PG8_SCHED;
;     ...
;         if constexpr (ALIGN_EPI) { if (wr == 0) PG8_BAR; }
	s_add_i32 s28, s56, s30
	v_lshl_add_u64 v[146:147], v[146:147], 0, s[12:13]
	s_mov_b32 m0, s28
	ds_read_b128 v[192:195], v157 offset:49152
	ds_read_b128 v[196:199], v157 offset:50176
	ds_read_b128 v[200:203], v157 offset:51200
	ds_read_b128 v[204:207], v157 offset:52224
	ds_read_b128 v[208:211], v157 offset:53248
	ds_read_b128 v[212:215], v157 offset:54272
	ds_read_b128 v[216:219], v157 offset:55296
	ds_read_b128 v[220:223], v157 offset:56320
	global_load_lds_dwordx4 v[146:147], off
	s_add_i32 m0, s28, 0x2000
	s_add_u32 s26, s26, 0x100080
	v_lshl_add_u64 v[146:147], v[224:225], 0, s[12:13]
	s_addc_u32 s27, s27, 0
	s_add_i32 s28, s57, s30
	global_load_lds_dwordx4 v[146:147], off
	v_lshl_add_u64 v[146:147], s[26:27], 0, v[134:135]
	s_mov_b32 m0, s28
	s_nop 0
	global_load_lds_dwordx4 v[146:147], off
	v_lshl_add_u64 v[146:147], s[26:27], 0, v[130:131]
	s_add_i32 m0, s28, 0x2000
	s_nop 0
	global_load_lds_dwordx4 v[146:147], off
	v_lshl_add_u64 v[146:147], v[226:227], 0, s[12:13]
	s_mov_b32 m0, s39
	s_nop 0
	global_load_lds_dwordx4 v[146:147], off
	v_lshl_add_u64 v[146:147], v[228:229], 0, s[12:13]
	s_mov_b32 m0, s40
	s_nop 0
	global_load_lds_dwordx4 v[146:147], off
	s_waitcnt vmcnt(8)
	s_waitcnt lgkmcnt(0)
	s_setprio 3
	s_barrier
	v_mfma_f32_16x16x32_bf16 v[62:65], v[158:161], v[192:195], v[62:65]
	v_mfma_f32_16x16x32_bf16 v[62:65], v[164:167], v[196:199], v[62:65]
	v_mfma_f32_16x16x32_bf16 v[58:61], v[168:171], v[192:195], v[58:61]
	v_mfma_f32_16x16x32_bf16 v[58:61], v[172:175], v[196:199], v[58:61]
	v_mfma_f32_16x16x32_bf16 v[42:45], v[168:171], v[200:203], v[42:45]
	v_mfma_f32_16x16x32_bf16 v[42:45], v[172:175], v[204:207], v[42:45]
	v_mfma_f32_16x16x32_bf16 v[50:53], v[158:161], v[200:203], v[50:53]
	v_mfma_f32_16x16x32_bf16 v[50:53], v[164:167], v[204:207], v[50:53]
	v_mfma_f32_16x16x32_bf16 v[34:37], v[158:161], v[208:211], v[34:37]
	v_mfma_f32_16x16x32_bf16 v[34:37], v[164:167], v[212:215], v[34:37]
	v_mfma_f32_16x16x32_bf16 v[26:29], v[168:171], v[208:211], v[26:29]
	v_mfma_f32_16x16x32_bf16 v[26:29], v[172:175], v[212:215], v[26:29]
	v_mfma_f32_16x16x32_bf16 v[10:13], v[168:171], v[216:219], v[10:13]
	v_mfma_f32_16x16x32_bf16 v[10:13], v[172:175], v[220:223], v[10:13]
	v_mfma_f32_16x16x32_bf16 v[14:17], v[158:161], v[216:219], v[14:17]
	v_mfma_f32_16x16x32_bf16 v[14:17], v[164:167], v[220:223], v[14:17]
	v_mfma_f32_16x16x32_bf16 v[54:57], v[176:179], v[192:195], v[54:57]
	v_mfma_f32_16x16x32_bf16 v[54:57], v[180:183], v[196:199], v[54:57]
	v_mfma_f32_16x16x32_bf16 v[46:49], v[184:187], v[192:195], v[46:49]
	v_mfma_f32_16x16x32_bf16 v[46:49], v[188:191], v[196:199], v[46:49]
	v_mfma_f32_16x16x32_bf16 v[30:33], v[184:187], v[200:203], v[30:33]
	v_mfma_f32_16x16x32_bf16 v[30:33], v[188:191], v[204:207], v[30:33]
	v_mfma_f32_16x16x32_bf16 v[38:41], v[176:179], v[200:203], v[38:41]
	v_mfma_f32_16x16x32_bf16 v[38:41], v[180:183], v[204:207], v[38:41]
	v_mfma_f32_16x16x32_bf16 v[22:25], v[176:179], v[208:211], v[22:25]
	v_mfma_f32_16x16x32_bf16 v[22:25], v[180:183], v[212:215], v[22:25]
	v_mfma_f32_16x16x32_bf16 v[18:21], v[184:187], v[208:211], v[18:21]
	v_mfma_f32_16x16x32_bf16 v[18:21], v[188:191], v[212:215], v[18:21]
	v_mfma_f32_16x16x32_bf16 v[2:5], v[184:187], v[216:219], v[2:5]
	v_mfma_f32_16x16x32_bf16 v[2:5], v[188:191], v[220:223], v[2:5]
	v_mfma_f32_16x16x32_bf16 v[6:9], v[176:179], v[216:219], v[6:9]
	v_mfma_f32_16x16x32_bf16 v[6:9], v[180:183], v[220:223], v[6:9]
	s_setprio 0
	s_barrier
	s_add_i32 s55, s55, 2
	s_add_u32 s24, s24, 0x100
	s_addc_u32 s25, s25, 0
	s_add_u32 s53, s53, 0x100
	s_addc_u32 s54, s54, 0
	s_cmp_gt_u32 s55, 61
	s_cbranch_scc0 .LBB0_908
	s_and_b64 vcc, exec, s[0:1]
	s_cbranch_vccz .LBB0_911
	s_barrier

; #define PG8_STAGE(bufoff, gbase, voff) do { _Pragma("unroll") for (int _i = 0; _i < 2; ++_i) \
;         __builtin_amdgcn_global_load_lds((const unsigned*)((const char*)(gbase) + (voff)[_i]), (PG8_LAS unsigned*)(lds + (bufoff) + ldsw + _i * 8192), 16, 0, 0); } while (0)
; #define PG8_LDA(dst, b, h) do { _Pragma("unroll") for (int m = 0; m < 4; ++m) _Pragma("unroll") for (int k = 0; k < 2; ++k) dst[m][k] = *(const PG8_LAS bf16x8*)(lds + PG8_SA(b, h) + aoff + m * 2048 + k * 1024); } while (0)
; #define PG8_LDB(dst, b, h) do { _Pragma("unroll") for (int n = 0; n < 2; ++n) _Pragma("unroll") for (int k = 0; k < 2; ++k) dst[n][k] = *(const PG8_LAS bf16x8*)(lds + PG8_SB(b, h) + boff + n * 2048 + k * 1024); } while (0)
; #define PG8_MMA(ai, bj, At, Bt) do { __builtin_amdgcn_s_setprio(3); _Pragma("unroll") for (int m = 0; m < 4; ++m) _Pragma("unroll") for (int n = 0; n < 2; ++n) _Pragma("unroll") for (int k = 0; k < 2; ++k) \
;         acc[ai][bj][m][n] = __builtin_amdgcn_mfma_f32_16x16x32_bf16(Bt[n][k], At[m][k], acc[ai][bj][m][n], 0, 0, 0); __builtin_amdgcn_s_setprio(0); } while (0)
; #define PG8_WAIT_V(n) asm volatile("s_waitcnt vmcnt(" #n ")" ::: "memory")
; #define PG8_WAIT_L(n) asm volatile("s_waitcnt lgkmcnt(" #n ")" ::: "memory")
; #define PG8_BAR __builtin_amdgcn_s_barrier()
; #define PG8_SCHED __builtin_amdgcn_sched_barrier(0)
; template <class Epi, class Sched, bool ALIGN_EPI = false, bool SP2 = false>
; __device__ __forceinline__ void gemm_phase(PG8_LAS unsigned char* lds, const Gemm g, const Sched& S, const Epi& E) {
;     ...
;             PG8_LDB(B0, 0, 0); PG8_LDB(B1, 0, 1); PG8_SCHED; PG8_LDA(At, 0, 0); PG8_STAGE(PG8_SA(1, 1), a1 + hstepA, voffA);
;             PG8_WAIT_V(8); PG8_WAIT_L(0); PG8_BAR; PG8_MMA(0, 0, At, B0); PG8_MMA(0, 1, At, B1); PG8_BAR; PG8_SCHED;
;             PG8_LDA(At, 0, 1); PG8_STAGE(PG8_SB(0, 0), b2, voffB); PG8_STAGE(PG8_SB(0, 1), b2 + hstepB, voffB); PG8_STAGE(PG8_SA(0, 0), a2, voffA);
;             PG8_WAIT_V(8); PG8_WAIT_L(0); PG8_BAR; PG8_MMA(1, 0, At, B0); PG8_MMA(1, 1, At, B1); PG8_BAR; PG8_SCHED;
.LBB0_975:
	v_add_u32_e32 v144, s46, v206
	v_add_u32_e32 v160, s47, v206
	s_add_u32 s28, s2, s12
	ds_read_b128 v[132:135], v144
	ds_read_b128 v[136:139], v144 offset:1024
	ds_read_b128 v[140:143], v144 offset:2048
	ds_read_b128 v[144:147], v144 offset:3072
	ds_read_b128 v[148:151], v160
	ds_read_b128 v[152:155], v160 offset:1024
	ds_read_b128 v[156:159], v160 offset:2048
	ds_read_b128 v[160:163], v160 offset:3072
	s_addc_u32 s29, s3, s13
	s_add_u32 s28, s28, 0x21500100
	s_addc_u32 s29, s29, 0
	s_add_u32 s81, s44, s12
	s_addc_u32 s82, s45, s13
	s_cmpk_eq_i32 s12, 0x5500
	s_cselect_b32 s31, s1, s29
	s_cselect_b32 s30, s0, s28
	s_cselect_b32 s29, s11, s82
	s_cselect_b32 s28, s10, s81
	s_mov_b32 m0, s71
	v_lshl_add_u64 v[234:235], v[2:3], 0, s[12:13]
	ds_read_b128 v[164:167], v207
	ds_read_b128 v[168:171], v207 offset:1024
	ds_read_b128 v[210:213], v207 offset:2048
	ds_read_b128 v[214:217], v207 offset:3072
	ds_read_b128 v[218:221], v207 offset:4096
	ds_read_b128 v[222:225], v207 offset:5120
	ds_read_b128 v[226:229], v207 offset:6144
	ds_read_b128 v[230:233], v207 offset:7168
	global_load_lds_dwordx4 v[234:235], off
	v_lshl_add_u64 v[234:235], v[200:201], 0, s[12:13]
	s_mov_b32 m0, s72
	s_nop 0
	global_load_lds_dwordx4 v[234:235], off
	s_waitcnt vmcnt(8)
	s_waitcnt lgkmcnt(0)
	s_setprio 3
	s_barrier
	v_mfma_f32_16x16x32_bf16 v[128:131], v[132:135], v[164:167], v[128:131]
	v_mfma_f32_16x16x32_bf16 v[128:131], v[136:139], v[168:171], v[128:131]
	v_mfma_f32_16x16x32_bf16 v[124:127], v[140:143], v[164:167], v[124:127]
	v_mfma_f32_16x16x32_bf16 v[124:127], v[144:147], v[168:171], v[124:127]
	v_mfma_f32_16x16x32_bf16 v[96:99], v[140:143], v[210:213], v[96:99]
	v_mfma_f32_16x16x32_bf16 v[96:99], v[144:147], v[214:217], v[96:99]
	v_mfma_f32_16x16x32_bf16 v[100:103], v[132:135], v[210:213], v[100:103]
	v_mfma_f32_16x16x32_bf16 v[100:103], v[136:139], v[214:217], v[100:103]
	v_mfma_f32_16x16x32_bf16 v[112:115], v[132:135], v[218:221], v[112:115]
	v_mfma_f32_16x16x32_bf16 v[112:115], v[136:139], v[222:225], v[112:115]
	v_mfma_f32_16x16x32_bf16 v[108:111], v[140:143], v[218:221], v[108:111]
	v_mfma_f32_16x16x32_bf16 v[108:111], v[144:147], v[222:225], v[108:111]
	v_mfma_f32_16x16x32_bf16 v[76:79], v[140:143], v[226:229], v[76:79]
	v_mfma_f32_16x16x32_bf16 v[76:79], v[144:147], v[230:233], v[76:79]
	v_mfma_f32_16x16x32_bf16 v[80:83], v[132:135], v[226:229], v[80:83]
	v_mfma_f32_16x16x32_bf16 v[80:83], v[136:139], v[230:233], v[80:83]
	v_mfma_f32_16x16x32_bf16 v[120:123], v[148:151], v[164:167], v[120:123]
	v_mfma_f32_16x16x32_bf16 v[120:123], v[152:155], v[168:171], v[120:123]
	v_mfma_f32_16x16x32_bf16 v[116:119], v[156:159], v[164:167], v[116:119]
	v_mfma_f32_16x16x32_bf16 v[116:119], v[160:163], v[168:171], v[116:119]
	v_mfma_f32_16x16x32_bf16 v[88:91], v[156:159], v[210:213], v[88:91]
	v_mfma_f32_16x16x32_bf16 v[88:91], v[160:163], v[214:217], v[88:91]
	v_mfma_f32_16x16x32_bf16 v[92:95], v[148:151], v[210:213], v[92:95]
	v_mfma_f32_16x16x32_bf16 v[92:95], v[152:155], v[214:217], v[92:95]
	v_mfma_f32_16x16x32_bf16 v[104:107], v[148:151], v[218:221], v[104:107]
	v_mfma_f32_16x16x32_bf16 v[104:107], v[152:155], v[222:225], v[104:107]
	v_mfma_f32_16x16x32_bf16 v[84:87], v[156:159], v[218:221], v[84:87]
	v_mfma_f32_16x16x32_bf16 v[84:87], v[160:163], v[222:225], v[84:87]
	v_mfma_f32_16x16x32_bf16 v[68:71], v[156:159], v[226:229], v[68:71]
	v_mfma_f32_16x16x32_bf16 v[68:71], v[160:163], v[230:233], v[68:71]
	v_mfma_f32_16x16x32_bf16 v[72:75], v[148:151], v[226:229], v[72:75]
	v_mfma_f32_16x16x32_bf16 v[72:75], v[152:155], v[230:233], v[72:75]
	s_setprio 0
	s_barrier
	s_mov_b32 m0, s73
	v_lshl_add_u64 v[234:235], s[28:29], 0, v[174:175]
	s_add_u32 s82, s28, 0x2b0000
	ds_read_b128 v[164:167], v207 offset:16384
	ds_read_b128 v[168:171], v207 offset:17408
	ds_read_b128 v[210:213], v207 offset:18432
	ds_read_b128 v[214:217], v207 offset:19456
	ds_read_b128 v[218:221], v207 offset:20480
	ds_read_b128 v[222:225], v207 offset:21504
	ds_read_b128 v[226:229], v207 offset:22528
	ds_read_b128 v[230:233], v207 offset:23552
	global_load_lds_dwordx4 v[234:235], off
	v_lshl_add_u64 v[236:237], s[28:29], 0, v[178:179]
	s_mov_b32 m0, s74
	s_addc_u32 s83, s29, 0
	global_load_lds_dwordx4 v[236:237], off
	v_lshl_add_u64 v[238:239], s[82:83], 0, v[174:175]
	s_mov_b32 m0, s75
	v_lshl_add_u64 v[240:241], s[30:31], 0, v[176:177]
	global_load_lds_dwordx4 v[238:239], off
	v_lshl_add_u64 v[238:239], s[82:83], 0, v[178:179]
	s_mov_b32 m0, s76
	s_nop 0
	global_load_lds_dwordx4 v[238:239], off
	v_lshl_add_u64 v[238:239], s[30:31], 0, v[172:173]
	s_mov_b32 m0, s42
	s_nop 0
	global_load_lds_dwordx4 v[238:239], off
	s_mov_b32 m0, s54
	s_nop 0
	global_load_lds_dwordx4 v[240:241], off
	s_waitcnt vmcnt(8)
	s_waitcnt lgkmcnt(0)
	s_setprio 3
	s_barrier
; #define PG8_STAGE(bufoff, gbase, voff) do { _Pragma("unroll") for (int _i = 0; _i < 2; ++_i) \
;         __builtin_amdgcn_global_load_lds((const unsigned*)((const char*)(gbase) + (voff)[_i]), (PG8_LAS unsigned*)(lds + (bufoff) + ldsw + _i * 8192), 16, 0, 0); } while (0)
; #define PG8_LDA(dst, b, h) do { _Pragma("unroll") for (int m = 0; m < 4; ++m) _Pragma("unroll") for (int k = 0; k < 2; ++k) dst[m][k] = *(const PG8_LAS bf16x8*)(lds + PG8_SA(b, h) + aoff + m * 2048 + k * 1024); } while (0)
; #define PG8_LDB(dst, b, h) do { _Pragma("unroll") for (int n = 0; n < 2; ++n) _Pragma("unroll") for (int k = 0; k < 2; ++k) dst[n][k] = *(const PG8_LAS bf16x8*)(lds + PG8_SB(b, h) + boff + n * 2048 + k * 1024); } while (0)
; #define PG8_MMA(ai, bj, At, Bt) do { __builtin_amdgcn_s_setprio(3); _Pragma("unroll") for (int m = 0; m < 4; ++m) _Pragma("unroll") for (int n = 0; n < 2; ++n) _Pragma("unroll") for (int k = 0; k < 2; ++k) \
;         acc[ai][bj][m][n] = __builtin_amdgcn_mfma_f32_16x16x32_bf16(Bt[n][k], At[m][k], acc[ai][bj][m][n], 0, 0, 0); __builtin_amdgcn_s_setprio(0); } while (0)
; #define PG8_WAIT_V(n) asm volatile("s_waitcnt vmcnt(" #n ")" ::: "memory")
; #define PG8_WAIT_L(n) asm volatile("s_waitcnt lgkmcnt(" #n ")" ::: "memory")
; #define PG8_BAR __builtin_amdgcn_s_barrier()
; #define PG8_SCHED __builtin_amdgcn_sched_barrier(0)
; template <class Epi, class Sched, bool ALIGN_EPI = false, bool SP2 = false>
; __device__ __forceinline__ void gemm_phase(PG8_LAS unsigned char* lds, const Gemm g, const Sched& S, const Epi& E) {
;     ...
;             PG8_WAIT_V(8); PG8_WAIT_L(0); PG8_BAR; PG8_MMA(1, 0, At, B0); PG8_MMA(1, 1, At, B1); PG8_BAR; PG8_SCHED;
;             PG8_LDB(B0, 1, 0); PG8_LDB(B1, 1, 1); PG8_SCHED; PG8_LDA(At, 1, 0); PG8_STAGE(PG8_SA(0, 1), a2 + hstepA, voffA);
;             PG8_WAIT_V(8); PG8_WAIT_L(0); PG8_BAR; PG8_MMA(0, 0, At, B0); PG8_MMA(0, 1, At, B1); PG8_BAR; PG8_SCHED;
	v_mfma_f32_16x16x32_bf16 v[64:67], v[132:135], v[164:167], v[64:67]
	v_mfma_f32_16x16x32_bf16 v[64:67], v[136:139], v[168:171], v[64:67]
	v_mfma_f32_16x16x32_bf16 v[60:63], v[140:143], v[164:167], v[60:63]
	v_mfma_f32_16x16x32_bf16 v[60:63], v[144:147], v[168:171], v[60:63]
	v_mfma_f32_16x16x32_bf16 v[44:47], v[140:143], v[210:213], v[44:47]
	v_mfma_f32_16x16x32_bf16 v[44:47], v[144:147], v[214:217], v[44:47]
	v_mfma_f32_16x16x32_bf16 v[48:51], v[132:135], v[210:213], v[48:51]
	v_mfma_f32_16x16x32_bf16 v[48:51], v[136:139], v[214:217], v[48:51]
	v_mfma_f32_16x16x32_bf16 v[32:35], v[132:135], v[218:221], v[32:35]
	v_mfma_f32_16x16x32_bf16 v[32:35], v[136:139], v[222:225], v[32:35]
	v_mfma_f32_16x16x32_bf16 v[28:31], v[140:143], v[218:221], v[28:31]
	v_mfma_f32_16x16x32_bf16 v[28:31], v[144:147], v[222:225], v[28:31]
	v_mfma_f32_16x16x32_bf16 v[12:15], v[140:143], v[226:229], v[12:15]
	v_mfma_f32_16x16x32_bf16 v[12:15], v[144:147], v[230:233], v[12:15]
	v_mfma_f32_16x16x32_bf16 v[16:19], v[132:135], v[226:229], v[16:19]
	v_mfma_f32_16x16x32_bf16 v[16:19], v[136:139], v[230:233], v[16:19]
	v_mfma_f32_16x16x32_bf16 v[56:59], v[148:151], v[164:167], v[56:59]
	v_mfma_f32_16x16x32_bf16 v[56:59], v[152:155], v[168:171], v[56:59]
	v_mfma_f32_16x16x32_bf16 v[52:55], v[156:159], v[164:167], v[52:55]
	v_mfma_f32_16x16x32_bf16 v[52:55], v[160:163], v[168:171], v[52:55]
	v_mfma_f32_16x16x32_bf16 v[36:39], v[156:159], v[210:213], v[36:39]
	v_mfma_f32_16x16x32_bf16 v[36:39], v[160:163], v[214:217], v[36:39]
	v_mfma_f32_16x16x32_bf16 v[40:43], v[148:151], v[210:213], v[40:43]
	v_mfma_f32_16x16x32_bf16 v[40:43], v[152:155], v[214:217], v[40:43]
	v_mfma_f32_16x16x32_bf16 v[24:27], v[148:151], v[218:221], v[24:27]
	v_mfma_f32_16x16x32_bf16 v[24:27], v[152:155], v[222:225], v[24:27]
	v_mfma_f32_16x16x32_bf16 v[20:23], v[156:159], v[218:221], v[20:23]
	v_mfma_f32_16x16x32_bf16 v[20:23], v[160:163], v[222:225], v[20:23]
	v_mfma_f32_16x16x32_bf16 v[4:7], v[156:159], v[226:229], v[4:7]
	v_mfma_f32_16x16x32_bf16 v[4:7], v[160:163], v[230:233], v[4:7]
	v_mfma_f32_16x16x32_bf16 v[8:11], v[148:151], v[226:229], v[8:11]
	v_mfma_f32_16x16x32_bf16 v[8:11], v[152:155], v[230:233], v[8:11]
	s_setprio 0
	s_barrier
	v_add_u32_e32 v144, s52, v206
	v_add_u32_e32 v160, s53, v206
	ds_read_b128 v[132:135], v144
	ds_read_b128 v[136:139], v144 offset:1024
	ds_read_b128 v[140:143], v144 offset:2048
	ds_read_b128 v[144:147], v144 offset:3072
	ds_read_b128 v[148:151], v160
	ds_read_b128 v[152:155], v160 offset:1024
	ds_read_b128 v[156:159], v160 offset:2048
	ds_read_b128 v[160:163], v160 offset:3072
	s_add_u32 s30, s30, 0x2b0000
	s_addc_u32 s31, s31, 0
	s_mov_b32 m0, s55
	v_lshl_add_u64 v[242:243], s[30:31], 0, v[172:173]
	ds_read_b128 v[164:167], v207 offset:32768
	ds_read_b128 v[168:171], v207 offset:33792
	ds_read_b128 v[210:213], v207 offset:34816
	ds_read_b128 v[214:217], v207 offset:35840
	ds_read_b128 v[218:221], v207 offset:36864
	ds_read_b128 v[222:225], v207 offset:37888
	ds_read_b128 v[226:229], v207 offset:38912
	ds_read_b128 v[230:233], v207 offset:39936
	global_load_lds_dwordx4 v[242:243], off
	v_lshl_add_u64 v[242:243], s[30:31], 0, v[176:177]
	s_mov_b32 m0, s56
	s_nop 0
	global_load_lds_dwordx4 v[242:243], off
	s_waitcnt vmcnt(8)
	s_waitcnt lgkmcnt(0)
	s_setprio 3
	s_barrier
	v_mfma_f32_16x16x32_bf16 v[128:131], v[132:135], v[164:167], v[128:131]
	v_mfma_f32_16x16x32_bf16 v[128:131], v[136:139], v[168:171], v[128:131]
	v_mfma_f32_16x16x32_bf16 v[124:127], v[140:143], v[164:167], v[124:127]
	v_mfma_f32_16x16x32_bf16 v[124:127], v[144:147], v[168:171], v[124:127]
	v_mfma_f32_16x16x32_bf16 v[96:99], v[140:143], v[210:213], v[96:99]
	v_mfma_f32_16x16x32_bf16 v[96:99], v[144:147], v[214:217], v[96:99]
	v_mfma_f32_16x16x32_bf16 v[100:103], v[132:135], v[210:213], v[100:103]
	v_mfma_f32_16x16x32_bf16 v[100:103], v[136:139], v[214:217], v[100:103]
	v_mfma_f32_16x16x32_bf16 v[112:115], v[132:135], v[218:221], v[112:115]
	v_mfma_f32_16x16x32_bf16 v[112:115], v[136:139], v[222:225], v[112:115]
	v_mfma_f32_16x16x32_bf16 v[108:111], v[140:143], v[218:221], v[108:111]
	v_mfma_f32_16x16x32_bf16 v[108:111], v[144:147], v[222:225], v[108:111]
	v_mfma_f32_16x16x32_bf16 v[76:79], v[140:143], v[226:229], v[76:79]
	v_mfma_f32_16x16x32_bf16 v[76:79], v[144:147], v[230:233], v[76:79]
	v_mfma_f32_16x16x32_bf16 v[80:83], v[132:135], v[226:229], v[80:83]
	v_mfma_f32_16x16x32_bf16 v[80:83], v[136:139], v[230:233], v[80:83]
	v_mfma_f32_16x16x32_bf16 v[120:123], v[148:151], v[164:167], v[120:123]
	v_mfma_f32_16x16x32_bf16 v[120:123], v[152:155], v[168:171], v[120:123]
	v_mfma_f32_16x16x32_bf16 v[116:119], v[156:159], v[164:167], v[116:119]
	v_mfma_f32_16x16x32_bf16 v[116:119], v[160:163], v[168:171], v[116:119]
	v_mfma_f32_16x16x32_bf16 v[88:91], v[156:159], v[210:213], v[88:91]
	v_mfma_f32_16x16x32_bf16 v[88:91], v[160:163], v[214:217], v[88:91]
	v_mfma_f32_16x16x32_bf16 v[92:95], v[148:151], v[210:213], v[92:95]
	v_mfma_f32_16x16x32_bf16 v[92:95], v[152:155], v[214:217], v[92:95]
	v_mfma_f32_16x16x32_bf16 v[104:107], v[148:151], v[218:221], v[104:107]
	v_mfma_f32_16x16x32_bf16 v[104:107], v[152:155], v[222:225], v[104:107]
	v_mfma_f32_16x16x32_bf16 v[84:87], v[156:159], v[218:221], v[84:87]
	v_mfma_f32_16x16x32_bf16 v[84:87], v[160:163], v[222:225], v[84:87]
	v_mfma_f32_16x16x32_bf16 v[68:71], v[156:159], v[226:229], v[68:71]
	v_mfma_f32_16x16x32_bf16 v[68:71], v[160:163], v[230:233], v[68:71]
	v_mfma_f32_16x16x32_bf16 v[72:75], v[148:151], v[226:229], v[72:75]
	v_mfma_f32_16x16x32_bf16 v[72:75], v[152:155], v[230:233], v[72:75]
	s_setprio 0
	s_barrier
; #define PG8_STAGE(bufoff, gbase, voff) do { _Pragma("unroll") for (int _i = 0; _i < 2; ++_i) \
;         __builtin_amdgcn_global_load_lds((const unsigned*)((const char*)(gbase) + (voff)[_i]), (PG8_LAS unsigned*)(lds + (bufoff) + ldsw + _i * 8192), 16, 0, 0); } while (0)
; #define PG8_LDA(dst, b, h) do { _Pragma("unroll") for (int m = 0; m < 4; ++m) _Pragma("unroll") for (int k = 0; k < 2; ++k) dst[m][k] = *(const PG8_LAS bf16x8*)(lds + PG8_SA(b, h) + aoff + m * 2048 + k * 1024); } while (0)
; #define PG8_MMA(ai, bj, At, Bt) do { __builtin_amdgcn_s_setprio(3); _Pragma("unroll") for (int m = 0; m < 4; ++m) _Pragma("unroll") for (int n = 0; n < 2; ++n) _Pragma("unroll") for (int k = 0; k < 2; ++k) \
;         acc[ai][bj][m][n] = __builtin_amdgcn_mfma_f32_16x16x32_bf16(Bt[n][k], At[m][k], acc[ai][bj][m][n], 0, 0, 0); __builtin_amdgcn_s_setprio(0); } while (0)
; #define PG8_WAIT_V(n) asm volatile("s_waitcnt vmcnt(" #n ")" ::: "memory")
; #define PG8_WAIT_L(n) asm volatile("s_waitcnt lgkmcnt(" #n ")" ::: "memory")
; #define PG8_BAR __builtin_amdgcn_s_barrier()
; #define PG8_SCHED __builtin_amdgcn_sched_barrier(0)
; template <class Epi, class Sched, bool ALIGN_EPI = false, bool SP2 = false>
; __device__ __forceinline__ void gemm_phase(PG8_LAS unsigned char* lds, const Gemm g, const Sched& S, const Epi& E) {
;     ...
;         for (int t = 0; t < nt; t += 2) {
;     ...
;             PG8_LDA(At, 1, 1); PG8_STAGE(PG8_SB(1, 0), b3, voffB); PG8_STAGE(PG8_SB(1, 1), b3 + hstepB, voffB); PG8_STAGE(PG8_SA(1, 0), a3, voffA);
;             PG8_WAIT_V(8); PG8_WAIT_L(0); PG8_BAR; PG8_MMA(1, 0, At, B0); PG8_MMA(1, 1, At, B1); PG8_BAR; PG8_SCHED;
	s_mov_b32 m0, s77
	v_lshl_add_u64 v[234:235], v[234:235], 0, s[4:5]
	s_add_u32 s28, s28, 0x2b0080
	ds_read_b128 v[164:167], v207 offset:49152
	ds_read_b128 v[168:171], v207 offset:50176
	ds_read_b128 v[210:213], v207 offset:51200
	ds_read_b128 v[214:217], v207 offset:52224
	ds_read_b128 v[218:221], v207 offset:53248
	ds_read_b128 v[222:225], v207 offset:54272
	ds_read_b128 v[226:229], v207 offset:55296
	ds_read_b128 v[230:233], v207 offset:56320
	global_load_lds_dwordx4 v[234:235], off
	v_lshl_add_u64 v[234:235], v[236:237], 0, s[4:5]
	s_mov_b32 m0, s78
	s_addc_u32 s29, s29, 0
	global_load_lds_dwordx4 v[234:235], off
	v_lshl_add_u64 v[234:235], s[28:29], 0, v[174:175]
	s_mov_b32 m0, s79
	s_nop 0
	global_load_lds_dwordx4 v[234:235], off
	v_lshl_add_u64 v[234:235], s[28:29], 0, v[178:179]
	s_mov_b32 m0, s80
	s_nop 0
	global_load_lds_dwordx4 v[234:235], off
	v_lshl_add_u64 v[234:235], v[238:239], 0, s[4:5]
	s_mov_b32 m0, s57
	s_nop 0
	global_load_lds_dwordx4 v[234:235], off
	v_lshl_add_u64 v[234:235], v[240:241], 0, s[4:5]
	s_mov_b32 m0, s58
	s_nop 0
	global_load_lds_dwordx4 v[234:235], off
	s_waitcnt vmcnt(8)
	s_waitcnt lgkmcnt(0)
	s_setprio 3
	s_barrier
	v_mfma_f32_16x16x32_bf16 v[64:67], v[132:135], v[164:167], v[64:67]
	v_mfma_f32_16x16x32_bf16 v[64:67], v[136:139], v[168:171], v[64:67]
	v_mfma_f32_16x16x32_bf16 v[60:63], v[140:143], v[164:167], v[60:63]
	v_mfma_f32_16x16x32_bf16 v[60:63], v[144:147], v[168:171], v[60:63]
	v_mfma_f32_16x16x32_bf16 v[44:47], v[140:143], v[210:213], v[44:47]
	v_mfma_f32_16x16x32_bf16 v[44:47], v[144:147], v[214:217], v[44:47]
	v_mfma_f32_16x16x32_bf16 v[48:51], v[132:135], v[210:213], v[48:51]
	v_mfma_f32_16x16x32_bf16 v[48:51], v[136:139], v[214:217], v[48:51]
	v_mfma_f32_16x16x32_bf16 v[32:35], v[132:135], v[218:221], v[32:35]
	v_mfma_f32_16x16x32_bf16 v[32:35], v[136:139], v[222:225], v[32:35]
	v_mfma_f32_16x16x32_bf16 v[28:31], v[140:143], v[218:221], v[28:31]
	v_mfma_f32_16x16x32_bf16 v[28:31], v[144:147], v[222:225], v[28:31]
	v_mfma_f32_16x16x32_bf16 v[12:15], v[140:143], v[226:229], v[12:15]
	v_mfma_f32_16x16x32_bf16 v[12:15], v[144:147], v[230:233], v[12:15]
	v_mfma_f32_16x16x32_bf16 v[16:19], v[132:135], v[226:229], v[16:19]
	v_mfma_f32_16x16x32_bf16 v[16:19], v[136:139], v[230:233], v[16:19]
	v_mfma_f32_16x16x32_bf16 v[56:59], v[148:151], v[164:167], v[56:59]
	v_mfma_f32_16x16x32_bf16 v[56:59], v[152:155], v[168:171], v[56:59]
	v_mfma_f32_16x16x32_bf16 v[52:55], v[156:159], v[164:167], v[52:55]
	v_mfma_f32_16x16x32_bf16 v[52:55], v[160:163], v[168:171], v[52:55]
	v_mfma_f32_16x16x32_bf16 v[36:39], v[156:159], v[210:213], v[36:39]
	v_mfma_f32_16x16x32_bf16 v[36:39], v[160:163], v[214:217], v[36:39]
	v_mfma_f32_16x16x32_bf16 v[40:43], v[148:151], v[210:213], v[40:43]
	v_mfma_f32_16x16x32_bf16 v[40:43], v[152:155], v[214:217], v[40:43]
	v_mfma_f32_16x16x32_bf16 v[24:27], v[148:151], v[218:221], v[24:27]
	v_mfma_f32_16x16x32_bf16 v[24:27], v[152:155], v[222:225], v[24:27]
	v_mfma_f32_16x16x32_bf16 v[20:23], v[156:159], v[218:221], v[20:23]
	v_mfma_f32_16x16x32_bf16 v[20:23], v[160:163], v[222:225], v[20:23]
	v_mfma_f32_16x16x32_bf16 v[4:7], v[156:159], v[226:229], v[4:7]
	v_mfma_f32_16x16x32_bf16 v[4:7], v[160:163], v[230:233], v[4:7]
	v_mfma_f32_16x16x32_bf16 v[8:11], v[148:151], v[226:229], v[8:11]
	v_mfma_f32_16x16x32_bf16 v[8:11], v[152:155], v[230:233], v[8:11]
	s_setprio 0
	s_barrier
	s_add_i32 s61, s61, 2
	s_add_u32 s12, s12, 0x100
	s_addc_u32 s13, s13, 0
	s_cmpk_gt_u32 s61, 0xa9
	s_cbranch_scc1 .LBB0_978

; #define PG8_STAGE(bufoff, gbase, voff) do { _Pragma("unroll") for (int _i = 0; _i < 2; ++_i) \
;         __builtin_amdgcn_global_load_lds((const unsigned*)((const char*)(gbase) + (voff)[_i]), (PG8_LAS unsigned*)(lds + (bufoff) + ldsw + _i * 8192), 16, 0, 0); } while (0)
; #define PG8_LDA(dst, b, h) do { _Pragma("unroll") for (int m = 0; m < 4; ++m) _Pragma("unroll") for (int k = 0; k < 2; ++k) dst[m][k] = *(const PG8_LAS bf16x8*)(lds + PG8_SA(b, h) + aoff + m * 2048 + k * 1024); } while (0)
; #define PG8_LDB(dst, b, h) do { _Pragma("unroll") for (int n = 0; n < 2; ++n) _Pragma("unroll") for (int k = 0; k < 2; ++k) dst[n][k] = *(const PG8_LAS bf16x8*)(lds + PG8_SB(b, h) + boff + n * 2048 + k * 1024); } while (0)
; #define PG8_MMA(ai, bj, At, Bt) do { __builtin_amdgcn_s_setprio(3); _Pragma("unroll") for (int m = 0; m < 4; ++m) _Pragma("unroll") for (int n = 0; n < 2; ++n) _Pragma("unroll") for (int k = 0; k < 2; ++k) \
;         acc[ai][bj][m][n] = __builtin_amdgcn_mfma_f32_16x16x32_bf16(Bt[n][k], At[m][k], acc[ai][bj][m][n], 0, 0, 0); __builtin_amdgcn_s_setprio(0); } while (0)
; #define PG8_WAIT_V(n) asm volatile("s_waitcnt vmcnt(" #n ")" ::: "memory")
; #define PG8_BAR __builtin_amdgcn_s_barrier()
; template <class Epi, class Sched, bool ALIGN_EPI = false, bool SP2 = false>
; __device__ __forceinline__ void gemm_phase(PG8_LAS unsigned char* lds, const Gemm g, const Sched& S, const Epi& E) {
;     ...
;             const char* a1 = cA + (size_t)(t + 1) * kstep;
;             const char* a2 = last ? nA : cA + (size_t)(t + 2) * kstep; const char* b2 = last ? nB : cB + (size_t)(t + 2) * kstep;
;             const char* a3 = a2 + kstep; const char* b3 = b2 + kstep;
;             if (last && has_next) S.a_ready(nxt);
;             if constexpr (Epi::MIDK) { if (t == E.midk_step(nt)) E.midk(acc, cur, wr, wc, fr, fq); }
;             if constexpr (SP2) {
;             PG8_LDB(B0, 0, 0); PG8_LDB(B1, 0, 1); PG8_SCHED; PG8_LDA(At, 0, 0); PG8_STAGE(PG8_SA(1, 1), a1 + hstepA, voffA);
;             PG8_WAIT_V(8); PG8_WAIT_L(0); PG8_BAR; PG8_MMA(0, 0, At, B0); PG8_MMA(0, 1, At, B1); PG8_BAR; PG8_SCHED;
;             PG8_LDA(At, 0, 1); PG8_STAGE(PG8_SB(0, 0), b2, voffB); PG8_STAGE(PG8_SB(0, 1), b2 + hstepB, voffB); PG8_STAGE(PG8_SA(0, 0), a2, voffA);
;             PG8_WAIT_V(8); PG8_WAIT_L(0); PG8_BAR; PG8_MMA(1, 0, At, B0); PG8_MMA(1, 1, At, B1); PG8_BAR; PG8_SCHED;
.LBB0_1018:
	v_add_u32_e32 v142, s46, v189
	v_add_u32_e32 v158, s47, v189
	s_add_u32 s40, s20, s22
	ds_read_b128 v[130:133], v142
	ds_read_b128 v[134:137], v142 offset:1024
	ds_read_b128 v[138:141], v142 offset:2048
	ds_read_b128 v[142:145], v142 offset:3072
	ds_read_b128 v[146:149], v158
	ds_read_b128 v[150:153], v158 offset:1024
	ds_read_b128 v[154:157], v158 offset:2048
	ds_read_b128 v[158:161], v158 offset:3072
	s_addc_u32 s41, s21, s23
	s_add_u32 s40, s40, 0x21500100
	s_addc_u32 s41, s41, 0
	s_add_u32 s87, s44, s22
	s_addc_u32 s88, s45, s23
	s_cmpk_eq_i32 s22, 0x5500
	s_cselect_b32 s43, s17, s41
	s_cselect_b32 s42, s16, s40
	s_cselect_b32 s41, s11, s88
	s_cselect_b32 s40, s10, s87
	s_mov_b32 m0, s77
	v_lshl_add_u64 v[186:187], v[0:1], 0, s[22:23]
	ds_read_b128 v[162:165], v180
	ds_read_b128 v[166:169], v180 offset:1024
	ds_read_b128 v[182:185], v180 offset:2048
	ds_read_b128 v[190:193], v180 offset:3072
	ds_read_b128 v[194:197], v180 offset:4096
	ds_read_b128 v[208:211], v180 offset:5120
	ds_read_b128 v[212:215], v180 offset:6144
	ds_read_b128 v[216:219], v180 offset:7168
	global_load_lds_dwordx4 v[186:187], off
	v_lshl_add_u64 v[186:187], v[170:171], 0, s[22:23]
	s_mov_b32 m0, s78
	s_nop 0
	global_load_lds_dwordx4 v[186:187], off
	s_waitcnt vmcnt(8)
	s_waitcnt lgkmcnt(0)
	s_setprio 3
	s_barrier
	v_mfma_f32_16x16x32_bf16 v[126:129], v[130:133], v[162:165], v[126:129]
	v_mfma_f32_16x16x32_bf16 v[126:129], v[134:137], v[166:169], v[126:129]
	v_mfma_f32_16x16x32_bf16 v[122:125], v[138:141], v[162:165], v[122:125]
	v_mfma_f32_16x16x32_bf16 v[122:125], v[142:145], v[166:169], v[122:125]
	v_mfma_f32_16x16x32_bf16 v[94:97], v[138:141], v[182:185], v[94:97]
	v_mfma_f32_16x16x32_bf16 v[94:97], v[142:145], v[190:193], v[94:97]
	v_mfma_f32_16x16x32_bf16 v[98:101], v[130:133], v[182:185], v[98:101]
	v_mfma_f32_16x16x32_bf16 v[98:101], v[134:137], v[190:193], v[98:101]
	v_mfma_f32_16x16x32_bf16 v[110:113], v[130:133], v[194:197], v[110:113]
	v_mfma_f32_16x16x32_bf16 v[110:113], v[134:137], v[208:211], v[110:113]
	v_mfma_f32_16x16x32_bf16 v[106:109], v[138:141], v[194:197], v[106:109]
	v_mfma_f32_16x16x32_bf16 v[106:109], v[142:145], v[208:211], v[106:109]
	v_mfma_f32_16x16x32_bf16 v[74:77], v[138:141], v[212:215], v[74:77]
	v_mfma_f32_16x16x32_bf16 v[74:77], v[142:145], v[216:219], v[74:77]
	v_mfma_f32_16x16x32_bf16 v[78:81], v[130:133], v[212:215], v[78:81]
	v_mfma_f32_16x16x32_bf16 v[78:81], v[134:137], v[216:219], v[78:81]
	v_mfma_f32_16x16x32_bf16 v[118:121], v[146:149], v[162:165], v[118:121]
	v_mfma_f32_16x16x32_bf16 v[118:121], v[150:153], v[166:169], v[118:121]
	v_mfma_f32_16x16x32_bf16 v[114:117], v[154:157], v[162:165], v[114:117]
	v_mfma_f32_16x16x32_bf16 v[114:117], v[158:161], v[166:169], v[114:117]
	v_mfma_f32_16x16x32_bf16 v[86:89], v[154:157], v[182:185], v[86:89]
	v_mfma_f32_16x16x32_bf16 v[86:89], v[158:161], v[190:193], v[86:89]
	v_mfma_f32_16x16x32_bf16 v[90:93], v[146:149], v[182:185], v[90:93]
	v_mfma_f32_16x16x32_bf16 v[90:93], v[150:153], v[190:193], v[90:93]
	v_mfma_f32_16x16x32_bf16 v[102:105], v[146:149], v[194:197], v[102:105]
	v_mfma_f32_16x16x32_bf16 v[102:105], v[150:153], v[208:211], v[102:105]
	v_mfma_f32_16x16x32_bf16 v[82:85], v[154:157], v[194:197], v[82:85]
	v_mfma_f32_16x16x32_bf16 v[82:85], v[158:161], v[208:211], v[82:85]
	v_mfma_f32_16x16x32_bf16 v[66:69], v[154:157], v[212:215], v[66:69]
	v_mfma_f32_16x16x32_bf16 v[66:69], v[158:161], v[216:219], v[66:69]
	v_mfma_f32_16x16x32_bf16 v[70:73], v[146:149], v[212:215], v[70:73]
	v_mfma_f32_16x16x32_bf16 v[70:73], v[150:153], v[216:219], v[70:73]
	s_setprio 0
	s_barrier
	s_mov_b32 m0, s79
	v_lshl_add_u64 v[186:187], s[40:41], 0, v[174:175]
	s_add_u32 s88, s40, 0x2b0000
	ds_read_b128 v[162:165], v180 offset:16384
	ds_read_b128 v[166:169], v180 offset:17408
	ds_read_b128 v[182:185], v180 offset:18432
	ds_read_b128 v[190:193], v180 offset:19456
	ds_read_b128 v[194:197], v180 offset:20480
	ds_read_b128 v[208:211], v180 offset:21504
	ds_read_b128 v[212:215], v180 offset:22528
	ds_read_b128 v[216:219], v180 offset:23552
	global_load_lds_dwordx4 v[186:187], off
	v_lshl_add_u64 v[198:199], s[40:41], 0, v[178:179]
	s_mov_b32 m0, s80
	s_addc_u32 s89, s41, 0
	global_load_lds_dwordx4 v[198:199], off
	v_lshl_add_u64 v[204:205], s[88:89], 0, v[174:175]
	s_mov_b32 m0, s81
	v_lshl_add_u64 v[220:221], s[42:43], 0, v[176:177]
	global_load_lds_dwordx4 v[204:205], off
	v_lshl_add_u64 v[204:205], s[88:89], 0, v[178:179]
	s_mov_b32 m0, s82
	s_nop 0
	global_load_lds_dwordx4 v[204:205], off
	v_lshl_add_u64 v[204:205], s[42:43], 0, v[172:173]
	s_mov_b32 m0, s58
	s_nop 0
	global_load_lds_dwordx4 v[204:205], off
	s_mov_b32 m0, s60
	s_nop 0
	global_load_lds_dwordx4 v[220:221], off
	s_waitcnt vmcnt(8)
	s_waitcnt lgkmcnt(0)
	s_setprio 3
	s_barrier
; #define PG8_STAGE(bufoff, gbase, voff) do { _Pragma("unroll") for (int _i = 0; _i < 2; ++_i) \
;         __builtin_amdgcn_global_load_lds((const unsigned*)((const char*)(gbase) + (voff)[_i]), (PG8_LAS unsigned*)(lds + (bufoff) + ldsw + _i * 8192), 16, 0, 0); } while (0)
; #define PG8_LDA(dst, b, h) do { _Pragma("unroll") for (int m = 0; m < 4; ++m) _Pragma("unroll") for (int k = 0; k < 2; ++k) dst[m][k] = *(const PG8_LAS bf16x8*)(lds + PG8_SA(b, h) + aoff + m * 2048 + k * 1024); } while (0)
; #define PG8_LDB(dst, b, h) do { _Pragma("unroll") for (int n = 0; n < 2; ++n) _Pragma("unroll") for (int k = 0; k < 2; ++k) dst[n][k] = *(const PG8_LAS bf16x8*)(lds + PG8_SB(b, h) + boff + n * 2048 + k * 1024); } while (0)
; #define PG8_MMA(ai, bj, At, Bt) do { __builtin_amdgcn_s_setprio(3); _Pragma("unroll") for (int m = 0; m < 4; ++m) _Pragma("unroll") for (int n = 0; n < 2; ++n) _Pragma("unroll") for (int k = 0; k < 2; ++k) \
;         acc[ai][bj][m][n] = __builtin_amdgcn_mfma_f32_16x16x32_bf16(Bt[n][k], At[m][k], acc[ai][bj][m][n], 0, 0, 0); __builtin_amdgcn_s_setprio(0); } while (0)
; #define PG8_WAIT_V(n) asm volatile("s_waitcnt vmcnt(" #n ")" ::: "memory")
; #define PG8_WAIT_L(n) asm volatile("s_waitcnt lgkmcnt(" #n ")" ::: "memory")
; #define PG8_BAR __builtin_amdgcn_s_barrier()
; #define PG8_SCHED __builtin_amdgcn_sched_barrier(0)
; template <class Epi, class Sched, bool ALIGN_EPI = false, bool SP2 = false>
; __device__ __forceinline__ void gemm_phase(PG8_LAS unsigned char* lds, const Gemm g, const Sched& S, const Epi& E) {
;     ...
;             PG8_WAIT_V(8); PG8_WAIT_L(0); PG8_BAR; PG8_MMA(1, 0, At, B0); PG8_MMA(1, 1, At, B1); PG8_BAR; PG8_SCHED;
;             PG8_LDB(B0, 1, 0); PG8_LDB(B1, 1, 1); PG8_SCHED; PG8_LDA(At, 1, 0); PG8_STAGE(PG8_SA(0, 1), a2 + hstepA, voffA);
;             PG8_WAIT_V(8); PG8_WAIT_L(0); PG8_BAR; PG8_MMA(0, 0, At, B0); PG8_MMA(0, 1, At, B1); PG8_BAR; PG8_SCHED;
	v_mfma_f32_16x16x32_bf16 v[62:65], v[130:133], v[162:165], v[62:65]
	v_mfma_f32_16x16x32_bf16 v[62:65], v[134:137], v[166:169], v[62:65]
	v_mfma_f32_16x16x32_bf16 v[58:61], v[138:141], v[162:165], v[58:61]
	v_mfma_f32_16x16x32_bf16 v[58:61], v[142:145], v[166:169], v[58:61]
	v_mfma_f32_16x16x32_bf16 v[42:45], v[138:141], v[182:185], v[42:45]
	v_mfma_f32_16x16x32_bf16 v[42:45], v[142:145], v[190:193], v[42:45]
	v_mfma_f32_16x16x32_bf16 v[46:49], v[130:133], v[182:185], v[46:49]
	v_mfma_f32_16x16x32_bf16 v[46:49], v[134:137], v[190:193], v[46:49]
	v_mfma_f32_16x16x32_bf16 v[30:33], v[130:133], v[194:197], v[30:33]
	v_mfma_f32_16x16x32_bf16 v[30:33], v[134:137], v[208:211], v[30:33]
	v_mfma_f32_16x16x32_bf16 v[26:29], v[138:141], v[194:197], v[26:29]
	v_mfma_f32_16x16x32_bf16 v[26:29], v[142:145], v[208:211], v[26:29]
	v_mfma_f32_16x16x32_bf16 v[10:13], v[138:141], v[212:215], v[10:13]
	v_mfma_f32_16x16x32_bf16 v[10:13], v[142:145], v[216:219], v[10:13]
	v_mfma_f32_16x16x32_bf16 v[14:17], v[130:133], v[212:215], v[14:17]
	v_mfma_f32_16x16x32_bf16 v[14:17], v[134:137], v[216:219], v[14:17]
	v_mfma_f32_16x16x32_bf16 v[54:57], v[146:149], v[162:165], v[54:57]
	v_mfma_f32_16x16x32_bf16 v[54:57], v[150:153], v[166:169], v[54:57]
	v_mfma_f32_16x16x32_bf16 v[50:53], v[154:157], v[162:165], v[50:53]
	v_mfma_f32_16x16x32_bf16 v[50:53], v[158:161], v[166:169], v[50:53]
	v_mfma_f32_16x16x32_bf16 v[34:37], v[154:157], v[182:185], v[34:37]
	v_mfma_f32_16x16x32_bf16 v[34:37], v[158:161], v[190:193], v[34:37]
	v_mfma_f32_16x16x32_bf16 v[38:41], v[146:149], v[182:185], v[38:41]
	v_mfma_f32_16x16x32_bf16 v[38:41], v[150:153], v[190:193], v[38:41]
	v_mfma_f32_16x16x32_bf16 v[22:25], v[146:149], v[194:197], v[22:25]
	v_mfma_f32_16x16x32_bf16 v[22:25], v[150:153], v[208:211], v[22:25]
	v_mfma_f32_16x16x32_bf16 v[18:21], v[154:157], v[194:197], v[18:21]
	v_mfma_f32_16x16x32_bf16 v[18:21], v[158:161], v[208:211], v[18:21]
	v_mfma_f32_16x16x32_bf16 v[2:5], v[154:157], v[212:215], v[2:5]
	v_mfma_f32_16x16x32_bf16 v[2:5], v[158:161], v[216:219], v[2:5]
	v_mfma_f32_16x16x32_bf16 v[6:9], v[146:149], v[212:215], v[6:9]
	v_mfma_f32_16x16x32_bf16 v[6:9], v[150:153], v[216:219], v[6:9]
	s_setprio 0
	s_barrier
	v_add_u32_e32 v142, s52, v189
	v_add_u32_e32 v158, s53, v189
	ds_read_b128 v[130:133], v142
	ds_read_b128 v[134:137], v142 offset:1024
	ds_read_b128 v[138:141], v142 offset:2048
	ds_read_b128 v[142:145], v142 offset:3072
	ds_read_b128 v[146:149], v158
	ds_read_b128 v[150:153], v158 offset:1024
	ds_read_b128 v[154:157], v158 offset:2048
	ds_read_b128 v[158:161], v158 offset:3072
	s_add_u32 s42, s42, 0x2b0000
	s_addc_u32 s43, s43, 0
	s_mov_b32 m0, s61
	v_lshl_add_u64 v[222:223], s[42:43], 0, v[172:173]
	ds_read_b128 v[162:165], v180 offset:32768
	ds_read_b128 v[166:169], v180 offset:33792
	ds_read_b128 v[182:185], v180 offset:34816
	ds_read_b128 v[190:193], v180 offset:35840
	ds_read_b128 v[194:197], v180 offset:36864
	ds_read_b128 v[208:211], v180 offset:37888
	ds_read_b128 v[212:215], v180 offset:38912
	ds_read_b128 v[216:219], v180 offset:39936
	global_load_lds_dwordx4 v[222:223], off
	v_lshl_add_u64 v[222:223], s[42:43], 0, v[176:177]
	s_mov_b32 m0, s62
	s_nop 0
	global_load_lds_dwordx4 v[222:223], off
	s_waitcnt vmcnt(8)
	s_waitcnt lgkmcnt(0)
	s_setprio 3
	s_barrier
	v_mfma_f32_16x16x32_bf16 v[126:129], v[130:133], v[162:165], v[126:129]
	v_mfma_f32_16x16x32_bf16 v[126:129], v[134:137], v[166:169], v[126:129]
	v_mfma_f32_16x16x32_bf16 v[122:125], v[138:141], v[162:165], v[122:125]
	v_mfma_f32_16x16x32_bf16 v[122:125], v[142:145], v[166:169], v[122:125]
	v_mfma_f32_16x16x32_bf16 v[94:97], v[138:141], v[182:185], v[94:97]
	v_mfma_f32_16x16x32_bf16 v[94:97], v[142:145], v[190:193], v[94:97]
	v_mfma_f32_16x16x32_bf16 v[98:101], v[130:133], v[182:185], v[98:101]
	v_mfma_f32_16x16x32_bf16 v[98:101], v[134:137], v[190:193], v[98:101]
	v_mfma_f32_16x16x32_bf16 v[110:113], v[130:133], v[194:197], v[110:113]
	v_mfma_f32_16x16x32_bf16 v[110:113], v[134:137], v[208:211], v[110:113]
	v_mfma_f32_16x16x32_bf16 v[106:109], v[138:141], v[194:197], v[106:109]
	v_mfma_f32_16x16x32_bf16 v[106:109], v[142:145], v[208:211], v[106:109]
	v_mfma_f32_16x16x32_bf16 v[74:77], v[138:141], v[212:215], v[74:77]
	v_mfma_f32_16x16x32_bf16 v[74:77], v[142:145], v[216:219], v[74:77]
	v_mfma_f32_16x16x32_bf16 v[78:81], v[130:133], v[212:215], v[78:81]
	v_mfma_f32_16x16x32_bf16 v[78:81], v[134:137], v[216:219], v[78:81]
	v_mfma_f32_16x16x32_bf16 v[118:121], v[146:149], v[162:165], v[118:121]
	v_mfma_f32_16x16x32_bf16 v[118:121], v[150:153], v[166:169], v[118:121]
	v_mfma_f32_16x16x32_bf16 v[114:117], v[154:157], v[162:165], v[114:117]
	v_mfma_f32_16x16x32_bf16 v[114:117], v[158:161], v[166:169], v[114:117]
	v_mfma_f32_16x16x32_bf16 v[86:89], v[154:157], v[182:185], v[86:89]
	v_mfma_f32_16x16x32_bf16 v[86:89], v[158:161], v[190:193], v[86:89]
	v_mfma_f32_16x16x32_bf16 v[90:93], v[146:149], v[182:185], v[90:93]
	v_mfma_f32_16x16x32_bf16 v[90:93], v[150:153], v[190:193], v[90:93]
	v_mfma_f32_16x16x32_bf16 v[102:105], v[146:149], v[194:197], v[102:105]
	v_mfma_f32_16x16x32_bf16 v[102:105], v[150:153], v[208:211], v[102:105]
	v_mfma_f32_16x16x32_bf16 v[82:85], v[154:157], v[194:197], v[82:85]
	v_mfma_f32_16x16x32_bf16 v[82:85], v[158:161], v[208:211], v[82:85]
	v_mfma_f32_16x16x32_bf16 v[66:69], v[154:157], v[212:215], v[66:69]
	v_mfma_f32_16x16x32_bf16 v[66:69], v[158:161], v[216:219], v[66:69]
	v_mfma_f32_16x16x32_bf16 v[70:73], v[146:149], v[212:215], v[70:73]
	v_mfma_f32_16x16x32_bf16 v[70:73], v[150:153], v[216:219], v[70:73]
	s_setprio 0
	s_barrier
; #define PG8_STAGE(bufoff, gbase, voff) do { _Pragma("unroll") for (int _i = 0; _i < 2; ++_i) \
;         __builtin_amdgcn_global_load_lds((const unsigned*)((const char*)(gbase) + (voff)[_i]), (PG8_LAS unsigned*)(lds + (bufoff) + ldsw + _i * 8192), 16, 0, 0); } while (0)
; #define PG8_LDA(dst, b, h) do { _Pragma("unroll") for (int m = 0; m < 4; ++m) _Pragma("unroll") for (int k = 0; k < 2; ++k) dst[m][k] = *(const PG8_LAS bf16x8*)(lds + PG8_SA(b, h) + aoff + m * 2048 + k * 1024); } while (0)
; #define PG8_MMA(ai, bj, At, Bt) do { __builtin_amdgcn_s_setprio(3); _Pragma("unroll") for (int m = 0; m < 4; ++m) _Pragma("unroll") for (int n = 0; n < 2; ++n) _Pragma("unroll") for (int k = 0; k < 2; ++k) \
;         acc[ai][bj][m][n] = __builtin_amdgcn_mfma_f32_16x16x32_bf16(Bt[n][k], At[m][k], acc[ai][bj][m][n], 0, 0, 0); __builtin_amdgcn_s_setprio(0); } while (0)
; #define PG8_WAIT_V(n) asm volatile("s_waitcnt vmcnt(" #n ")" ::: "memory")
; #define PG8_WAIT_L(n) asm volatile("s_waitcnt lgkmcnt(" #n ")" ::: "memory")
; #define PG8_BAR __builtin_amdgcn_s_barrier()
; #define PG8_SCHED __builtin_amdgcn_sched_barrier(0)
; template <class Epi, class Sched, bool ALIGN_EPI = false, bool SP2 = false>
; __device__ __forceinline__ void gemm_phase(PG8_LAS unsigned char* lds, const Gemm g, const Sched& S, const Epi& E) {
;     ...
;         for (int t = 0; t < nt; t += 2) {
;     ...
;             PG8_LDA(At, 1, 1); PG8_STAGE(PG8_SB(1, 0), b3, voffB); PG8_STAGE(PG8_SB(1, 1), b3 + hstepB, voffB); PG8_STAGE(PG8_SA(1, 0), a3, voffA);
;             PG8_WAIT_V(8); PG8_WAIT_L(0); PG8_BAR; PG8_MMA(1, 0, At, B0); PG8_MMA(1, 1, At, B1); PG8_BAR; PG8_SCHED;
	s_mov_b32 m0, s83
	v_lshl_add_u64 v[186:187], v[186:187], 0, s[18:19]
	s_add_u32 s40, s40, 0x2b0080
	ds_read_b128 v[162:165], v180 offset:49152
	ds_read_b128 v[166:169], v180 offset:50176
	ds_read_b128 v[182:185], v180 offset:51200
	ds_read_b128 v[190:193], v180 offset:52224
	ds_read_b128 v[194:197], v180 offset:53248
	ds_read_b128 v[208:211], v180 offset:54272
	ds_read_b128 v[212:215], v180 offset:55296
	ds_read_b128 v[216:219], v180 offset:56320
	global_load_lds_dwordx4 v[186:187], off
	v_lshl_add_u64 v[186:187], v[198:199], 0, s[18:19]
	s_mov_b32 m0, s84
	s_addc_u32 s41, s41, 0
	global_load_lds_dwordx4 v[186:187], off
	v_lshl_add_u64 v[186:187], s[40:41], 0, v[174:175]
	s_mov_b32 m0, s85
	s_nop 0
	global_load_lds_dwordx4 v[186:187], off
	v_lshl_add_u64 v[186:187], s[40:41], 0, v[178:179]
	s_mov_b32 m0, s86
	s_nop 0
	global_load_lds_dwordx4 v[186:187], off
	v_lshl_add_u64 v[186:187], v[204:205], 0, s[18:19]
	s_mov_b32 m0, s63
	s_nop 0
	global_load_lds_dwordx4 v[186:187], off
	v_lshl_add_u64 v[186:187], v[220:221], 0, s[18:19]
	s_mov_b32 m0, s64
	s_nop 0
	global_load_lds_dwordx4 v[186:187], off
	s_waitcnt vmcnt(8)
	s_waitcnt lgkmcnt(0)
	s_setprio 3
	s_barrier
	v_mfma_f32_16x16x32_bf16 v[62:65], v[130:133], v[162:165], v[62:65]
	v_mfma_f32_16x16x32_bf16 v[62:65], v[134:137], v[166:169], v[62:65]
	v_mfma_f32_16x16x32_bf16 v[58:61], v[138:141], v[162:165], v[58:61]
	v_mfma_f32_16x16x32_bf16 v[58:61], v[142:145], v[166:169], v[58:61]
	v_mfma_f32_16x16x32_bf16 v[42:45], v[138:141], v[182:185], v[42:45]
	v_mfma_f32_16x16x32_bf16 v[42:45], v[142:145], v[190:193], v[42:45]
	v_mfma_f32_16x16x32_bf16 v[46:49], v[130:133], v[182:185], v[46:49]
	v_mfma_f32_16x16x32_bf16 v[46:49], v[134:137], v[190:193], v[46:49]
	v_mfma_f32_16x16x32_bf16 v[30:33], v[130:133], v[194:197], v[30:33]
	v_mfma_f32_16x16x32_bf16 v[30:33], v[134:137], v[208:211], v[30:33]
	v_mfma_f32_16x16x32_bf16 v[26:29], v[138:141], v[194:197], v[26:29]
	v_mfma_f32_16x16x32_bf16 v[26:29], v[142:145], v[208:211], v[26:29]
	v_mfma_f32_16x16x32_bf16 v[10:13], v[138:141], v[212:215], v[10:13]
	v_mfma_f32_16x16x32_bf16 v[10:13], v[142:145], v[216:219], v[10:13]
	v_mfma_f32_16x16x32_bf16 v[14:17], v[130:133], v[212:215], v[14:17]
	v_mfma_f32_16x16x32_bf16 v[14:17], v[134:137], v[216:219], v[14:17]
	v_mfma_f32_16x16x32_bf16 v[54:57], v[146:149], v[162:165], v[54:57]
	v_mfma_f32_16x16x32_bf16 v[54:57], v[150:153], v[166:169], v[54:57]
	v_mfma_f32_16x16x32_bf16 v[50:53], v[154:157], v[162:165], v[50:53]
	v_mfma_f32_16x16x32_bf16 v[50:53], v[158:161], v[166:169], v[50:53]
	v_mfma_f32_16x16x32_bf16 v[34:37], v[154:157], v[182:185], v[34:37]
	v_mfma_f32_16x16x32_bf16 v[34:37], v[158:161], v[190:193], v[34:37]
	v_mfma_f32_16x16x32_bf16 v[38:41], v[146:149], v[182:185], v[38:41]
	v_mfma_f32_16x16x32_bf16 v[38:41], v[150:153], v[190:193], v[38:41]
	v_mfma_f32_16x16x32_bf16 v[22:25], v[146:149], v[194:197], v[22:25]
	v_mfma_f32_16x16x32_bf16 v[22:25], v[150:153], v[208:211], v[22:25]
	v_mfma_f32_16x16x32_bf16 v[18:21], v[154:157], v[194:197], v[18:21]
	v_mfma_f32_16x16x32_bf16 v[18:21], v[158:161], v[208:211], v[18:21]
	v_mfma_f32_16x16x32_bf16 v[2:5], v[154:157], v[212:215], v[2:5]
	v_mfma_f32_16x16x32_bf16 v[2:5], v[158:161], v[216:219], v[2:5]
	v_mfma_f32_16x16x32_bf16 v[6:9], v[146:149], v[212:215], v[6:9]
	v_mfma_f32_16x16x32_bf16 v[6:9], v[150:153], v[216:219], v[6:9]
	s_setprio 0
	s_barrier
	s_add_i32 s67, s67, 2
	s_add_u32 s22, s22, 0x100
	s_addc_u32 s23, s23, 0
	s_cmpk_gt_u32 s67, 0xa9
	s_cbranch_scc1 .LBB0_1021
